# v26 + s_setprio 1 ahead of the pre-MMA barrier + redundant post-barrier lgkmcnt wait removed (MMA segment now starts with an MFMA right after the barrier)
# speedup vs baseline: 1.0092x; 1.0037x over previous
; #define PG8_STAGE(bufoff, gbase, voff) do { _Pragma("unroll") for (int _i = 0; _i < 2; ++_i) \
;         __builtin_amdgcn_global_load_lds((const unsigned*)((const char*)(gbase) + (voff)[_i]), (PG8_LAS unsigned*)(lds + (bufoff) + ldsw + _i * 8192), 16, 0, 0); } while (0)
; #define PG8_LDA(dst, b, h) do { _Pragma("unroll") for (int m = 0; m < 4; ++m) _Pragma("unroll") for (int k = 0; k < 2; ++k) dst[m][k] = *(const PG8_LAS bf16x8*)(lds + PG8_SA(b, h) + aoff + m * 2048 + k * 1024); } while (0)
; #define PG8_LDB(dst, b, h) do { _Pragma("unroll") for (int n = 0; n < 2; ++n) _Pragma("unroll") for (int k = 0; k < 2; ++k) dst[n][k] = *(const PG8_LAS bf16x8*)(lds + PG8_SB(b, h) + boff + n * 2048 + k * 1024); } while (0)
; #define PG8_MMA(ai, bj, At, Bt) do { __builtin_amdgcn_s_setprio(1); _Pragma("unroll") for (int m = 0; m < 4; ++m) _Pragma("unroll") for (int n = 0; n < 2; ++n) _Pragma("unroll") for (int k = 0; k < 2; ++k) \
;         acc[ai][bj][m][n] = __builtin_amdgcn_mfma_f32_16x16x32_bf16(Bt[n][k], At[m][k], acc[ai][bj][m][n], 0, 0, 0); __builtin_amdgcn_s_setprio(0); } while (0)
; #define PG8_BAR __builtin_amdgcn_s_barrier()
; template <class Epi, class Sched, bool ALIGN_EPI = false, bool SP2 = false>
; __device__ __forceinline__ void gemm_phase(PG8_LAS unsigned char* lds, const Gemm g, const Sched& S, const Epi& E, const int wave0) {
;     ...
;             PG8_LDB(B0, 0, 0); PG8_LDB(B1, 0, 1); PG8_SCHED; PG8_LDA(At, 0, 0); PG8_STAGE(PG8_SA(1, 1), a1 + hstepA, voffA);
;             PG8_WAIT_V(8); PG8_WAIT_L(0); PG8_BAR; PG8_MMA(0, 0, At, B0); PG8_MMA(0, 1, At, B1); PG8_BAR; PG8_SCHED;
;             PG8_LDA(At, 0, 1); PG8_STAGE(PG8_SB(0, 0), b2, voffB); PG8_STAGE(PG8_SB(0, 1), b2 + hstepB, voffB); PG8_STAGE(PG8_SA(0, 0), a2, voffA);
;             PG8_WAIT_V(8); PG8_WAIT_L(0); PG8_BAR; PG8_MMA(1, 0, At, B0); PG8_MMA(1, 1, At, B1); PG8_BAR; PG8_SCHED;
;             PG8_LDB(B0, 1, 0); PG8_LDB(B1, 1, 1); PG8_SCHED; PG8_LDA(At, 1, 0); PG8_STAGE(PG8_SA(0, 1), a2 + hstepA, voffA);
;             PG8_WAIT_V(8); PG8_WAIT_L(0); PG8_BAR; PG8_MMA(0, 0, At, B0); PG8_MMA(0, 1, At, B1); PG8_BAR; PG8_SCHED;
;             PG8_LDA(At, 1, 1); PG8_STAGE(PG8_SB(1, 0), b3, voffB); PG8_STAGE(PG8_SB(1, 1), b3 + hstepB, voffB); PG8_STAGE(PG8_SA(1, 0), a3, voffA);
;             PG8_WAIT_V(8); PG8_WAIT_L(0); PG8_BAR; PG8_MMA(1, 0, At, B0); PG8_MMA(1, 1, At, B1); PG8_BAR; PG8_SCHED;
.LBB0_316:
	s_add_u32 s16, s0, 0xfff80080
	s_addc_u32 s17, s1, -1
	s_add_i32 s38, 0, 0x10000
	s_cmp_eq_u32 s37, 28
	s_cselect_b32 s19, s11, s17
	s_cselect_b32 s18, s33, s16
	s_cselect_b32 s17, s9, s36
	s_cselect_b32 s16, s34, s35
	s_add_i32 s40, 0, 0x14000
	ds_read_b128 v[144:147], v252
	ds_read_b128 v[148:151], v252 offset:1024
	ds_read_b128 v[152:155], v252 offset:2048
	ds_read_b128 v[156:159], v252 offset:3072
	ds_read_b128 v[178:181], v253
	ds_read_b128 v[182:185], v253 offset:1024
	ds_read_b128 v[186:189], v253 offset:2048
	ds_read_b128 v[190:193], v253 offset:3072
	s_add_i32 m0, s23, 0xc000
	ds_read_b128 v[194:197], v143
	ds_read_b128 v[208:211], v143 offset:1024
	ds_read_b128 v[212:215], v143 offset:2048
	ds_read_b128 v[216:219], v143 offset:3072
	ds_read_b128 v[220:223], v143 offset:4096
	ds_read_b128 v[224:227], v143 offset:5120
	ds_read_b128 v[228:231], v143 offset:6144
	ds_read_b128 v[232:235], v143 offset:7168
	global_load_lds_dwordx4 v136, s[0:1]
	s_add_i32 m0, s23, 0xe000
	s_nop 0
	global_load_lds_dwordx4 v138, s[0:1]
	s_waitcnt vmcnt(8)
	s_waitcnt lgkmcnt(0)
	s_setprio 1
	s_barrier
	v_mfma_f32_16x16x32_bf16 v[126:129], v[144:147], v[194:197], v[126:129]
	v_mfma_f32_16x16x32_bf16 v[122:125], v[152:155], v[194:197], v[122:125]
	v_mfma_f32_16x16x32_bf16 v[118:121], v[144:147], v[212:215], v[118:121]
	v_mfma_f32_16x16x32_bf16 v[114:117], v[152:155], v[212:215], v[114:117]
	v_mfma_f32_16x16x32_bf16 v[102:105], v[144:147], v[220:223], v[102:105]
	v_mfma_f32_16x16x32_bf16 v[98:101], v[152:155], v[220:223], v[98:101]
	v_mfma_f32_16x16x32_bf16 v[86:89], v[144:147], v[228:231], v[86:89]
	v_mfma_f32_16x16x32_bf16 v[82:85], v[152:155], v[228:231], v[82:85]
	s_setprio 0
	s_setprio 1
	v_mfma_f32_16x16x32_bf16 v[126:129], v[148:151], v[208:211], v[126:129]
	v_mfma_f32_16x16x32_bf16 v[122:125], v[156:159], v[208:211], v[122:125]
	v_mfma_f32_16x16x32_bf16 v[118:121], v[148:151], v[216:219], v[118:121]
	v_mfma_f32_16x16x32_bf16 v[114:117], v[156:159], v[216:219], v[114:117]
	v_mfma_f32_16x16x32_bf16 v[102:105], v[148:151], v[224:227], v[102:105]
	v_mfma_f32_16x16x32_bf16 v[98:101], v[156:159], v[224:227], v[98:101]
	v_mfma_f32_16x16x32_bf16 v[86:89], v[148:151], v[232:235], v[86:89]
	v_mfma_f32_16x16x32_bf16 v[82:85], v[156:159], v[232:235], v[82:85]
	s_setprio 0
	s_setprio 1
	v_mfma_f32_16x16x32_bf16 v[110:113], v[178:181], v[194:197], v[110:113]
	v_mfma_f32_16x16x32_bf16 v[106:109], v[186:189], v[194:197], v[106:109]
	v_mfma_f32_16x16x32_bf16 v[94:97], v[178:181], v[212:215], v[94:97]
	v_mfma_f32_16x16x32_bf16 v[90:93], v[186:189], v[212:215], v[90:93]
	v_mfma_f32_16x16x32_bf16 v[78:81], v[178:181], v[220:223], v[78:81]
	v_mfma_f32_16x16x32_bf16 v[74:77], v[186:189], v[220:223], v[74:77]
	v_mfma_f32_16x16x32_bf16 v[70:73], v[178:181], v[228:231], v[70:73]
	v_mfma_f32_16x16x32_bf16 v[66:69], v[186:189], v[228:231], v[66:69]
	s_setprio 0
	s_setprio 1
	v_mfma_f32_16x16x32_bf16 v[110:113], v[182:185], v[208:211], v[110:113]
	v_mfma_f32_16x16x32_bf16 v[106:109], v[190:193], v[208:211], v[106:109]
	v_mfma_f32_16x16x32_bf16 v[94:97], v[182:185], v[216:219], v[94:97]
	v_mfma_f32_16x16x32_bf16 v[90:93], v[190:193], v[216:219], v[90:93]
	v_mfma_f32_16x16x32_bf16 v[78:81], v[182:185], v[224:227], v[78:81]
	v_mfma_f32_16x16x32_bf16 v[74:77], v[190:193], v[224:227], v[74:77]
	v_mfma_f32_16x16x32_bf16 v[70:73], v[182:185], v[232:235], v[70:73]
	v_mfma_f32_16x16x32_bf16 v[66:69], v[190:193], v[232:235], v[66:69]
	s_setprio 0
	s_barrier
	s_add_i32 s38, s38, s22
	s_mov_b32 m0, s38
	ds_read_b128 v[194:197], v143 offset:16384
	ds_read_b128 v[208:211], v143 offset:17408
	ds_read_b128 v[212:215], v143 offset:18432
	ds_read_b128 v[216:219], v143 offset:19456
	ds_read_b128 v[220:223], v143 offset:20480
	ds_read_b128 v[224:227], v143 offset:21504
	ds_read_b128 v[228:231], v143 offset:22528
	ds_read_b128 v[232:235], v143 offset:23552
	global_load_lds_dwordx4 v64, s[16:17]
	s_add_i32 m0, s38, 0x2000
	s_add_u32 s38, s16, 0x80000
	s_addc_u32 s39, s17, 0
	s_add_i32 s40, s40, s22
	global_load_lds_dwordx4 v130, s[16:17]
	s_mov_b32 m0, s40
	s_mov_b64 s[100:101], s[18:19]
	global_load_lds_dwordx4 v64, s[38:39]
	s_add_i32 m0, s40, 0x2000
	s_nop 0
	global_load_lds_dwordx4 v130, s[38:39]
	s_mov_b32 m0, s23
	s_nop 0
	global_load_lds_dwordx4 v134, s[18:19]
	s_mov_b32 m0, s24
	s_nop 0
	global_load_lds_dwordx4 v132, s[18:19]
	s_waitcnt vmcnt(8)
	s_waitcnt lgkmcnt(0)
	s_setprio 1
	s_barrier
	v_mfma_f32_16x16x32_bf16 v[60:63], v[144:147], v[194:197], v[60:63]
	v_mfma_f32_16x16x32_bf16 v[56:59], v[152:155], v[194:197], v[56:59]
	v_mfma_f32_16x16x32_bf16 v[52:55], v[144:147], v[212:215], v[52:55]
	v_mfma_f32_16x16x32_bf16 v[48:51], v[152:155], v[212:215], v[48:51]
	v_mfma_f32_16x16x32_bf16 v[36:39], v[144:147], v[220:223], v[36:39]
	v_mfma_f32_16x16x32_bf16 v[32:35], v[152:155], v[220:223], v[32:35]
	v_mfma_f32_16x16x32_bf16 v[20:23], v[144:147], v[228:231], v[20:23]
	v_mfma_f32_16x16x32_bf16 v[16:19], v[152:155], v[228:231], v[16:19]
	s_setprio 0
	s_setprio 1
	v_mfma_f32_16x16x32_bf16 v[60:63], v[148:151], v[208:211], v[60:63]
	v_mfma_f32_16x16x32_bf16 v[56:59], v[156:159], v[208:211], v[56:59]
	v_mfma_f32_16x16x32_bf16 v[52:55], v[148:151], v[216:219], v[52:55]
	v_mfma_f32_16x16x32_bf16 v[48:51], v[156:159], v[216:219], v[48:51]
	v_mfma_f32_16x16x32_bf16 v[36:39], v[148:151], v[224:227], v[36:39]
	v_mfma_f32_16x16x32_bf16 v[32:35], v[156:159], v[224:227], v[32:35]
	v_mfma_f32_16x16x32_bf16 v[20:23], v[148:151], v[232:235], v[20:23]
	v_mfma_f32_16x16x32_bf16 v[16:19], v[156:159], v[232:235], v[16:19]
	s_setprio 0
	s_setprio 1
	v_mfma_f32_16x16x32_bf16 v[44:47], v[178:181], v[194:197], v[44:47]
	v_mfma_f32_16x16x32_bf16 v[40:43], v[186:189], v[194:197], v[40:43]
	v_mfma_f32_16x16x32_bf16 v[28:31], v[178:181], v[212:215], v[28:31]
	v_mfma_f32_16x16x32_bf16 v[24:27], v[186:189], v[212:215], v[24:27]
	v_mfma_f32_16x16x32_bf16 v[12:15], v[178:181], v[220:223], v[12:15]
	v_mfma_f32_16x16x32_bf16 v[8:11], v[186:189], v[220:223], v[8:11]
	v_mfma_f32_16x16x32_bf16 v[4:7], v[178:181], v[228:231], v[4:7]
	v_mfma_f32_16x16x32_bf16 v[0:3], v[186:189], v[228:231], v[0:3]
	s_setprio 0
	s_setprio 1
	v_mfma_f32_16x16x32_bf16 v[44:47], v[182:185], v[208:211], v[44:47]
	v_mfma_f32_16x16x32_bf16 v[40:43], v[190:193], v[208:211], v[40:43]
	v_mfma_f32_16x16x32_bf16 v[28:31], v[182:185], v[216:219], v[28:31]
	v_mfma_f32_16x16x32_bf16 v[24:27], v[190:193], v[216:219], v[24:27]
	v_mfma_f32_16x16x32_bf16 v[12:15], v[182:185], v[224:227], v[12:15]
	v_mfma_f32_16x16x32_bf16 v[8:11], v[190:193], v[224:227], v[8:11]
	v_mfma_f32_16x16x32_bf16 v[4:7], v[182:185], v[232:235], v[4:7]
	v_mfma_f32_16x16x32_bf16 v[0:3], v[190:193], v[232:235], v[0:3]
	s_setprio 0
	s_barrier
; #define PG8_STAGE(bufoff, gbase, voff) do { _Pragma("unroll") for (int _i = 0; _i < 2; ++_i) \
;         __builtin_amdgcn_global_load_lds((const unsigned*)((const char*)(gbase) + (voff)[_i]), (PG8_LAS unsigned*)(lds + (bufoff) + ldsw + _i * 8192), 16, 0, 0); } while (0)
; #define PG8_LDA(dst, b, h) do { _Pragma("unroll") for (int m = 0; m < 4; ++m) _Pragma("unroll") for (int k = 0; k < 2; ++k) dst[m][k] = *(const PG8_LAS bf16x8*)(lds + PG8_SA(b, h) + aoff + m * 2048 + k * 1024); } while (0)
; #define PG8_LDB(dst, b, h) do { _Pragma("unroll") for (int n = 0; n < 2; ++n) _Pragma("unroll") for (int k = 0; k < 2; ++k) dst[n][k] = *(const PG8_LAS bf16x8*)(lds + PG8_SB(b, h) + boff + n * 2048 + k * 1024); } while (0)
; #define PG8_MMA(ai, bj, At, Bt) do { __builtin_amdgcn_s_setprio(1); _Pragma("unroll") for (int m = 0; m < 4; ++m) _Pragma("unroll") for (int n = 0; n < 2; ++n) _Pragma("unroll") for (int k = 0; k < 2; ++k) \
;         acc[ai][bj][m][n] = __builtin_amdgcn_mfma_f32_16x16x32_bf16(Bt[n][k], At[m][k], acc[ai][bj][m][n], 0, 0, 0); __builtin_amdgcn_s_setprio(0); } while (0)
; #define PG8_WAIT_V(n) asm volatile("s_waitcnt vmcnt(" #n ")" ::: "memory")
; #define PG8_WAIT_L(n) asm volatile("s_waitcnt lgkmcnt(" #n ")" ::: "memory")
; #define PG8_BAR __builtin_amdgcn_s_barrier()
; #define PG8_SCHED __builtin_amdgcn_sched_barrier(0)
; template <class Epi, class Sched, bool ALIGN_EPI = false, bool SP2 = false>
; __device__ __forceinline__ void gemm_phase(PG8_LAS unsigned char* lds, const Gemm g, const Sched& S, const Epi& E, const int wave0) {
;     ...
;         for (int t = 0; t < nt; t += 2) {
;             const bool last = (t == nt - 2);
;             const char* a1 = cA + (size_t)(t + 1) * kstep;
;             const char* a2 = last ? nA : cA + (size_t)(t + 2) * kstep; const char* b2 = last ? nB : cB + (size_t)(t + 2) * kstep;
;     ...
;             PG8_LDB(B0, 1, 0); PG8_LDB(B1, 1, 1); PG8_SCHED; PG8_LDA(At, 1, 0); PG8_STAGE(PG8_SA(0, 1), a2 + hstepA, voffA);
;             PG8_WAIT_V(8); PG8_WAIT_L(0); PG8_BAR; PG8_MMA(0, 0, At, B0); PG8_MMA(0, 1, At, B1); PG8_BAR; PG8_SCHED;
;             PG8_LDA(At, 1, 1); PG8_STAGE(PG8_SB(1, 0), b3, voffB); PG8_STAGE(PG8_SB(1, 1), b3 + hstepB, voffB); PG8_STAGE(PG8_SA(1, 0), a3, voffA);
;             PG8_WAIT_V(8); PG8_WAIT_L(0); PG8_BAR; PG8_MMA(1, 0, At, B0); PG8_MMA(1, 1, At, B1); PG8_BAR; PG8_SCHED;
	s_add_i32 s38, 0, 0x18000
	s_add_i32 s39, 0, 0x1c000
	ds_read_b128 v[144:147], v254
	ds_read_b128 v[148:151], v254 offset:1024
	ds_read_b128 v[152:155], v254 offset:2048
	ds_read_b128 v[156:159], v254 offset:3072
	ds_read_b128 v[178:181], v255
	ds_read_b128 v[182:185], v255 offset:1024
	ds_read_b128 v[186:189], v255 offset:2048
	ds_read_b128 v[190:193], v255 offset:3072
	s_add_u32 s18, s18, 0x80000
	s_addc_u32 s19, s19, 0
	s_mov_b32 m0, s25
	ds_read_b128 v[194:197], v143 offset:32768
	ds_read_b128 v[208:211], v143 offset:33792
	ds_read_b128 v[212:215], v143 offset:34816
	ds_read_b128 v[216:219], v143 offset:35840
	ds_read_b128 v[220:223], v143 offset:36864
	ds_read_b128 v[224:227], v143 offset:37888
	ds_read_b128 v[228:231], v143 offset:38912
	ds_read_b128 v[232:235], v143 offset:39936
	global_load_lds_dwordx4 v134, s[18:19]
	s_mov_b32 m0, s26
	s_nop 0
	global_load_lds_dwordx4 v132, s[18:19]
	s_waitcnt vmcnt(8)
	s_waitcnt lgkmcnt(0)
	s_setprio 1
	s_barrier
	v_mfma_f32_16x16x32_bf16 v[126:129], v[144:147], v[194:197], v[126:129]
	v_mfma_f32_16x16x32_bf16 v[122:125], v[152:155], v[194:197], v[122:125]
	v_mfma_f32_16x16x32_bf16 v[118:121], v[144:147], v[212:215], v[118:121]
	v_mfma_f32_16x16x32_bf16 v[114:117], v[152:155], v[212:215], v[114:117]
	v_mfma_f32_16x16x32_bf16 v[102:105], v[144:147], v[220:223], v[102:105]
	v_mfma_f32_16x16x32_bf16 v[98:101], v[152:155], v[220:223], v[98:101]
	v_mfma_f32_16x16x32_bf16 v[86:89], v[144:147], v[228:231], v[86:89]
	v_mfma_f32_16x16x32_bf16 v[82:85], v[152:155], v[228:231], v[82:85]
	s_setprio 0
	s_setprio 1
	v_mfma_f32_16x16x32_bf16 v[126:129], v[148:151], v[208:211], v[126:129]
	v_mfma_f32_16x16x32_bf16 v[122:125], v[156:159], v[208:211], v[122:125]
	v_mfma_f32_16x16x32_bf16 v[118:121], v[148:151], v[216:219], v[118:121]
	v_mfma_f32_16x16x32_bf16 v[114:117], v[156:159], v[216:219], v[114:117]
	v_mfma_f32_16x16x32_bf16 v[102:105], v[148:151], v[224:227], v[102:105]
	v_mfma_f32_16x16x32_bf16 v[98:101], v[156:159], v[224:227], v[98:101]
	v_mfma_f32_16x16x32_bf16 v[86:89], v[148:151], v[232:235], v[86:89]
	v_mfma_f32_16x16x32_bf16 v[82:85], v[156:159], v[232:235], v[82:85]
	s_setprio 0
	s_setprio 1
	v_mfma_f32_16x16x32_bf16 v[110:113], v[178:181], v[194:197], v[110:113]
	v_mfma_f32_16x16x32_bf16 v[106:109], v[186:189], v[194:197], v[106:109]
	v_mfma_f32_16x16x32_bf16 v[94:97], v[178:181], v[212:215], v[94:97]
	v_mfma_f32_16x16x32_bf16 v[90:93], v[186:189], v[212:215], v[90:93]
	v_mfma_f32_16x16x32_bf16 v[78:81], v[178:181], v[220:223], v[78:81]
	v_mfma_f32_16x16x32_bf16 v[74:77], v[186:189], v[220:223], v[74:77]
	v_mfma_f32_16x16x32_bf16 v[70:73], v[178:181], v[228:231], v[70:73]
	v_mfma_f32_16x16x32_bf16 v[66:69], v[186:189], v[228:231], v[66:69]
	s_setprio 0
	s_setprio 1
	v_mfma_f32_16x16x32_bf16 v[110:113], v[182:185], v[208:211], v[110:113]
	v_mfma_f32_16x16x32_bf16 v[106:109], v[190:193], v[208:211], v[106:109]
	v_mfma_f32_16x16x32_bf16 v[94:97], v[182:185], v[216:219], v[94:97]
	v_mfma_f32_16x16x32_bf16 v[90:93], v[190:193], v[216:219], v[90:93]
	v_mfma_f32_16x16x32_bf16 v[78:81], v[182:185], v[224:227], v[78:81]
	v_mfma_f32_16x16x32_bf16 v[74:77], v[190:193], v[224:227], v[74:77]
	v_mfma_f32_16x16x32_bf16 v[70:73], v[182:185], v[232:235], v[70:73]
	v_mfma_f32_16x16x32_bf16 v[66:69], v[190:193], v[232:235], v[66:69]
	s_setprio 0
	s_barrier
	s_add_i32 s18, s38, s22
	s_add_u32 s42, s16, 0x80
	s_addc_u32 s43, s17, 0
	s_mov_b32 m0, s18
	ds_read_b128 v[194:197], v143 offset:49152
	ds_read_b128 v[208:211], v143 offset:50176
	ds_read_b128 v[212:215], v143 offset:51200
	ds_read_b128 v[216:219], v143 offset:52224
	ds_read_b128 v[220:223], v143 offset:53248
	ds_read_b128 v[224:227], v143 offset:54272
	ds_read_b128 v[228:231], v143 offset:55296
	ds_read_b128 v[232:235], v143 offset:56320
	global_load_lds_dwordx4 v64, s[42:43]
	s_add_i32 m0, s18, 0x2000
	s_add_u32 s16, s16, 0x80080
	s_addc_u32 s17, s17, 0
	s_add_i32 s18, s39, s22
	global_load_lds_dwordx4 v130, s[42:43]
	s_mov_b32 m0, s18
	s_nop 0
	global_load_lds_dwordx4 v64, s[16:17]
	s_add_i32 m0, s18, 0x2000
	s_nop 0
	global_load_lds_dwordx4 v130, s[16:17]
	s_add_u32 s100, s100, 0x80
	s_addc_u32 s101, s101, 0
	s_mov_b32 m0, s27
	s_nop 0
	global_load_lds_dwordx4 v134, s[100:101]
	s_mov_b32 m0, s28
	s_nop 0
	global_load_lds_dwordx4 v132, s[100:101]
	s_waitcnt vmcnt(8)
	s_waitcnt lgkmcnt(0)
	s_setprio 1
	s_barrier
	v_mfma_f32_16x16x32_bf16 v[60:63], v[144:147], v[194:197], v[60:63]
	v_mfma_f32_16x16x32_bf16 v[56:59], v[152:155], v[194:197], v[56:59]
	v_mfma_f32_16x16x32_bf16 v[52:55], v[144:147], v[212:215], v[52:55]
	v_mfma_f32_16x16x32_bf16 v[48:51], v[152:155], v[212:215], v[48:51]
	v_mfma_f32_16x16x32_bf16 v[36:39], v[144:147], v[220:223], v[36:39]
	v_mfma_f32_16x16x32_bf16 v[32:35], v[152:155], v[220:223], v[32:35]
	v_mfma_f32_16x16x32_bf16 v[20:23], v[144:147], v[228:231], v[20:23]
	v_mfma_f32_16x16x32_bf16 v[16:19], v[152:155], v[228:231], v[16:19]
	s_setprio 0
	s_setprio 1
	v_mfma_f32_16x16x32_bf16 v[60:63], v[148:151], v[208:211], v[60:63]
	v_mfma_f32_16x16x32_bf16 v[56:59], v[156:159], v[208:211], v[56:59]
	v_mfma_f32_16x16x32_bf16 v[52:55], v[148:151], v[216:219], v[52:55]
	v_mfma_f32_16x16x32_bf16 v[48:51], v[156:159], v[216:219], v[48:51]
	v_mfma_f32_16x16x32_bf16 v[36:39], v[148:151], v[224:227], v[36:39]
	v_mfma_f32_16x16x32_bf16 v[32:35], v[156:159], v[224:227], v[32:35]
	v_mfma_f32_16x16x32_bf16 v[20:23], v[148:151], v[232:235], v[20:23]
	v_mfma_f32_16x16x32_bf16 v[16:19], v[156:159], v[232:235], v[16:19]
	s_setprio 0
	s_setprio 1
	v_mfma_f32_16x16x32_bf16 v[44:47], v[178:181], v[194:197], v[44:47]
	v_mfma_f32_16x16x32_bf16 v[40:43], v[186:189], v[194:197], v[40:43]
	v_mfma_f32_16x16x32_bf16 v[28:31], v[178:181], v[212:215], v[28:31]
	v_mfma_f32_16x16x32_bf16 v[24:27], v[186:189], v[212:215], v[24:27]
	v_mfma_f32_16x16x32_bf16 v[12:15], v[178:181], v[220:223], v[12:15]
	v_mfma_f32_16x16x32_bf16 v[8:11], v[186:189], v[220:223], v[8:11]
	v_mfma_f32_16x16x32_bf16 v[4:7], v[178:181], v[228:231], v[4:7]
	v_mfma_f32_16x16x32_bf16 v[0:3], v[186:189], v[228:231], v[0:3]
	s_setprio 0
	s_setprio 1
	v_mfma_f32_16x16x32_bf16 v[44:47], v[182:185], v[208:211], v[44:47]
	v_mfma_f32_16x16x32_bf16 v[40:43], v[190:193], v[208:211], v[40:43]
	v_mfma_f32_16x16x32_bf16 v[28:31], v[182:185], v[216:219], v[28:31]
	v_mfma_f32_16x16x32_bf16 v[24:27], v[190:193], v[216:219], v[24:27]
	v_mfma_f32_16x16x32_bf16 v[12:15], v[182:185], v[224:227], v[12:15]
	v_mfma_f32_16x16x32_bf16 v[8:11], v[190:193], v[224:227], v[8:11]
	v_mfma_f32_16x16x32_bf16 v[4:7], v[182:185], v[232:235], v[4:7]
	v_mfma_f32_16x16x32_bf16 v[0:3], v[190:193], v[232:235], v[0:3]
	s_setprio 0
	s_barrier
	s_add_i32 s37, s37, 2
	s_add_u32 s0, s0, 0x100
	s_addc_u32 s1, s1, 0
	s_add_u32 s35, s35, 0x100
	s_addc_u32 s36, s36, 0
	s_cmp_gt_u32 s37, 29
	s_cbranch_scc0 .LBB0_316
	s_mov_b64 s[42:43], 0x80
	s_and_b64 vcc, exec, s[6:7]
	s_mov_b64 s[34:35], 0x45000
	s_cbranch_vccz .LBB0_319
	s_barrier

; #define PG8_STAGE(bufoff, gbase, voff) do { _Pragma("unroll") for (int _i = 0; _i < 2; ++_i) \
;         __builtin_amdgcn_global_load_lds((const unsigned*)((const char*)(gbase) + (voff)[_i]), (PG8_LAS unsigned*)(lds + (bufoff) + ldsw + _i * 8192), 16, 0, 0); } while (0)
; #define PG8_LDA(dst, b, h) do { _Pragma("unroll") for (int m = 0; m < 4; ++m) _Pragma("unroll") for (int k = 0; k < 2; ++k) dst[m][k] = *(const PG8_LAS bf16x8*)(lds + PG8_SA(b, h) + aoff + m * 2048 + k * 1024); } while (0)
; #define PG8_LDB(dst, b, h) do { _Pragma("unroll") for (int n = 0; n < 2; ++n) _Pragma("unroll") for (int k = 0; k < 2; ++k) dst[n][k] = *(const PG8_LAS bf16x8*)(lds + PG8_SB(b, h) + boff + n * 2048 + k * 1024); } while (0)
; #define PG8_MMA(ai, bj, At, Bt) do { __builtin_amdgcn_s_setprio(1); _Pragma("unroll") for (int m = 0; m < 4; ++m) _Pragma("unroll") for (int n = 0; n < 2; ++n) _Pragma("unroll") for (int k = 0; k < 2; ++k) \
;         acc[ai][bj][m][n] = __builtin_amdgcn_mfma_f32_16x16x32_bf16(Bt[n][k], At[m][k], acc[ai][bj][m][n], 0, 0, 0); __builtin_amdgcn_s_setprio(0); } while (0)
; template <class Epi, class Sched, bool ALIGN_EPI = false, bool SP2 = false>
; __device__ __forceinline__ void gemm_phase(PG8_LAS unsigned char* lds, const Gemm g, const Sched& S, const Epi& E, const int wave0) {
;     ...
;         const char* nA = has_next ? (const char*)g.A + (size_t)nxt.z * g.zsA + (size_t)nxt.pm * tstepA + (size_t)nxt.k0 * 2 : cA; const char* nB = has_next ? (const char*)g.Bt + (size_t)nxt.z * g.zsB + (size_t)nxt.pn * tstepB + (size_t)nxt.k0 * 2 : cB;
;         for (int t = 0; t < nt; t += 2) {
;             const bool last = (t == nt - 2);
;             const char* a1 = cA + (size_t)(t + 1) * kstep;
;             const char* a2 = last ? nA : cA + (size_t)(t + 2) * kstep; const char* b2 = last ? nB : cB + (size_t)(t + 2) * kstep;
;     ...
;             PG8_LDB(B0, 0, 0); PG8_LDB(B1, 0, 1); PG8_SCHED; PG8_LDA(At, 0, 0); PG8_STAGE(PG8_SA(1, 1), a1 + hstepA, voffA);
;             PG8_WAIT_V(8); PG8_WAIT_L(0); PG8_BAR; PG8_MMA(0, 0, At, B0); PG8_MMA(0, 1, At, B1); PG8_BAR; PG8_SCHED;
;             PG8_LDA(At, 0, 1); PG8_STAGE(PG8_SB(0, 0), b2, voffB); PG8_STAGE(PG8_SB(0, 1), b2 + hstepB, voffB); PG8_STAGE(PG8_SA(0, 0), a2, voffA);
;             PG8_WAIT_V(8); PG8_WAIT_L(0); PG8_BAR; PG8_MMA(1, 0, At, B0); PG8_MMA(1, 1, At, B1); PG8_BAR; PG8_SCHED;
.LBB0_1178:
	s_add_u32 s2, s0, 0xfffc0080
	s_addc_u32 s3, s1, -1
	s_add_i32 s31, 0, 0x10000
	s_cmp_eq_u32 s19, 12
	s_cselect_b32 s17, s45, s3
	s_cselect_b32 s16, s44, s2
	s_cselect_b32 s3, s9, s18
	s_cselect_b32 s2, s11, s13
	s_add_i32 s33, 0, 0x14000
	ds_read_b128 v[130:133], v252
	ds_read_b128 v[134:137], v252 offset:1024
	ds_read_b128 v[148:151], v252 offset:2048
	ds_read_b128 v[152:155], v252 offset:3072
	ds_read_b128 v[178:181], v253
	ds_read_b128 v[182:185], v253 offset:1024
	ds_read_b128 v[186:189], v253 offset:2048
	ds_read_b128 v[190:193], v253 offset:3072
	s_add_i32 m0, s23, 0xc000
	ds_read_b128 v[194:197], v159
	ds_read_b128 v[208:211], v159 offset:1024
	ds_read_b128 v[212:215], v159 offset:2048
	ds_read_b128 v[216:219], v159 offset:3072
	ds_read_b128 v[220:223], v159 offset:4096
	ds_read_b128 v[224:227], v159 offset:5120
	ds_read_b128 v[228:231], v159 offset:6144
	ds_read_b128 v[232:235], v159 offset:7168
	global_load_lds_dwordx4 v144, s[0:1]
	s_add_i32 m0, s23, 0xe000
	s_nop 0
	global_load_lds_dwordx4 v146, s[0:1]
	s_waitcnt vmcnt(8)
	s_waitcnt lgkmcnt(0)
	s_setprio 1
	s_barrier
	v_mfma_f32_16x16x32_bf16 v[126:129], v[130:133], v[194:197], v[126:129]
	v_mfma_f32_16x16x32_bf16 v[122:125], v[148:151], v[194:197], v[122:125]
	v_mfma_f32_16x16x32_bf16 v[110:113], v[130:133], v[212:215], v[110:113]
	v_mfma_f32_16x16x32_bf16 v[106:109], v[148:151], v[212:215], v[106:109]
	v_mfma_f32_16x16x32_bf16 v[94:97], v[130:133], v[220:223], v[94:97]
	v_mfma_f32_16x16x32_bf16 v[90:93], v[148:151], v[220:223], v[90:93]
	v_mfma_f32_16x16x32_bf16 v[78:81], v[130:133], v[228:231], v[78:81]
	v_mfma_f32_16x16x32_bf16 v[74:77], v[148:151], v[228:231], v[74:77]
	s_setprio 0
	s_setprio 1
	v_mfma_f32_16x16x32_bf16 v[126:129], v[134:137], v[208:211], v[126:129]
	v_mfma_f32_16x16x32_bf16 v[122:125], v[152:155], v[208:211], v[122:125]
	v_mfma_f32_16x16x32_bf16 v[110:113], v[134:137], v[216:219], v[110:113]
	v_mfma_f32_16x16x32_bf16 v[106:109], v[152:155], v[216:219], v[106:109]
	v_mfma_f32_16x16x32_bf16 v[94:97], v[134:137], v[224:227], v[94:97]
	v_mfma_f32_16x16x32_bf16 v[90:93], v[152:155], v[224:227], v[90:93]
	v_mfma_f32_16x16x32_bf16 v[78:81], v[134:137], v[232:235], v[78:81]
	v_mfma_f32_16x16x32_bf16 v[74:77], v[152:155], v[232:235], v[74:77]
	s_setprio 0
	s_setprio 1
	v_mfma_f32_16x16x32_bf16 v[118:121], v[178:181], v[194:197], v[118:121]
	v_mfma_f32_16x16x32_bf16 v[114:117], v[186:189], v[194:197], v[114:117]
	v_mfma_f32_16x16x32_bf16 v[102:105], v[178:181], v[212:215], v[102:105]
	v_mfma_f32_16x16x32_bf16 v[98:101], v[186:189], v[212:215], v[98:101]
	v_mfma_f32_16x16x32_bf16 v[86:89], v[178:181], v[220:223], v[86:89]
	v_mfma_f32_16x16x32_bf16 v[82:85], v[186:189], v[220:223], v[82:85]
	v_mfma_f32_16x16x32_bf16 v[70:73], v[178:181], v[228:231], v[70:73]
	v_mfma_f32_16x16x32_bf16 v[66:69], v[186:189], v[228:231], v[66:69]
	s_setprio 0
	s_setprio 1
	v_mfma_f32_16x16x32_bf16 v[118:121], v[182:185], v[208:211], v[118:121]
	v_mfma_f32_16x16x32_bf16 v[114:117], v[190:193], v[208:211], v[114:117]
	v_mfma_f32_16x16x32_bf16 v[102:105], v[182:185], v[216:219], v[102:105]
	v_mfma_f32_16x16x32_bf16 v[98:101], v[190:193], v[216:219], v[98:101]
	v_mfma_f32_16x16x32_bf16 v[86:89], v[182:185], v[224:227], v[86:89]
	v_mfma_f32_16x16x32_bf16 v[82:85], v[190:193], v[224:227], v[82:85]
	v_mfma_f32_16x16x32_bf16 v[70:73], v[182:185], v[232:235], v[70:73]
	v_mfma_f32_16x16x32_bf16 v[66:69], v[190:193], v[232:235], v[66:69]
	s_setprio 0
	s_barrier
	s_add_i32 s31, s31, s22
	s_mov_b32 m0, s31
	ds_read_b128 v[194:197], v159 offset:16384
	ds_read_b128 v[208:211], v159 offset:17408
	ds_read_b128 v[212:215], v159 offset:18432
	ds_read_b128 v[216:219], v159 offset:19456
	ds_read_b128 v[220:223], v159 offset:20480
	ds_read_b128 v[224:227], v159 offset:21504
	ds_read_b128 v[228:231], v159 offset:22528
	ds_read_b128 v[232:235], v159 offset:23552
	global_load_lds_dwordx4 v64, s[2:3]
	s_add_i32 m0, s31, 0x2000
	s_add_u32 s34, s2, 0x40000
	s_addc_u32 s35, s3, 0
	s_add_i32 s31, s33, s22
	global_load_lds_dwordx4 v138, s[2:3]
	s_mov_b32 m0, s31
	s_mov_b64 s[100:101], s[16:17]
	global_load_lds_dwordx4 v64, s[34:35]
	s_add_i32 m0, s31, 0x2000
	s_nop 0
	global_load_lds_dwordx4 v138, s[34:35]
	s_mov_b32 m0, s23
	s_nop 0
	global_load_lds_dwordx4 v142, s[16:17]
	s_mov_b32 m0, s24
	s_nop 0
	global_load_lds_dwordx4 v140, s[16:17]
	s_waitcnt vmcnt(8)
	s_waitcnt lgkmcnt(0)
	s_setprio 1
	s_barrier
	v_mfma_f32_16x16x32_bf16 v[60:63], v[130:133], v[194:197], v[60:63]
	v_mfma_f32_16x16x32_bf16 v[56:59], v[148:151], v[194:197], v[56:59]
	v_mfma_f32_16x16x32_bf16 v[44:47], v[130:133], v[212:215], v[44:47]
	v_mfma_f32_16x16x32_bf16 v[40:43], v[148:151], v[212:215], v[40:43]
	v_mfma_f32_16x16x32_bf16 v[28:31], v[130:133], v[220:223], v[28:31]
	v_mfma_f32_16x16x32_bf16 v[24:27], v[148:151], v[220:223], v[24:27]
	v_mfma_f32_16x16x32_bf16 v[12:15], v[130:133], v[228:231], v[12:15]
	v_mfma_f32_16x16x32_bf16 v[8:11], v[148:151], v[228:231], v[8:11]
	s_setprio 0
	s_setprio 1
	v_mfma_f32_16x16x32_bf16 v[60:63], v[134:137], v[208:211], v[60:63]
	v_mfma_f32_16x16x32_bf16 v[56:59], v[152:155], v[208:211], v[56:59]
	v_mfma_f32_16x16x32_bf16 v[44:47], v[134:137], v[216:219], v[44:47]
	v_mfma_f32_16x16x32_bf16 v[40:43], v[152:155], v[216:219], v[40:43]
	v_mfma_f32_16x16x32_bf16 v[28:31], v[134:137], v[224:227], v[28:31]
	v_mfma_f32_16x16x32_bf16 v[24:27], v[152:155], v[224:227], v[24:27]
	v_mfma_f32_16x16x32_bf16 v[12:15], v[134:137], v[232:235], v[12:15]
	v_mfma_f32_16x16x32_bf16 v[8:11], v[152:155], v[232:235], v[8:11]
	s_setprio 0
	s_setprio 1
	v_mfma_f32_16x16x32_bf16 v[52:55], v[178:181], v[194:197], v[52:55]
	v_mfma_f32_16x16x32_bf16 v[48:51], v[186:189], v[194:197], v[48:51]
	v_mfma_f32_16x16x32_bf16 v[36:39], v[178:181], v[212:215], v[36:39]
	v_mfma_f32_16x16x32_bf16 v[32:35], v[186:189], v[212:215], v[32:35]
	v_mfma_f32_16x16x32_bf16 v[20:23], v[178:181], v[220:223], v[20:23]
	v_mfma_f32_16x16x32_bf16 v[16:19], v[186:189], v[220:223], v[16:19]
	v_mfma_f32_16x16x32_bf16 v[4:7], v[178:181], v[228:231], v[4:7]
	v_mfma_f32_16x16x32_bf16 v[0:3], v[186:189], v[228:231], v[0:3]
	s_setprio 0
	s_setprio 1
	v_mfma_f32_16x16x32_bf16 v[52:55], v[182:185], v[208:211], v[52:55]
	v_mfma_f32_16x16x32_bf16 v[48:51], v[190:193], v[208:211], v[48:51]
	v_mfma_f32_16x16x32_bf16 v[36:39], v[182:185], v[216:219], v[36:39]
	v_mfma_f32_16x16x32_bf16 v[32:35], v[190:193], v[216:219], v[32:35]
	v_mfma_f32_16x16x32_bf16 v[20:23], v[182:185], v[224:227], v[20:23]
	v_mfma_f32_16x16x32_bf16 v[16:19], v[190:193], v[224:227], v[16:19]
	v_mfma_f32_16x16x32_bf16 v[4:7], v[182:185], v[232:235], v[4:7]
	v_mfma_f32_16x16x32_bf16 v[0:3], v[190:193], v[232:235], v[0:3]
	s_setprio 0
	s_barrier
; #define PG8_STAGE(bufoff, gbase, voff) do { _Pragma("unroll") for (int _i = 0; _i < 2; ++_i) \
;         __builtin_amdgcn_global_load_lds((const unsigned*)((const char*)(gbase) + (voff)[_i]), (PG8_LAS unsigned*)(lds + (bufoff) + ldsw + _i * 8192), 16, 0, 0); } while (0)
; #define PG8_LDA(dst, b, h) do { _Pragma("unroll") for (int m = 0; m < 4; ++m) _Pragma("unroll") for (int k = 0; k < 2; ++k) dst[m][k] = *(const PG8_LAS bf16x8*)(lds + PG8_SA(b, h) + aoff + m * 2048 + k * 1024); } while (0)
; #define PG8_LDB(dst, b, h) do { _Pragma("unroll") for (int n = 0; n < 2; ++n) _Pragma("unroll") for (int k = 0; k < 2; ++k) dst[n][k] = *(const PG8_LAS bf16x8*)(lds + PG8_SB(b, h) + boff + n * 2048 + k * 1024); } while (0)
; #define PG8_MMA(ai, bj, At, Bt) do { __builtin_amdgcn_s_setprio(1); _Pragma("unroll") for (int m = 0; m < 4; ++m) _Pragma("unroll") for (int n = 0; n < 2; ++n) _Pragma("unroll") for (int k = 0; k < 2; ++k) \
;         acc[ai][bj][m][n] = __builtin_amdgcn_mfma_f32_16x16x32_bf16(Bt[n][k], At[m][k], acc[ai][bj][m][n], 0, 0, 0); __builtin_amdgcn_s_setprio(0); } while (0)
; #define PG8_WAIT_V(n) asm volatile("s_waitcnt vmcnt(" #n ")" ::: "memory")
; #define PG8_WAIT_L(n) asm volatile("s_waitcnt lgkmcnt(" #n ")" ::: "memory")
; #define PG8_BAR __builtin_amdgcn_s_barrier()
; #define PG8_SCHED __builtin_amdgcn_sched_barrier(0)
; template <class Epi, class Sched, bool ALIGN_EPI = false, bool SP2 = false>
; __device__ __forceinline__ void gemm_phase(PG8_LAS unsigned char* lds, const Gemm g, const Sched& S, const Epi& E, const int wave0) {
;     ...
;         for (int t = 0; t < nt; t += 2) {
;             const bool last = (t == nt - 2);
;             const char* a1 = cA + (size_t)(t + 1) * kstep;
;             const char* a2 = last ? nA : cA + (size_t)(t + 2) * kstep; const char* b2 = last ? nB : cB + (size_t)(t + 2) * kstep;
;     ...
;             PG8_LDB(B0, 1, 0); PG8_LDB(B1, 1, 1); PG8_SCHED; PG8_LDA(At, 1, 0); PG8_STAGE(PG8_SA(0, 1), a2 + hstepA, voffA);
;             PG8_WAIT_V(8); PG8_WAIT_L(0); PG8_BAR; PG8_MMA(0, 0, At, B0); PG8_MMA(0, 1, At, B1); PG8_BAR; PG8_SCHED;
;             PG8_LDA(At, 1, 1); PG8_STAGE(PG8_SB(1, 0), b3, voffB); PG8_STAGE(PG8_SB(1, 1), b3 + hstepB, voffB); PG8_STAGE(PG8_SA(1, 0), a3, voffA);
;             PG8_WAIT_V(8); PG8_WAIT_L(0); PG8_BAR; PG8_MMA(1, 0, At, B0); PG8_MMA(1, 1, At, B1); PG8_BAR; PG8_SCHED;
	s_add_i32 s31, 0, 0x18000
	s_add_i32 s33, 0, 0x1c000
	ds_read_b128 v[130:133], v254
	ds_read_b128 v[134:137], v254 offset:1024
	ds_read_b128 v[148:151], v254 offset:2048
	ds_read_b128 v[152:155], v254 offset:3072
	ds_read_b128 v[178:181], v255
	ds_read_b128 v[182:185], v255 offset:1024
	ds_read_b128 v[186:189], v255 offset:2048
	ds_read_b128 v[190:193], v255 offset:3072
	s_add_u32 s16, s16, 0x40000
	s_addc_u32 s17, s17, 0
	s_mov_b32 m0, s25
	ds_read_b128 v[194:197], v159 offset:32768
	ds_read_b128 v[208:211], v159 offset:33792
	ds_read_b128 v[212:215], v159 offset:34816
	ds_read_b128 v[216:219], v159 offset:35840
	ds_read_b128 v[220:223], v159 offset:36864
	ds_read_b128 v[224:227], v159 offset:37888
	ds_read_b128 v[228:231], v159 offset:38912
	ds_read_b128 v[232:235], v159 offset:39936
	global_load_lds_dwordx4 v142, s[16:17]
	s_mov_b32 m0, s26
	s_nop 0
	global_load_lds_dwordx4 v140, s[16:17]
	s_waitcnt vmcnt(8)
	s_waitcnt lgkmcnt(0)
	s_setprio 1
	s_barrier
	v_mfma_f32_16x16x32_bf16 v[126:129], v[130:133], v[194:197], v[126:129]
	v_mfma_f32_16x16x32_bf16 v[122:125], v[148:151], v[194:197], v[122:125]
	v_mfma_f32_16x16x32_bf16 v[110:113], v[130:133], v[212:215], v[110:113]
	v_mfma_f32_16x16x32_bf16 v[106:109], v[148:151], v[212:215], v[106:109]
	v_mfma_f32_16x16x32_bf16 v[94:97], v[130:133], v[220:223], v[94:97]
	v_mfma_f32_16x16x32_bf16 v[90:93], v[148:151], v[220:223], v[90:93]
	v_mfma_f32_16x16x32_bf16 v[78:81], v[130:133], v[228:231], v[78:81]
	v_mfma_f32_16x16x32_bf16 v[74:77], v[148:151], v[228:231], v[74:77]
	s_setprio 0
	s_setprio 1
	v_mfma_f32_16x16x32_bf16 v[126:129], v[134:137], v[208:211], v[126:129]
	v_mfma_f32_16x16x32_bf16 v[122:125], v[152:155], v[208:211], v[122:125]
	v_mfma_f32_16x16x32_bf16 v[110:113], v[134:137], v[216:219], v[110:113]
	v_mfma_f32_16x16x32_bf16 v[106:109], v[152:155], v[216:219], v[106:109]
	v_mfma_f32_16x16x32_bf16 v[94:97], v[134:137], v[224:227], v[94:97]
	v_mfma_f32_16x16x32_bf16 v[90:93], v[152:155], v[224:227], v[90:93]
	v_mfma_f32_16x16x32_bf16 v[78:81], v[134:137], v[232:235], v[78:81]
	v_mfma_f32_16x16x32_bf16 v[74:77], v[152:155], v[232:235], v[74:77]
	s_setprio 0
	s_setprio 1
	v_mfma_f32_16x16x32_bf16 v[118:121], v[178:181], v[194:197], v[118:121]
	v_mfma_f32_16x16x32_bf16 v[114:117], v[186:189], v[194:197], v[114:117]
	v_mfma_f32_16x16x32_bf16 v[102:105], v[178:181], v[212:215], v[102:105]
	v_mfma_f32_16x16x32_bf16 v[98:101], v[186:189], v[212:215], v[98:101]
	v_mfma_f32_16x16x32_bf16 v[86:89], v[178:181], v[220:223], v[86:89]
	v_mfma_f32_16x16x32_bf16 v[82:85], v[186:189], v[220:223], v[82:85]
	v_mfma_f32_16x16x32_bf16 v[70:73], v[178:181], v[228:231], v[70:73]
	v_mfma_f32_16x16x32_bf16 v[66:69], v[186:189], v[228:231], v[66:69]
	s_setprio 0
	s_setprio 1
	v_mfma_f32_16x16x32_bf16 v[118:121], v[182:185], v[208:211], v[118:121]
	v_mfma_f32_16x16x32_bf16 v[114:117], v[190:193], v[208:211], v[114:117]
	v_mfma_f32_16x16x32_bf16 v[102:105], v[182:185], v[216:219], v[102:105]
	v_mfma_f32_16x16x32_bf16 v[98:101], v[190:193], v[216:219], v[98:101]
	v_mfma_f32_16x16x32_bf16 v[86:89], v[182:185], v[224:227], v[86:89]
	v_mfma_f32_16x16x32_bf16 v[82:85], v[190:193], v[224:227], v[82:85]
	v_mfma_f32_16x16x32_bf16 v[70:73], v[182:185], v[232:235], v[70:73]
	v_mfma_f32_16x16x32_bf16 v[66:69], v[190:193], v[232:235], v[66:69]
	s_setprio 0
	s_barrier
	s_add_i32 s16, s31, s22
	s_add_u32 s36, s2, 0x80
	s_addc_u32 s37, s3, 0
	s_mov_b32 m0, s16
	ds_read_b128 v[194:197], v159 offset:49152
	ds_read_b128 v[208:211], v159 offset:50176
	ds_read_b128 v[212:215], v159 offset:51200
	ds_read_b128 v[216:219], v159 offset:52224
	ds_read_b128 v[220:223], v159 offset:53248
	ds_read_b128 v[224:227], v159 offset:54272
	ds_read_b128 v[228:231], v159 offset:55296
	ds_read_b128 v[232:235], v159 offset:56320
	global_load_lds_dwordx4 v64, s[36:37]
	s_add_i32 m0, s16, 0x2000
	s_add_u32 s2, s2, 0x40080
	s_addc_u32 s3, s3, 0
	s_add_i32 s16, s33, s22
	global_load_lds_dwordx4 v138, s[36:37]
	s_mov_b32 m0, s16
	s_nop 0
	global_load_lds_dwordx4 v64, s[2:3]
	s_add_i32 m0, s16, 0x2000
	s_nop 0
	global_load_lds_dwordx4 v138, s[2:3]
	s_add_u32 s100, s100, 0x80
	s_addc_u32 s101, s101, 0
	s_mov_b32 m0, s27
	s_nop 0
	global_load_lds_dwordx4 v142, s[100:101]
	s_mov_b32 m0, s28
	s_nop 0
	global_load_lds_dwordx4 v140, s[100:101]
	s_waitcnt vmcnt(8)
	s_waitcnt lgkmcnt(0)
	s_setprio 1
	s_barrier
	v_mfma_f32_16x16x32_bf16 v[60:63], v[130:133], v[194:197], v[60:63]
	v_mfma_f32_16x16x32_bf16 v[56:59], v[148:151], v[194:197], v[56:59]
	v_mfma_f32_16x16x32_bf16 v[44:47], v[130:133], v[212:215], v[44:47]
	v_mfma_f32_16x16x32_bf16 v[40:43], v[148:151], v[212:215], v[40:43]
	v_mfma_f32_16x16x32_bf16 v[28:31], v[130:133], v[220:223], v[28:31]
	v_mfma_f32_16x16x32_bf16 v[24:27], v[148:151], v[220:223], v[24:27]
	v_mfma_f32_16x16x32_bf16 v[12:15], v[130:133], v[228:231], v[12:15]
	v_mfma_f32_16x16x32_bf16 v[8:11], v[148:151], v[228:231], v[8:11]
	s_setprio 0
	s_setprio 1
	v_mfma_f32_16x16x32_bf16 v[60:63], v[134:137], v[208:211], v[60:63]
	v_mfma_f32_16x16x32_bf16 v[56:59], v[152:155], v[208:211], v[56:59]
	v_mfma_f32_16x16x32_bf16 v[44:47], v[134:137], v[216:219], v[44:47]
	v_mfma_f32_16x16x32_bf16 v[40:43], v[152:155], v[216:219], v[40:43]
	v_mfma_f32_16x16x32_bf16 v[28:31], v[134:137], v[224:227], v[28:31]
	v_mfma_f32_16x16x32_bf16 v[24:27], v[152:155], v[224:227], v[24:27]
	v_mfma_f32_16x16x32_bf16 v[12:15], v[134:137], v[232:235], v[12:15]
	v_mfma_f32_16x16x32_bf16 v[8:11], v[152:155], v[232:235], v[8:11]
	s_setprio 0
	s_setprio 1
	v_mfma_f32_16x16x32_bf16 v[52:55], v[178:181], v[194:197], v[52:55]
	v_mfma_f32_16x16x32_bf16 v[48:51], v[186:189], v[194:197], v[48:51]
	v_mfma_f32_16x16x32_bf16 v[36:39], v[178:181], v[212:215], v[36:39]
	v_mfma_f32_16x16x32_bf16 v[32:35], v[186:189], v[212:215], v[32:35]
	v_mfma_f32_16x16x32_bf16 v[20:23], v[178:181], v[220:223], v[20:23]
	v_mfma_f32_16x16x32_bf16 v[16:19], v[186:189], v[220:223], v[16:19]
	v_mfma_f32_16x16x32_bf16 v[4:7], v[178:181], v[228:231], v[4:7]
	v_mfma_f32_16x16x32_bf16 v[0:3], v[186:189], v[228:231], v[0:3]
	s_setprio 0
	s_setprio 1
	v_mfma_f32_16x16x32_bf16 v[52:55], v[182:185], v[208:211], v[52:55]
	v_mfma_f32_16x16x32_bf16 v[48:51], v[190:193], v[208:211], v[48:51]
	v_mfma_f32_16x16x32_bf16 v[36:39], v[182:185], v[216:219], v[36:39]
	v_mfma_f32_16x16x32_bf16 v[32:35], v[190:193], v[216:219], v[32:35]
	v_mfma_f32_16x16x32_bf16 v[20:23], v[182:185], v[224:227], v[20:23]
	v_mfma_f32_16x16x32_bf16 v[16:19], v[190:193], v[224:227], v[16:19]
	v_mfma_f32_16x16x32_bf16 v[4:7], v[182:185], v[232:235], v[4:7]
	v_mfma_f32_16x16x32_bf16 v[0:3], v[190:193], v[232:235], v[0:3]
	s_setprio 0
	s_barrier
	s_add_i32 s19, s19, 2
	s_add_u32 s0, s0, 0x100
	s_addc_u32 s1, s1, 0
	s_add_u32 s13, s13, 0x100
	s_addc_u32 s18, s18, 0
	s_cmp_gt_u32 s19, 13
	s_cbranch_scc0 .LBB0_1178
	s_mov_b64 s[36:37], 0x80
	s_and_b64 vcc, exec, s[6:7]
	s_cbranch_vccz .LBB0_1181
	s_barrier

; #define PG8_STAGE(bufoff, gbase, voff) do { _Pragma("unroll") for (int _i = 0; _i < 2; ++_i) \
;         __builtin_amdgcn_global_load_lds((const unsigned*)((const char*)(gbase) + (voff)[_i]), (PG8_LAS unsigned*)(lds + (bufoff) + ldsw + _i * 8192), 16, 0, 0); } while (0)
; #define PG8_LDA(dst, b, h) do { _Pragma("unroll") for (int m = 0; m < 4; ++m) _Pragma("unroll") for (int k = 0; k < 2; ++k) dst[m][k] = *(const PG8_LAS bf16x8*)(lds + PG8_SA(b, h) + aoff + m * 2048 + k * 1024); } while (0)
; #define PG8_LDB(dst, b, h) do { _Pragma("unroll") for (int n = 0; n < 2; ++n) _Pragma("unroll") for (int k = 0; k < 2; ++k) dst[n][k] = *(const PG8_LAS bf16x8*)(lds + PG8_SB(b, h) + boff + n * 2048 + k * 1024); } while (0)
; #define PG8_MMA(ai, bj, At, Bt) do { __builtin_amdgcn_s_setprio(1); _Pragma("unroll") for (int m = 0; m < 4; ++m) _Pragma("unroll") for (int n = 0; n < 2; ++n) _Pragma("unroll") for (int k = 0; k < 2; ++k) \
;         acc[ai][bj][m][n] = __builtin_amdgcn_mfma_f32_16x16x32_bf16(Bt[n][k], At[m][k], acc[ai][bj][m][n], 0, 0, 0); __builtin_amdgcn_s_setprio(0); } while (0)
; template <class Epi, class Sched, bool ALIGN_EPI = false, bool SP2 = false>
; __device__ __forceinline__ void gemm_phase(PG8_LAS unsigned char* lds, const Gemm g, const Sched& S, const Epi& E, const int wave0) {
;     ...
;         const char* nA = has_next ? (const char*)g.A + (size_t)nxt.z * g.zsA + (size_t)nxt.pm * tstepA + (size_t)nxt.k0 * 2 : cA; const char* nB = has_next ? (const char*)g.Bt + (size_t)nxt.z * g.zsB + (size_t)nxt.pn * tstepB + (size_t)nxt.k0 * 2 : cB;
;         for (int t = 0; t < nt; t += 2) {
;             const bool last = (t == nt - 2);
;             const char* a1 = cA + (size_t)(t + 1) * kstep;
;             const char* a2 = last ? nA : cA + (size_t)(t + 2) * kstep; const char* b2 = last ? nB : cB + (size_t)(t + 2) * kstep;
;     ...
;             PG8_LDB(B0, 0, 0); PG8_LDB(B1, 0, 1); PG8_SCHED; PG8_LDA(At, 0, 0); PG8_STAGE(PG8_SA(1, 1), a1 + hstepA, voffA);
;             PG8_WAIT_V(8); PG8_WAIT_L(0); PG8_BAR; PG8_MMA(0, 0, At, B0); PG8_MMA(0, 1, At, B1); PG8_BAR; PG8_SCHED;
;             PG8_LDA(At, 0, 1); PG8_STAGE(PG8_SB(0, 0), b2, voffB); PG8_STAGE(PG8_SB(0, 1), b2 + hstepB, voffB); PG8_STAGE(PG8_SA(0, 0), a2, voffA);
;             PG8_WAIT_V(8); PG8_WAIT_L(0); PG8_BAR; PG8_MMA(1, 0, At, B0); PG8_MMA(1, 1, At, B1); PG8_BAR; PG8_SCHED;
.LBB0_1231:
	s_add_u32 s2, s0, 0xfffc0080
	s_addc_u32 s3, s1, -1
	s_add_i32 s31, 0, 0x10000
	s_cmp_eq_u32 s19, 12
	s_cselect_b32 s17, s43, s3
	s_cselect_b32 s16, s42, s2
	s_cselect_b32 s3, s9, s18
	s_cselect_b32 s2, s11, s13
	s_add_i32 s33, 0, 0x14000
	ds_read_b128 v[140:143], v252
	ds_read_b128 v[144:147], v252 offset:1024
	ds_read_b128 v[154:157], v252 offset:2048
	ds_read_b128 v[158:161], v252 offset:3072
	ds_read_b128 v[178:181], v253
	ds_read_b128 v[182:185], v253 offset:1024
	ds_read_b128 v[186:189], v253 offset:2048
	ds_read_b128 v[190:193], v253 offset:3072
	s_add_i32 m0, s23, 0xc000
	ds_read_b128 v[194:197], v153
	ds_read_b128 v[208:211], v153 offset:1024
	ds_read_b128 v[212:215], v153 offset:2048
	ds_read_b128 v[216:219], v153 offset:3072
	ds_read_b128 v[220:223], v153 offset:4096
	ds_read_b128 v[224:227], v153 offset:5120
	ds_read_b128 v[228:231], v153 offset:6144
	ds_read_b128 v[232:235], v153 offset:7168
	global_load_lds_dwordx4 v136, s[0:1]
	s_add_i32 m0, s23, 0xe000
	s_nop 0
	global_load_lds_dwordx4 v138, s[0:1]
	s_waitcnt vmcnt(8)
	s_waitcnt lgkmcnt(0)
	s_setprio 1
	s_barrier
	v_mfma_f32_16x16x32_bf16 v[126:129], v[140:143], v[194:197], v[126:129]
	v_mfma_f32_16x16x32_bf16 v[122:125], v[154:157], v[194:197], v[122:125]
	v_mfma_f32_16x16x32_bf16 v[110:113], v[140:143], v[212:215], v[110:113]
	v_mfma_f32_16x16x32_bf16 v[106:109], v[154:157], v[212:215], v[106:109]
	v_mfma_f32_16x16x32_bf16 v[94:97], v[140:143], v[220:223], v[94:97]
	v_mfma_f32_16x16x32_bf16 v[90:93], v[154:157], v[220:223], v[90:93]
	v_mfma_f32_16x16x32_bf16 v[78:81], v[140:143], v[228:231], v[78:81]
	v_mfma_f32_16x16x32_bf16 v[74:77], v[154:157], v[228:231], v[74:77]
	s_setprio 0
	s_setprio 1
	v_mfma_f32_16x16x32_bf16 v[126:129], v[144:147], v[208:211], v[126:129]
	v_mfma_f32_16x16x32_bf16 v[122:125], v[158:161], v[208:211], v[122:125]
	v_mfma_f32_16x16x32_bf16 v[110:113], v[144:147], v[216:219], v[110:113]
	v_mfma_f32_16x16x32_bf16 v[106:109], v[158:161], v[216:219], v[106:109]
	v_mfma_f32_16x16x32_bf16 v[94:97], v[144:147], v[224:227], v[94:97]
	v_mfma_f32_16x16x32_bf16 v[90:93], v[158:161], v[224:227], v[90:93]
	v_mfma_f32_16x16x32_bf16 v[78:81], v[144:147], v[232:235], v[78:81]
	v_mfma_f32_16x16x32_bf16 v[74:77], v[158:161], v[232:235], v[74:77]
	s_setprio 0
	s_setprio 1
	v_mfma_f32_16x16x32_bf16 v[118:121], v[178:181], v[194:197], v[118:121]
	v_mfma_f32_16x16x32_bf16 v[114:117], v[186:189], v[194:197], v[114:117]
	v_mfma_f32_16x16x32_bf16 v[102:105], v[178:181], v[212:215], v[102:105]
	v_mfma_f32_16x16x32_bf16 v[98:101], v[186:189], v[212:215], v[98:101]
	v_mfma_f32_16x16x32_bf16 v[86:89], v[178:181], v[220:223], v[86:89]
	v_mfma_f32_16x16x32_bf16 v[82:85], v[186:189], v[220:223], v[82:85]
	v_mfma_f32_16x16x32_bf16 v[70:73], v[178:181], v[228:231], v[70:73]
	v_mfma_f32_16x16x32_bf16 v[66:69], v[186:189], v[228:231], v[66:69]
	s_setprio 0
	s_setprio 1
	v_mfma_f32_16x16x32_bf16 v[118:121], v[182:185], v[208:211], v[118:121]
	v_mfma_f32_16x16x32_bf16 v[114:117], v[190:193], v[208:211], v[114:117]
	v_mfma_f32_16x16x32_bf16 v[102:105], v[182:185], v[216:219], v[102:105]
	v_mfma_f32_16x16x32_bf16 v[98:101], v[190:193], v[216:219], v[98:101]
	v_mfma_f32_16x16x32_bf16 v[86:89], v[182:185], v[224:227], v[86:89]
	v_mfma_f32_16x16x32_bf16 v[82:85], v[190:193], v[224:227], v[82:85]
	v_mfma_f32_16x16x32_bf16 v[70:73], v[182:185], v[232:235], v[70:73]
	v_mfma_f32_16x16x32_bf16 v[66:69], v[190:193], v[232:235], v[66:69]
	s_setprio 0
	s_barrier
	s_add_i32 s31, s31, s22
	s_mov_b32 m0, s31
	ds_read_b128 v[194:197], v153 offset:16384
	ds_read_b128 v[208:211], v153 offset:17408
	ds_read_b128 v[212:215], v153 offset:18432
	ds_read_b128 v[216:219], v153 offset:19456
	ds_read_b128 v[220:223], v153 offset:20480
	ds_read_b128 v[224:227], v153 offset:21504
	ds_read_b128 v[228:231], v153 offset:22528
	ds_read_b128 v[232:235], v153 offset:23552
	global_load_lds_dwordx4 v64, s[2:3]
	s_add_i32 m0, s31, 0x2000
	s_add_u32 s34, s2, 0x40000
	s_addc_u32 s35, s3, 0
	s_add_i32 s31, s33, s22
	global_load_lds_dwordx4 v130, s[2:3]
	s_mov_b32 m0, s31
	s_mov_b64 s[100:101], s[16:17]
	global_load_lds_dwordx4 v64, s[34:35]
	s_add_i32 m0, s31, 0x2000
	s_nop 0
	global_load_lds_dwordx4 v130, s[34:35]
	s_mov_b32 m0, s23
	s_nop 0
	global_load_lds_dwordx4 v134, s[16:17]
	s_mov_b32 m0, s24
	s_nop 0
	global_load_lds_dwordx4 v132, s[16:17]
	s_waitcnt vmcnt(8)
	s_waitcnt lgkmcnt(0)
	s_setprio 1
	s_barrier
	v_mfma_f32_16x16x32_bf16 v[60:63], v[140:143], v[194:197], v[60:63]
	v_mfma_f32_16x16x32_bf16 v[56:59], v[154:157], v[194:197], v[56:59]
	v_mfma_f32_16x16x32_bf16 v[44:47], v[140:143], v[212:215], v[44:47]
	v_mfma_f32_16x16x32_bf16 v[40:43], v[154:157], v[212:215], v[40:43]
	v_mfma_f32_16x16x32_bf16 v[28:31], v[140:143], v[220:223], v[28:31]
	v_mfma_f32_16x16x32_bf16 v[24:27], v[154:157], v[220:223], v[24:27]
	v_mfma_f32_16x16x32_bf16 v[12:15], v[140:143], v[228:231], v[12:15]
	v_mfma_f32_16x16x32_bf16 v[8:11], v[154:157], v[228:231], v[8:11]
	s_setprio 0
	s_setprio 1
	v_mfma_f32_16x16x32_bf16 v[60:63], v[144:147], v[208:211], v[60:63]
	v_mfma_f32_16x16x32_bf16 v[56:59], v[158:161], v[208:211], v[56:59]
	v_mfma_f32_16x16x32_bf16 v[44:47], v[144:147], v[216:219], v[44:47]
	v_mfma_f32_16x16x32_bf16 v[40:43], v[158:161], v[216:219], v[40:43]
	v_mfma_f32_16x16x32_bf16 v[28:31], v[144:147], v[224:227], v[28:31]
	v_mfma_f32_16x16x32_bf16 v[24:27], v[158:161], v[224:227], v[24:27]
	v_mfma_f32_16x16x32_bf16 v[12:15], v[144:147], v[232:235], v[12:15]
	v_mfma_f32_16x16x32_bf16 v[8:11], v[158:161], v[232:235], v[8:11]
	s_setprio 0
	s_setprio 1
	v_mfma_f32_16x16x32_bf16 v[52:55], v[178:181], v[194:197], v[52:55]
	v_mfma_f32_16x16x32_bf16 v[48:51], v[186:189], v[194:197], v[48:51]
	v_mfma_f32_16x16x32_bf16 v[36:39], v[178:181], v[212:215], v[36:39]
	v_mfma_f32_16x16x32_bf16 v[32:35], v[186:189], v[212:215], v[32:35]
	v_mfma_f32_16x16x32_bf16 v[20:23], v[178:181], v[220:223], v[20:23]
	v_mfma_f32_16x16x32_bf16 v[16:19], v[186:189], v[220:223], v[16:19]
	v_mfma_f32_16x16x32_bf16 v[4:7], v[178:181], v[228:231], v[4:7]
	v_mfma_f32_16x16x32_bf16 v[0:3], v[186:189], v[228:231], v[0:3]
	s_setprio 0
	s_setprio 1
	v_mfma_f32_16x16x32_bf16 v[52:55], v[182:185], v[208:211], v[52:55]
	v_mfma_f32_16x16x32_bf16 v[48:51], v[190:193], v[208:211], v[48:51]
	v_mfma_f32_16x16x32_bf16 v[36:39], v[182:185], v[216:219], v[36:39]
	v_mfma_f32_16x16x32_bf16 v[32:35], v[190:193], v[216:219], v[32:35]
	v_mfma_f32_16x16x32_bf16 v[20:23], v[182:185], v[224:227], v[20:23]
	v_mfma_f32_16x16x32_bf16 v[16:19], v[190:193], v[224:227], v[16:19]
	v_mfma_f32_16x16x32_bf16 v[4:7], v[182:185], v[232:235], v[4:7]
	v_mfma_f32_16x16x32_bf16 v[0:3], v[190:193], v[232:235], v[0:3]
	s_setprio 0
	s_barrier
; #define PG8_STAGE(bufoff, gbase, voff) do { _Pragma("unroll") for (int _i = 0; _i < 2; ++_i) \
;         __builtin_amdgcn_global_load_lds((const unsigned*)((const char*)(gbase) + (voff)[_i]), (PG8_LAS unsigned*)(lds + (bufoff) + ldsw + _i * 8192), 16, 0, 0); } while (0)
; #define PG8_LDA(dst, b, h) do { _Pragma("unroll") for (int m = 0; m < 4; ++m) _Pragma("unroll") for (int k = 0; k < 2; ++k) dst[m][k] = *(const PG8_LAS bf16x8*)(lds + PG8_SA(b, h) + aoff + m * 2048 + k * 1024); } while (0)
; #define PG8_LDB(dst, b, h) do { _Pragma("unroll") for (int n = 0; n < 2; ++n) _Pragma("unroll") for (int k = 0; k < 2; ++k) dst[n][k] = *(const PG8_LAS bf16x8*)(lds + PG8_SB(b, h) + boff + n * 2048 + k * 1024); } while (0)
; #define PG8_MMA(ai, bj, At, Bt) do { __builtin_amdgcn_s_setprio(1); _Pragma("unroll") for (int m = 0; m < 4; ++m) _Pragma("unroll") for (int n = 0; n < 2; ++n) _Pragma("unroll") for (int k = 0; k < 2; ++k) \
;         acc[ai][bj][m][n] = __builtin_amdgcn_mfma_f32_16x16x32_bf16(Bt[n][k], At[m][k], acc[ai][bj][m][n], 0, 0, 0); __builtin_amdgcn_s_setprio(0); } while (0)
; #define PG8_WAIT_V(n) asm volatile("s_waitcnt vmcnt(" #n ")" ::: "memory")
; #define PG8_WAIT_L(n) asm volatile("s_waitcnt lgkmcnt(" #n ")" ::: "memory")
; #define PG8_BAR __builtin_amdgcn_s_barrier()
; #define PG8_SCHED __builtin_amdgcn_sched_barrier(0)
; template <class Epi, class Sched, bool ALIGN_EPI = false, bool SP2 = false>
; __device__ __forceinline__ void gemm_phase(PG8_LAS unsigned char* lds, const Gemm g, const Sched& S, const Epi& E, const int wave0) {
;     ...
;         for (int t = 0; t < nt; t += 2) {
;             const bool last = (t == nt - 2);
;             const char* a1 = cA + (size_t)(t + 1) * kstep;
;             const char* a2 = last ? nA : cA + (size_t)(t + 2) * kstep; const char* b2 = last ? nB : cB + (size_t)(t + 2) * kstep;
;     ...
;             PG8_LDB(B0, 1, 0); PG8_LDB(B1, 1, 1); PG8_SCHED; PG8_LDA(At, 1, 0); PG8_STAGE(PG8_SA(0, 1), a2 + hstepA, voffA);
;             PG8_WAIT_V(8); PG8_WAIT_L(0); PG8_BAR; PG8_MMA(0, 0, At, B0); PG8_MMA(0, 1, At, B1); PG8_BAR; PG8_SCHED;
;             PG8_LDA(At, 1, 1); PG8_STAGE(PG8_SB(1, 0), b3, voffB); PG8_STAGE(PG8_SB(1, 1), b3 + hstepB, voffB); PG8_STAGE(PG8_SA(1, 0), a3, voffA);
;             PG8_WAIT_V(8); PG8_WAIT_L(0); PG8_BAR; PG8_MMA(1, 0, At, B0); PG8_MMA(1, 1, At, B1); PG8_BAR; PG8_SCHED;
	s_add_i32 s31, 0, 0x18000
	s_add_i32 s33, 0, 0x1c000
	ds_read_b128 v[140:143], v254
	ds_read_b128 v[144:147], v254 offset:1024
	ds_read_b128 v[154:157], v254 offset:2048
	ds_read_b128 v[158:161], v254 offset:3072
	ds_read_b128 v[178:181], v255
	ds_read_b128 v[182:185], v255 offset:1024
	ds_read_b128 v[186:189], v255 offset:2048
	ds_read_b128 v[190:193], v255 offset:3072
	s_add_u32 s16, s16, 0x40000
	s_addc_u32 s17, s17, 0
	s_mov_b32 m0, s25
	ds_read_b128 v[194:197], v153 offset:32768
	ds_read_b128 v[208:211], v153 offset:33792
	ds_read_b128 v[212:215], v153 offset:34816
	ds_read_b128 v[216:219], v153 offset:35840
	ds_read_b128 v[220:223], v153 offset:36864
	ds_read_b128 v[224:227], v153 offset:37888
	ds_read_b128 v[228:231], v153 offset:38912
	ds_read_b128 v[232:235], v153 offset:39936
	global_load_lds_dwordx4 v134, s[16:17]
	s_mov_b32 m0, s26
	s_nop 0
	global_load_lds_dwordx4 v132, s[16:17]
	s_waitcnt vmcnt(8)
	s_waitcnt lgkmcnt(0)
	s_setprio 1
	s_barrier
	v_mfma_f32_16x16x32_bf16 v[126:129], v[140:143], v[194:197], v[126:129]
	v_mfma_f32_16x16x32_bf16 v[122:125], v[154:157], v[194:197], v[122:125]
	v_mfma_f32_16x16x32_bf16 v[110:113], v[140:143], v[212:215], v[110:113]
	v_mfma_f32_16x16x32_bf16 v[106:109], v[154:157], v[212:215], v[106:109]
	v_mfma_f32_16x16x32_bf16 v[94:97], v[140:143], v[220:223], v[94:97]
	v_mfma_f32_16x16x32_bf16 v[90:93], v[154:157], v[220:223], v[90:93]
	v_mfma_f32_16x16x32_bf16 v[78:81], v[140:143], v[228:231], v[78:81]
	v_mfma_f32_16x16x32_bf16 v[74:77], v[154:157], v[228:231], v[74:77]
	s_setprio 0
	s_setprio 1
	v_mfma_f32_16x16x32_bf16 v[126:129], v[144:147], v[208:211], v[126:129]
	v_mfma_f32_16x16x32_bf16 v[122:125], v[158:161], v[208:211], v[122:125]
	v_mfma_f32_16x16x32_bf16 v[110:113], v[144:147], v[216:219], v[110:113]
	v_mfma_f32_16x16x32_bf16 v[106:109], v[158:161], v[216:219], v[106:109]
	v_mfma_f32_16x16x32_bf16 v[94:97], v[144:147], v[224:227], v[94:97]
	v_mfma_f32_16x16x32_bf16 v[90:93], v[158:161], v[224:227], v[90:93]
	v_mfma_f32_16x16x32_bf16 v[78:81], v[144:147], v[232:235], v[78:81]
	v_mfma_f32_16x16x32_bf16 v[74:77], v[158:161], v[232:235], v[74:77]
	s_setprio 0
	s_setprio 1
	v_mfma_f32_16x16x32_bf16 v[118:121], v[178:181], v[194:197], v[118:121]
	v_mfma_f32_16x16x32_bf16 v[114:117], v[186:189], v[194:197], v[114:117]
	v_mfma_f32_16x16x32_bf16 v[102:105], v[178:181], v[212:215], v[102:105]
	v_mfma_f32_16x16x32_bf16 v[98:101], v[186:189], v[212:215], v[98:101]
	v_mfma_f32_16x16x32_bf16 v[86:89], v[178:181], v[220:223], v[86:89]
	v_mfma_f32_16x16x32_bf16 v[82:85], v[186:189], v[220:223], v[82:85]
	v_mfma_f32_16x16x32_bf16 v[70:73], v[178:181], v[228:231], v[70:73]
	v_mfma_f32_16x16x32_bf16 v[66:69], v[186:189], v[228:231], v[66:69]
	s_setprio 0
	s_setprio 1
	v_mfma_f32_16x16x32_bf16 v[118:121], v[182:185], v[208:211], v[118:121]
	v_mfma_f32_16x16x32_bf16 v[114:117], v[190:193], v[208:211], v[114:117]
	v_mfma_f32_16x16x32_bf16 v[102:105], v[182:185], v[216:219], v[102:105]
	v_mfma_f32_16x16x32_bf16 v[98:101], v[190:193], v[216:219], v[98:101]
	v_mfma_f32_16x16x32_bf16 v[86:89], v[182:185], v[224:227], v[86:89]
	v_mfma_f32_16x16x32_bf16 v[82:85], v[190:193], v[224:227], v[82:85]
	v_mfma_f32_16x16x32_bf16 v[70:73], v[182:185], v[232:235], v[70:73]
	v_mfma_f32_16x16x32_bf16 v[66:69], v[190:193], v[232:235], v[66:69]
	s_setprio 0
	s_barrier
	s_add_i32 s16, s31, s22
	s_add_u32 s36, s2, 0x80
	s_addc_u32 s37, s3, 0
	s_mov_b32 m0, s16
	ds_read_b128 v[194:197], v153 offset:49152
	ds_read_b128 v[208:211], v153 offset:50176
	ds_read_b128 v[212:215], v153 offset:51200
	ds_read_b128 v[216:219], v153 offset:52224
	ds_read_b128 v[220:223], v153 offset:53248
	ds_read_b128 v[224:227], v153 offset:54272
	ds_read_b128 v[228:231], v153 offset:55296
	ds_read_b128 v[232:235], v153 offset:56320
	global_load_lds_dwordx4 v64, s[36:37]
	s_add_i32 m0, s16, 0x2000
	s_add_u32 s2, s2, 0x40080
	s_addc_u32 s3, s3, 0
	s_add_i32 s16, s33, s22
	global_load_lds_dwordx4 v130, s[36:37]
	s_mov_b32 m0, s16
	s_nop 0
	global_load_lds_dwordx4 v64, s[2:3]
	s_add_i32 m0, s16, 0x2000
	s_nop 0
	global_load_lds_dwordx4 v130, s[2:3]
	s_add_u32 s100, s100, 0x80
	s_addc_u32 s101, s101, 0
	s_mov_b32 m0, s27
	s_nop 0
	global_load_lds_dwordx4 v134, s[100:101]
	s_mov_b32 m0, s28
	s_nop 0
	global_load_lds_dwordx4 v132, s[100:101]
	s_waitcnt vmcnt(8)
	s_waitcnt lgkmcnt(0)
	s_setprio 1
	s_barrier
	v_mfma_f32_16x16x32_bf16 v[60:63], v[140:143], v[194:197], v[60:63]
	v_mfma_f32_16x16x32_bf16 v[56:59], v[154:157], v[194:197], v[56:59]
	v_mfma_f32_16x16x32_bf16 v[44:47], v[140:143], v[212:215], v[44:47]
	v_mfma_f32_16x16x32_bf16 v[40:43], v[154:157], v[212:215], v[40:43]
	v_mfma_f32_16x16x32_bf16 v[28:31], v[140:143], v[220:223], v[28:31]
	v_mfma_f32_16x16x32_bf16 v[24:27], v[154:157], v[220:223], v[24:27]
	v_mfma_f32_16x16x32_bf16 v[12:15], v[140:143], v[228:231], v[12:15]
	v_mfma_f32_16x16x32_bf16 v[8:11], v[154:157], v[228:231], v[8:11]
	s_setprio 0
	s_setprio 1
	v_mfma_f32_16x16x32_bf16 v[60:63], v[144:147], v[208:211], v[60:63]
	v_mfma_f32_16x16x32_bf16 v[56:59], v[158:161], v[208:211], v[56:59]
	v_mfma_f32_16x16x32_bf16 v[44:47], v[144:147], v[216:219], v[44:47]
	v_mfma_f32_16x16x32_bf16 v[40:43], v[158:161], v[216:219], v[40:43]
	v_mfma_f32_16x16x32_bf16 v[28:31], v[144:147], v[224:227], v[28:31]
	v_mfma_f32_16x16x32_bf16 v[24:27], v[158:161], v[224:227], v[24:27]
	v_mfma_f32_16x16x32_bf16 v[12:15], v[144:147], v[232:235], v[12:15]
	v_mfma_f32_16x16x32_bf16 v[8:11], v[158:161], v[232:235], v[8:11]
	s_setprio 0
	s_setprio 1
	v_mfma_f32_16x16x32_bf16 v[52:55], v[178:181], v[194:197], v[52:55]
	v_mfma_f32_16x16x32_bf16 v[48:51], v[186:189], v[194:197], v[48:51]
	v_mfma_f32_16x16x32_bf16 v[36:39], v[178:181], v[212:215], v[36:39]
	v_mfma_f32_16x16x32_bf16 v[32:35], v[186:189], v[212:215], v[32:35]
	v_mfma_f32_16x16x32_bf16 v[20:23], v[178:181], v[220:223], v[20:23]
	v_mfma_f32_16x16x32_bf16 v[16:19], v[186:189], v[220:223], v[16:19]
	v_mfma_f32_16x16x32_bf16 v[4:7], v[178:181], v[228:231], v[4:7]
	v_mfma_f32_16x16x32_bf16 v[0:3], v[186:189], v[228:231], v[0:3]
	s_setprio 0
	s_setprio 1
	v_mfma_f32_16x16x32_bf16 v[52:55], v[182:185], v[208:211], v[52:55]
	v_mfma_f32_16x16x32_bf16 v[48:51], v[190:193], v[208:211], v[48:51]
	v_mfma_f32_16x16x32_bf16 v[36:39], v[182:185], v[216:219], v[36:39]
	v_mfma_f32_16x16x32_bf16 v[32:35], v[190:193], v[216:219], v[32:35]
	v_mfma_f32_16x16x32_bf16 v[20:23], v[182:185], v[224:227], v[20:23]
	v_mfma_f32_16x16x32_bf16 v[16:19], v[190:193], v[224:227], v[16:19]
	v_mfma_f32_16x16x32_bf16 v[4:7], v[182:185], v[232:235], v[4:7]
	v_mfma_f32_16x16x32_bf16 v[0:3], v[190:193], v[232:235], v[0:3]
	s_setprio 0
	s_barrier
	s_add_i32 s19, s19, 2
	s_add_u32 s0, s0, 0x100
	s_addc_u32 s1, s1, 0
	s_add_u32 s13, s13, 0x100
	s_addc_u32 s18, s18, 0
	s_cmp_gt_u32 s19, 13
	s_cbranch_scc0 .LBB0_1231
	s_mov_b64 s[36:37], 0x80
	s_and_b64 vcc, exec, s[6:7]
	s_cbranch_vccz .LBB0_1234
	s_barrier

; #define PG8_STAGE(bufoff, gbase, voff) do { _Pragma("unroll") for (int _i = 0; _i < 2; ++_i) \
;         __builtin_amdgcn_global_load_lds((const unsigned*)((const char*)(gbase) + (voff)[_i]), (PG8_LAS unsigned*)(lds + (bufoff) + ldsw + _i * 8192), 16, 0, 0); } while (0)
; #define PG8_LDA(dst, b, h) do { _Pragma("unroll") for (int m = 0; m < 4; ++m) _Pragma("unroll") for (int k = 0; k < 2; ++k) dst[m][k] = *(const PG8_LAS bf16x8*)(lds + PG8_SA(b, h) + aoff + m * 2048 + k * 1024); } while (0)
; #define PG8_LDB(dst, b, h) do { _Pragma("unroll") for (int n = 0; n < 2; ++n) _Pragma("unroll") for (int k = 0; k < 2; ++k) dst[n][k] = *(const PG8_LAS bf16x8*)(lds + PG8_SB(b, h) + boff + n * 2048 + k * 1024); } while (0)
; #define PG8_MMA(ai, bj, At, Bt) do { __builtin_amdgcn_s_setprio(1); _Pragma("unroll") for (int m = 0; m < 4; ++m) _Pragma("unroll") for (int n = 0; n < 2; ++n) _Pragma("unroll") for (int k = 0; k < 2; ++k) \
;         acc[ai][bj][m][n] = __builtin_amdgcn_mfma_f32_16x16x32_bf16(Bt[n][k], At[m][k], acc[ai][bj][m][n], 0, 0, 0); __builtin_amdgcn_s_setprio(0); } while (0)
; template <class Epi, class Sched, bool ALIGN_EPI = false, bool SP2 = false>
; __device__ __forceinline__ void gemm_phase(PG8_LAS unsigned char* lds, const Gemm g, const Sched& S, const Epi& E, const int wave0) {
;     ...
;         const char* nA = has_next ? (const char*)g.A + (size_t)nxt.z * g.zsA + (size_t)nxt.pm * tstepA + (size_t)nxt.k0 * 2 : cA; const char* nB = has_next ? (const char*)g.Bt + (size_t)nxt.z * g.zsB + (size_t)nxt.pn * tstepB + (size_t)nxt.k0 * 2 : cB;
;         for (int t = 0; t < nt; t += 2) {
;             const bool last = (t == nt - 2);
;             const char* a1 = cA + (size_t)(t + 1) * kstep;
;             const char* a2 = last ? nA : cA + (size_t)(t + 2) * kstep; const char* b2 = last ? nB : cB + (size_t)(t + 2) * kstep;
;     ...
;             PG8_LDB(B0, 0, 0); PG8_LDB(B1, 0, 1); PG8_SCHED; PG8_LDA(At, 0, 0); PG8_STAGE(PG8_SA(1, 1), a1 + hstepA, voffA);
;             PG8_WAIT_V(8); PG8_WAIT_L(0); PG8_BAR; PG8_MMA(0, 0, At, B0); PG8_MMA(0, 1, At, B1); PG8_BAR; PG8_SCHED;
;             PG8_LDA(At, 0, 1); PG8_STAGE(PG8_SB(0, 0), b2, voffB); PG8_STAGE(PG8_SB(0, 1), b2 + hstepB, voffB); PG8_STAGE(PG8_SA(0, 0), a2, voffA);
;             PG8_WAIT_V(8); PG8_WAIT_L(0); PG8_BAR; PG8_MMA(1, 0, At, B0); PG8_MMA(1, 1, At, B1); PG8_BAR; PG8_SCHED;
.LBB0_1341:
	s_add_u32 s16, s0, 0xfff80080
	s_addc_u32 s17, s1, -1
	s_add_i32 s40, 0, 0x10000
	s_cmp_eq_u32 s37, 28
	s_cselect_b32 s19, s11, s17
	s_cselect_b32 s18, s33, s16
	s_cselect_b32 s17, s9, s36
	s_cselect_b32 s16, s34, s35
	s_add_i32 s42, 0, 0x14000
	ds_read_b128 v[144:147], v252
	ds_read_b128 v[148:151], v252 offset:1024
	ds_read_b128 v[152:155], v252 offset:2048
	ds_read_b128 v[156:159], v252 offset:3072
	ds_read_b128 v[178:181], v253
	ds_read_b128 v[182:185], v253 offset:1024
	ds_read_b128 v[186:189], v253 offset:2048
	ds_read_b128 v[190:193], v253 offset:3072
	s_add_i32 m0, s23, 0xc000
	ds_read_b128 v[194:197], v143
	ds_read_b128 v[208:211], v143 offset:1024
	ds_read_b128 v[212:215], v143 offset:2048
	ds_read_b128 v[216:219], v143 offset:3072
	ds_read_b128 v[220:223], v143 offset:4096
	ds_read_b128 v[224:227], v143 offset:5120
	ds_read_b128 v[228:231], v143 offset:6144
	ds_read_b128 v[232:235], v143 offset:7168
	global_load_lds_dwordx4 v136, s[0:1]
	s_add_i32 m0, s23, 0xe000
	s_nop 0
	global_load_lds_dwordx4 v138, s[0:1]
	s_waitcnt vmcnt(8)
	s_waitcnt lgkmcnt(0)
	s_setprio 1
	s_barrier
	v_mfma_f32_16x16x32_bf16 v[126:129], v[144:147], v[194:197], v[126:129]
	v_mfma_f32_16x16x32_bf16 v[122:125], v[152:155], v[194:197], v[122:125]
	v_mfma_f32_16x16x32_bf16 v[118:121], v[144:147], v[212:215], v[118:121]
	v_mfma_f32_16x16x32_bf16 v[114:117], v[152:155], v[212:215], v[114:117]
	v_mfma_f32_16x16x32_bf16 v[102:105], v[144:147], v[220:223], v[102:105]
	v_mfma_f32_16x16x32_bf16 v[98:101], v[152:155], v[220:223], v[98:101]
	v_mfma_f32_16x16x32_bf16 v[86:89], v[144:147], v[228:231], v[86:89]
	v_mfma_f32_16x16x32_bf16 v[82:85], v[152:155], v[228:231], v[82:85]
	s_setprio 0
	s_setprio 1
	v_mfma_f32_16x16x32_bf16 v[126:129], v[148:151], v[208:211], v[126:129]
	v_mfma_f32_16x16x32_bf16 v[122:125], v[156:159], v[208:211], v[122:125]
	v_mfma_f32_16x16x32_bf16 v[118:121], v[148:151], v[216:219], v[118:121]
	v_mfma_f32_16x16x32_bf16 v[114:117], v[156:159], v[216:219], v[114:117]
	v_mfma_f32_16x16x32_bf16 v[102:105], v[148:151], v[224:227], v[102:105]
	v_mfma_f32_16x16x32_bf16 v[98:101], v[156:159], v[224:227], v[98:101]
	v_mfma_f32_16x16x32_bf16 v[86:89], v[148:151], v[232:235], v[86:89]
	v_mfma_f32_16x16x32_bf16 v[82:85], v[156:159], v[232:235], v[82:85]
	s_setprio 0
	s_setprio 1
	v_mfma_f32_16x16x32_bf16 v[110:113], v[178:181], v[194:197], v[110:113]
	v_mfma_f32_16x16x32_bf16 v[106:109], v[186:189], v[194:197], v[106:109]
	v_mfma_f32_16x16x32_bf16 v[94:97], v[178:181], v[212:215], v[94:97]
	v_mfma_f32_16x16x32_bf16 v[90:93], v[186:189], v[212:215], v[90:93]
	v_mfma_f32_16x16x32_bf16 v[78:81], v[178:181], v[220:223], v[78:81]
	v_mfma_f32_16x16x32_bf16 v[74:77], v[186:189], v[220:223], v[74:77]
	v_mfma_f32_16x16x32_bf16 v[70:73], v[178:181], v[228:231], v[70:73]
	v_mfma_f32_16x16x32_bf16 v[66:69], v[186:189], v[228:231], v[66:69]
	s_setprio 0
	s_setprio 1
	v_mfma_f32_16x16x32_bf16 v[110:113], v[182:185], v[208:211], v[110:113]
	v_mfma_f32_16x16x32_bf16 v[106:109], v[190:193], v[208:211], v[106:109]
	v_mfma_f32_16x16x32_bf16 v[94:97], v[182:185], v[216:219], v[94:97]
	v_mfma_f32_16x16x32_bf16 v[90:93], v[190:193], v[216:219], v[90:93]
	v_mfma_f32_16x16x32_bf16 v[78:81], v[182:185], v[224:227], v[78:81]
	v_mfma_f32_16x16x32_bf16 v[74:77], v[190:193], v[224:227], v[74:77]
	v_mfma_f32_16x16x32_bf16 v[70:73], v[182:185], v[232:235], v[70:73]
	v_mfma_f32_16x16x32_bf16 v[66:69], v[190:193], v[232:235], v[66:69]
	s_setprio 0
	s_barrier
	s_add_i32 s40, s40, s22
	s_mov_b32 m0, s40
	ds_read_b128 v[194:197], v143 offset:16384
	ds_read_b128 v[208:211], v143 offset:17408
	ds_read_b128 v[212:215], v143 offset:18432
	ds_read_b128 v[216:219], v143 offset:19456
	ds_read_b128 v[220:223], v143 offset:20480
	ds_read_b128 v[224:227], v143 offset:21504
	ds_read_b128 v[228:231], v143 offset:22528
	ds_read_b128 v[232:235], v143 offset:23552
	global_load_lds_dwordx4 v64, s[16:17]
	s_add_i32 m0, s40, 0x2000
	s_add_u32 s40, s16, 0x80000
	s_addc_u32 s41, s17, 0
	s_add_i32 s42, s42, s22
	global_load_lds_dwordx4 v130, s[16:17]
	s_mov_b32 m0, s42
	s_mov_b64 s[100:101], s[18:19]
	global_load_lds_dwordx4 v64, s[40:41]
	s_add_i32 m0, s42, 0x2000
	s_nop 0
	global_load_lds_dwordx4 v130, s[40:41]
	s_mov_b32 m0, s23
	s_nop 0
	global_load_lds_dwordx4 v134, s[18:19]
	s_mov_b32 m0, s24
	s_nop 0
	global_load_lds_dwordx4 v132, s[18:19]
	s_waitcnt vmcnt(8)
	s_waitcnt lgkmcnt(0)
	s_setprio 1
	s_barrier
	v_mfma_f32_16x16x32_bf16 v[60:63], v[144:147], v[194:197], v[60:63]
	v_mfma_f32_16x16x32_bf16 v[56:59], v[152:155], v[194:197], v[56:59]
	v_mfma_f32_16x16x32_bf16 v[52:55], v[144:147], v[212:215], v[52:55]
	v_mfma_f32_16x16x32_bf16 v[48:51], v[152:155], v[212:215], v[48:51]
	v_mfma_f32_16x16x32_bf16 v[36:39], v[144:147], v[220:223], v[36:39]
	v_mfma_f32_16x16x32_bf16 v[32:35], v[152:155], v[220:223], v[32:35]
	v_mfma_f32_16x16x32_bf16 v[20:23], v[144:147], v[228:231], v[20:23]
	v_mfma_f32_16x16x32_bf16 v[16:19], v[152:155], v[228:231], v[16:19]
	s_setprio 0
	s_setprio 1
	v_mfma_f32_16x16x32_bf16 v[60:63], v[148:151], v[208:211], v[60:63]
	v_mfma_f32_16x16x32_bf16 v[56:59], v[156:159], v[208:211], v[56:59]
	v_mfma_f32_16x16x32_bf16 v[52:55], v[148:151], v[216:219], v[52:55]
	v_mfma_f32_16x16x32_bf16 v[48:51], v[156:159], v[216:219], v[48:51]
	v_mfma_f32_16x16x32_bf16 v[36:39], v[148:151], v[224:227], v[36:39]
	v_mfma_f32_16x16x32_bf16 v[32:35], v[156:159], v[224:227], v[32:35]
	v_mfma_f32_16x16x32_bf16 v[20:23], v[148:151], v[232:235], v[20:23]
	v_mfma_f32_16x16x32_bf16 v[16:19], v[156:159], v[232:235], v[16:19]
	s_setprio 0
	s_setprio 1
	v_mfma_f32_16x16x32_bf16 v[44:47], v[178:181], v[194:197], v[44:47]
	v_mfma_f32_16x16x32_bf16 v[40:43], v[186:189], v[194:197], v[40:43]
	v_mfma_f32_16x16x32_bf16 v[28:31], v[178:181], v[212:215], v[28:31]
	v_mfma_f32_16x16x32_bf16 v[24:27], v[186:189], v[212:215], v[24:27]
	v_mfma_f32_16x16x32_bf16 v[12:15], v[178:181], v[220:223], v[12:15]
	v_mfma_f32_16x16x32_bf16 v[8:11], v[186:189], v[220:223], v[8:11]
	v_mfma_f32_16x16x32_bf16 v[4:7], v[178:181], v[228:231], v[4:7]
	v_mfma_f32_16x16x32_bf16 v[0:3], v[186:189], v[228:231], v[0:3]
	s_setprio 0
	s_setprio 1
	v_mfma_f32_16x16x32_bf16 v[44:47], v[182:185], v[208:211], v[44:47]
	v_mfma_f32_16x16x32_bf16 v[40:43], v[190:193], v[208:211], v[40:43]
	v_mfma_f32_16x16x32_bf16 v[28:31], v[182:185], v[216:219], v[28:31]
	v_mfma_f32_16x16x32_bf16 v[24:27], v[190:193], v[216:219], v[24:27]
	v_mfma_f32_16x16x32_bf16 v[12:15], v[182:185], v[224:227], v[12:15]
	v_mfma_f32_16x16x32_bf16 v[8:11], v[190:193], v[224:227], v[8:11]
	v_mfma_f32_16x16x32_bf16 v[4:7], v[182:185], v[232:235], v[4:7]
	v_mfma_f32_16x16x32_bf16 v[0:3], v[190:193], v[232:235], v[0:3]
	s_setprio 0
	s_barrier
; #define PG8_STAGE(bufoff, gbase, voff) do { _Pragma("unroll") for (int _i = 0; _i < 2; ++_i) \
;         __builtin_amdgcn_global_load_lds((const unsigned*)((const char*)(gbase) + (voff)[_i]), (PG8_LAS unsigned*)(lds + (bufoff) + ldsw + _i * 8192), 16, 0, 0); } while (0)
; #define PG8_LDA(dst, b, h) do { _Pragma("unroll") for (int m = 0; m < 4; ++m) _Pragma("unroll") for (int k = 0; k < 2; ++k) dst[m][k] = *(const PG8_LAS bf16x8*)(lds + PG8_SA(b, h) + aoff + m * 2048 + k * 1024); } while (0)
; #define PG8_LDB(dst, b, h) do { _Pragma("unroll") for (int n = 0; n < 2; ++n) _Pragma("unroll") for (int k = 0; k < 2; ++k) dst[n][k] = *(const PG8_LAS bf16x8*)(lds + PG8_SB(b, h) + boff + n * 2048 + k * 1024); } while (0)
; #define PG8_MMA(ai, bj, At, Bt) do { __builtin_amdgcn_s_setprio(1); _Pragma("unroll") for (int m = 0; m < 4; ++m) _Pragma("unroll") for (int n = 0; n < 2; ++n) _Pragma("unroll") for (int k = 0; k < 2; ++k) \
;         acc[ai][bj][m][n] = __builtin_amdgcn_mfma_f32_16x16x32_bf16(Bt[n][k], At[m][k], acc[ai][bj][m][n], 0, 0, 0); __builtin_amdgcn_s_setprio(0); } while (0)
; #define PG8_WAIT_V(n) asm volatile("s_waitcnt vmcnt(" #n ")" ::: "memory")
; #define PG8_WAIT_L(n) asm volatile("s_waitcnt lgkmcnt(" #n ")" ::: "memory")
; #define PG8_BAR __builtin_amdgcn_s_barrier()
; #define PG8_SCHED __builtin_amdgcn_sched_barrier(0)
; template <class Epi, class Sched, bool ALIGN_EPI = false, bool SP2 = false>
; __device__ __forceinline__ void gemm_phase(PG8_LAS unsigned char* lds, const Gemm g, const Sched& S, const Epi& E, const int wave0) {
;     ...
;         for (int t = 0; t < nt; t += 2) {
;             const bool last = (t == nt - 2);
;             const char* a1 = cA + (size_t)(t + 1) * kstep;
;             const char* a2 = last ? nA : cA + (size_t)(t + 2) * kstep; const char* b2 = last ? nB : cB + (size_t)(t + 2) * kstep;
;     ...
;             PG8_LDB(B0, 1, 0); PG8_LDB(B1, 1, 1); PG8_SCHED; PG8_LDA(At, 1, 0); PG8_STAGE(PG8_SA(0, 1), a2 + hstepA, voffA);
;             PG8_WAIT_V(8); PG8_WAIT_L(0); PG8_BAR; PG8_MMA(0, 0, At, B0); PG8_MMA(0, 1, At, B1); PG8_BAR; PG8_SCHED;
;             PG8_LDA(At, 1, 1); PG8_STAGE(PG8_SB(1, 0), b3, voffB); PG8_STAGE(PG8_SB(1, 1), b3 + hstepB, voffB); PG8_STAGE(PG8_SA(1, 0), a3, voffA);
;             PG8_WAIT_V(8); PG8_WAIT_L(0); PG8_BAR; PG8_MMA(1, 0, At, B0); PG8_MMA(1, 1, At, B1); PG8_BAR; PG8_SCHED;
	s_add_i32 s40, 0, 0x18000
	s_add_i32 s41, 0, 0x1c000
	ds_read_b128 v[144:147], v254
	ds_read_b128 v[148:151], v254 offset:1024
	ds_read_b128 v[152:155], v254 offset:2048
	ds_read_b128 v[156:159], v254 offset:3072
	ds_read_b128 v[178:181], v255
	ds_read_b128 v[182:185], v255 offset:1024
	ds_read_b128 v[186:189], v255 offset:2048
	ds_read_b128 v[190:193], v255 offset:3072
	s_add_u32 s18, s18, 0x80000
	s_addc_u32 s19, s19, 0
	s_mov_b32 m0, s25
	ds_read_b128 v[194:197], v143 offset:32768
	ds_read_b128 v[208:211], v143 offset:33792
	ds_read_b128 v[212:215], v143 offset:34816
	ds_read_b128 v[216:219], v143 offset:35840
	ds_read_b128 v[220:223], v143 offset:36864
	ds_read_b128 v[224:227], v143 offset:37888
	ds_read_b128 v[228:231], v143 offset:38912
	ds_read_b128 v[232:235], v143 offset:39936
	global_load_lds_dwordx4 v134, s[18:19]
	s_mov_b32 m0, s26
	s_nop 0
	global_load_lds_dwordx4 v132, s[18:19]
	s_waitcnt vmcnt(8)
	s_waitcnt lgkmcnt(0)
	s_setprio 1
	s_barrier
	v_mfma_f32_16x16x32_bf16 v[126:129], v[144:147], v[194:197], v[126:129]
	v_mfma_f32_16x16x32_bf16 v[122:125], v[152:155], v[194:197], v[122:125]
	v_mfma_f32_16x16x32_bf16 v[118:121], v[144:147], v[212:215], v[118:121]
	v_mfma_f32_16x16x32_bf16 v[114:117], v[152:155], v[212:215], v[114:117]
	v_mfma_f32_16x16x32_bf16 v[102:105], v[144:147], v[220:223], v[102:105]
	v_mfma_f32_16x16x32_bf16 v[98:101], v[152:155], v[220:223], v[98:101]
	v_mfma_f32_16x16x32_bf16 v[86:89], v[144:147], v[228:231], v[86:89]
	v_mfma_f32_16x16x32_bf16 v[82:85], v[152:155], v[228:231], v[82:85]
	s_setprio 0
	s_setprio 1
	v_mfma_f32_16x16x32_bf16 v[126:129], v[148:151], v[208:211], v[126:129]
	v_mfma_f32_16x16x32_bf16 v[122:125], v[156:159], v[208:211], v[122:125]
	v_mfma_f32_16x16x32_bf16 v[118:121], v[148:151], v[216:219], v[118:121]
	v_mfma_f32_16x16x32_bf16 v[114:117], v[156:159], v[216:219], v[114:117]
	v_mfma_f32_16x16x32_bf16 v[102:105], v[148:151], v[224:227], v[102:105]
	v_mfma_f32_16x16x32_bf16 v[98:101], v[156:159], v[224:227], v[98:101]
	v_mfma_f32_16x16x32_bf16 v[86:89], v[148:151], v[232:235], v[86:89]
	v_mfma_f32_16x16x32_bf16 v[82:85], v[156:159], v[232:235], v[82:85]
	s_setprio 0
	s_setprio 1
	v_mfma_f32_16x16x32_bf16 v[110:113], v[178:181], v[194:197], v[110:113]
	v_mfma_f32_16x16x32_bf16 v[106:109], v[186:189], v[194:197], v[106:109]
	v_mfma_f32_16x16x32_bf16 v[94:97], v[178:181], v[212:215], v[94:97]
	v_mfma_f32_16x16x32_bf16 v[90:93], v[186:189], v[212:215], v[90:93]
	v_mfma_f32_16x16x32_bf16 v[78:81], v[178:181], v[220:223], v[78:81]
	v_mfma_f32_16x16x32_bf16 v[74:77], v[186:189], v[220:223], v[74:77]
	v_mfma_f32_16x16x32_bf16 v[70:73], v[178:181], v[228:231], v[70:73]
	v_mfma_f32_16x16x32_bf16 v[66:69], v[186:189], v[228:231], v[66:69]
	s_setprio 0
	s_setprio 1
	v_mfma_f32_16x16x32_bf16 v[110:113], v[182:185], v[208:211], v[110:113]
	v_mfma_f32_16x16x32_bf16 v[106:109], v[190:193], v[208:211], v[106:109]
	v_mfma_f32_16x16x32_bf16 v[94:97], v[182:185], v[216:219], v[94:97]
	v_mfma_f32_16x16x32_bf16 v[90:93], v[190:193], v[216:219], v[90:93]
	v_mfma_f32_16x16x32_bf16 v[78:81], v[182:185], v[224:227], v[78:81]
	v_mfma_f32_16x16x32_bf16 v[74:77], v[190:193], v[224:227], v[74:77]
	v_mfma_f32_16x16x32_bf16 v[70:73], v[182:185], v[232:235], v[70:73]
	v_mfma_f32_16x16x32_bf16 v[66:69], v[190:193], v[232:235], v[66:69]
	s_setprio 0
	s_barrier
	s_add_i32 s18, s40, s22
	s_add_u32 s44, s16, 0x80
	s_addc_u32 s45, s17, 0
	s_mov_b32 m0, s18
	ds_read_b128 v[194:197], v143 offset:49152
	ds_read_b128 v[208:211], v143 offset:50176
	ds_read_b128 v[212:215], v143 offset:51200
	ds_read_b128 v[216:219], v143 offset:52224
	ds_read_b128 v[220:223], v143 offset:53248
	ds_read_b128 v[224:227], v143 offset:54272
	ds_read_b128 v[228:231], v143 offset:55296
	ds_read_b128 v[232:235], v143 offset:56320
	global_load_lds_dwordx4 v64, s[44:45]
	s_add_i32 m0, s18, 0x2000
	s_add_u32 s16, s16, 0x80080
	s_addc_u32 s17, s17, 0
	s_add_i32 s18, s41, s22
	global_load_lds_dwordx4 v130, s[44:45]
	s_mov_b32 m0, s18
	s_nop 0
	global_load_lds_dwordx4 v64, s[16:17]
	s_add_i32 m0, s18, 0x2000
	s_nop 0
	global_load_lds_dwordx4 v130, s[16:17]
	s_add_u32 s100, s100, 0x80
	s_addc_u32 s101, s101, 0
	s_mov_b32 m0, s27
	s_nop 0
	global_load_lds_dwordx4 v134, s[100:101]
	s_mov_b32 m0, s28
	s_nop 0
	global_load_lds_dwordx4 v132, s[100:101]
	s_waitcnt vmcnt(8)
	s_waitcnt lgkmcnt(0)
	s_setprio 1
	s_barrier
	v_mfma_f32_16x16x32_bf16 v[60:63], v[144:147], v[194:197], v[60:63]
	v_mfma_f32_16x16x32_bf16 v[56:59], v[152:155], v[194:197], v[56:59]
	v_mfma_f32_16x16x32_bf16 v[52:55], v[144:147], v[212:215], v[52:55]
	v_mfma_f32_16x16x32_bf16 v[48:51], v[152:155], v[212:215], v[48:51]
	v_mfma_f32_16x16x32_bf16 v[36:39], v[144:147], v[220:223], v[36:39]
	v_mfma_f32_16x16x32_bf16 v[32:35], v[152:155], v[220:223], v[32:35]
	v_mfma_f32_16x16x32_bf16 v[20:23], v[144:147], v[228:231], v[20:23]
	v_mfma_f32_16x16x32_bf16 v[16:19], v[152:155], v[228:231], v[16:19]
	s_setprio 0
	s_setprio 1
	v_mfma_f32_16x16x32_bf16 v[60:63], v[148:151], v[208:211], v[60:63]
	v_mfma_f32_16x16x32_bf16 v[56:59], v[156:159], v[208:211], v[56:59]
	v_mfma_f32_16x16x32_bf16 v[52:55], v[148:151], v[216:219], v[52:55]
	v_mfma_f32_16x16x32_bf16 v[48:51], v[156:159], v[216:219], v[48:51]
	v_mfma_f32_16x16x32_bf16 v[36:39], v[148:151], v[224:227], v[36:39]
	v_mfma_f32_16x16x32_bf16 v[32:35], v[156:159], v[224:227], v[32:35]
	v_mfma_f32_16x16x32_bf16 v[20:23], v[148:151], v[232:235], v[20:23]
	v_mfma_f32_16x16x32_bf16 v[16:19], v[156:159], v[232:235], v[16:19]
	s_setprio 0
	s_setprio 1
	v_mfma_f32_16x16x32_bf16 v[44:47], v[178:181], v[194:197], v[44:47]
	v_mfma_f32_16x16x32_bf16 v[40:43], v[186:189], v[194:197], v[40:43]
	v_mfma_f32_16x16x32_bf16 v[28:31], v[178:181], v[212:215], v[28:31]
	v_mfma_f32_16x16x32_bf16 v[24:27], v[186:189], v[212:215], v[24:27]
	v_mfma_f32_16x16x32_bf16 v[12:15], v[178:181], v[220:223], v[12:15]
	v_mfma_f32_16x16x32_bf16 v[8:11], v[186:189], v[220:223], v[8:11]
	v_mfma_f32_16x16x32_bf16 v[4:7], v[178:181], v[228:231], v[4:7]
	v_mfma_f32_16x16x32_bf16 v[0:3], v[186:189], v[228:231], v[0:3]
	s_setprio 0
	s_setprio 1
	v_mfma_f32_16x16x32_bf16 v[44:47], v[182:185], v[208:211], v[44:47]
	v_mfma_f32_16x16x32_bf16 v[40:43], v[190:193], v[208:211], v[40:43]
	v_mfma_f32_16x16x32_bf16 v[28:31], v[182:185], v[216:219], v[28:31]
	v_mfma_f32_16x16x32_bf16 v[24:27], v[190:193], v[216:219], v[24:27]
	v_mfma_f32_16x16x32_bf16 v[12:15], v[182:185], v[224:227], v[12:15]
	v_mfma_f32_16x16x32_bf16 v[8:11], v[190:193], v[224:227], v[8:11]
	v_mfma_f32_16x16x32_bf16 v[4:7], v[182:185], v[232:235], v[4:7]
	v_mfma_f32_16x16x32_bf16 v[0:3], v[190:193], v[232:235], v[0:3]
	s_setprio 0
	s_barrier
	s_add_i32 s37, s37, 2
	s_add_u32 s0, s0, 0x100
	s_addc_u32 s1, s1, 0
	s_add_u32 s35, s35, 0x100
	s_addc_u32 s36, s36, 0
	s_cmp_gt_u32 s37, 29
	s_cbranch_scc0 .LBB0_1341
	s_mov_b64 s[44:45], 0x80
	s_and_b64 vcc, exec, s[6:7]
	s_mov_b64 s[34:35], 0x45000
	s_cbranch_vccz .LBB0_1344
	s_barrier

; #define PG8_STAGE(bufoff, gbase, voff) do { _Pragma("unroll") for (int _i = 0; _i < 2; ++_i) \
;         __builtin_amdgcn_global_load_lds((const unsigned*)((const char*)(gbase) + (voff)[_i]), (PG8_LAS unsigned*)(lds + (bufoff) + ldsw + _i * 8192), 16, 0, 0); } while (0)
; #define PG8_LDA(dst, b, h) do { _Pragma("unroll") for (int m = 0; m < 4; ++m) _Pragma("unroll") for (int k = 0; k < 2; ++k) dst[m][k] = *(const PG8_LAS bf16x8*)(lds + PG8_SA(b, h) + aoff + m * 2048 + k * 1024); } while (0)
; #define PG8_LDB(dst, b, h) do { _Pragma("unroll") for (int n = 0; n < 2; ++n) _Pragma("unroll") for (int k = 0; k < 2; ++k) dst[n][k] = *(const PG8_LAS bf16x8*)(lds + PG8_SB(b, h) + boff + n * 2048 + k * 1024); } while (0)
; #define PG8_MMA(ai, bj, At, Bt) do { __builtin_amdgcn_s_setprio(1); _Pragma("unroll") for (int m = 0; m < 4; ++m) _Pragma("unroll") for (int n = 0; n < 2; ++n) _Pragma("unroll") for (int k = 0; k < 2; ++k) \
;         acc[ai][bj][m][n] = __builtin_amdgcn_mfma_f32_16x16x32_bf16(Bt[n][k], At[m][k], acc[ai][bj][m][n], 0, 0, 0); __builtin_amdgcn_s_setprio(0); } while (0)
; template <class Epi, class Sched, bool ALIGN_EPI = false, bool SP2 = false>
; __device__ __forceinline__ void gemm_phase(PG8_LAS unsigned char* lds, const Gemm g, const Sched& S, const Epi& E, const int wave0) {
;     ...
;         const char* nA = has_next ? (const char*)g.A + (size_t)nxt.z * g.zsA + (size_t)nxt.pm * tstepA + (size_t)nxt.k0 * 2 : cA; const char* nB = has_next ? (const char*)g.Bt + (size_t)nxt.z * g.zsB + (size_t)nxt.pn * tstepB + (size_t)nxt.k0 * 2 : cB;
;         for (int t = 0; t < nt; t += 2) {
;             const bool last = (t == nt - 2);
;             const char* a1 = cA + (size_t)(t + 1) * kstep;
;             const char* a2 = last ? nA : cA + (size_t)(t + 2) * kstep; const char* b2 = last ? nB : cB + (size_t)(t + 2) * kstep;
;     ...
;             PG8_LDB(B0, 0, 0); PG8_LDB(B1, 0, 1); PG8_SCHED; PG8_LDA(At, 0, 0); PG8_STAGE(PG8_SA(1, 1), a1 + hstepA, voffA);
;             PG8_WAIT_V(8); PG8_WAIT_L(0); PG8_BAR; PG8_MMA(0, 0, At, B0); PG8_MMA(0, 1, At, B1); PG8_BAR; PG8_SCHED;
;             PG8_LDA(At, 0, 1); PG8_STAGE(PG8_SB(0, 0), b2, voffB); PG8_STAGE(PG8_SB(0, 1), b2 + hstepB, voffB); PG8_STAGE(PG8_SA(0, 0), a2, voffA);
;             PG8_WAIT_V(8); PG8_WAIT_L(0); PG8_BAR; PG8_MMA(1, 0, At, B0); PG8_MMA(1, 1, At, B1); PG8_BAR; PG8_SCHED;
.LBB0_1360:
	s_add_u32 s16, s0, 0xfff80080
	s_addc_u32 s17, s1, -1
	s_add_i32 s42, 0, 0x10000
	s_cmp_eq_u32 s41, 12
	s_cselect_b32 s19, s5, s17
	s_cselect_b32 s18, s4, s16
	s_cselect_b32 s17, s11, s27
	s_cselect_b32 s16, s13, s15
	s_add_i32 s44, 0, 0x14000
	ds_read_b128 v[144:147], v252
	ds_read_b128 v[148:151], v252 offset:1024
	ds_read_b128 v[152:155], v252 offset:2048
	ds_read_b128 v[156:159], v252 offset:3072
	ds_read_b128 v[178:181], v253
	ds_read_b128 v[182:185], v253 offset:1024
	ds_read_b128 v[186:189], v253 offset:2048
	ds_read_b128 v[190:193], v253 offset:3072
	s_add_i32 m0, s23, 0xc000
	ds_read_b128 v[194:197], v143
	ds_read_b128 v[208:211], v143 offset:1024
	ds_read_b128 v[212:215], v143 offset:2048
	ds_read_b128 v[216:219], v143 offset:3072
	ds_read_b128 v[220:223], v143 offset:4096
	ds_read_b128 v[224:227], v143 offset:5120
	ds_read_b128 v[228:231], v143 offset:6144
	ds_read_b128 v[232:235], v143 offset:7168
	global_load_lds_dwordx4 v136, s[0:1]
	s_add_i32 m0, s23, 0xe000
	s_nop 0
	global_load_lds_dwordx4 v138, s[0:1]
	s_waitcnt vmcnt(8)
	s_waitcnt lgkmcnt(0)
	s_setprio 1
	s_barrier
	v_mfma_f32_16x16x32_bf16 v[126:129], v[144:147], v[194:197], v[126:129]
	v_mfma_f32_16x16x32_bf16 v[122:125], v[152:155], v[194:197], v[122:125]
	v_mfma_f32_16x16x32_bf16 v[118:121], v[144:147], v[212:215], v[118:121]
	v_mfma_f32_16x16x32_bf16 v[114:117], v[152:155], v[212:215], v[114:117]
	v_mfma_f32_16x16x32_bf16 v[102:105], v[144:147], v[220:223], v[102:105]
	v_mfma_f32_16x16x32_bf16 v[98:101], v[152:155], v[220:223], v[98:101]
	v_mfma_f32_16x16x32_bf16 v[86:89], v[144:147], v[228:231], v[86:89]
	v_mfma_f32_16x16x32_bf16 v[82:85], v[152:155], v[228:231], v[82:85]
	s_setprio 0
	s_setprio 1
	v_mfma_f32_16x16x32_bf16 v[126:129], v[148:151], v[208:211], v[126:129]
	v_mfma_f32_16x16x32_bf16 v[122:125], v[156:159], v[208:211], v[122:125]
	v_mfma_f32_16x16x32_bf16 v[118:121], v[148:151], v[216:219], v[118:121]
	v_mfma_f32_16x16x32_bf16 v[114:117], v[156:159], v[216:219], v[114:117]
	v_mfma_f32_16x16x32_bf16 v[102:105], v[148:151], v[224:227], v[102:105]
	v_mfma_f32_16x16x32_bf16 v[98:101], v[156:159], v[224:227], v[98:101]
	v_mfma_f32_16x16x32_bf16 v[86:89], v[148:151], v[232:235], v[86:89]
	v_mfma_f32_16x16x32_bf16 v[82:85], v[156:159], v[232:235], v[82:85]
	s_setprio 0
	s_setprio 1
	v_mfma_f32_16x16x32_bf16 v[110:113], v[178:181], v[194:197], v[110:113]
	v_mfma_f32_16x16x32_bf16 v[106:109], v[186:189], v[194:197], v[106:109]
	v_mfma_f32_16x16x32_bf16 v[94:97], v[178:181], v[212:215], v[94:97]
	v_mfma_f32_16x16x32_bf16 v[90:93], v[186:189], v[212:215], v[90:93]
	v_mfma_f32_16x16x32_bf16 v[78:81], v[178:181], v[220:223], v[78:81]
	v_mfma_f32_16x16x32_bf16 v[74:77], v[186:189], v[220:223], v[74:77]
	v_mfma_f32_16x16x32_bf16 v[70:73], v[178:181], v[228:231], v[70:73]
	v_mfma_f32_16x16x32_bf16 v[66:69], v[186:189], v[228:231], v[66:69]
	s_setprio 0
	s_setprio 1
	v_mfma_f32_16x16x32_bf16 v[110:113], v[182:185], v[208:211], v[110:113]
	v_mfma_f32_16x16x32_bf16 v[106:109], v[190:193], v[208:211], v[106:109]
	v_mfma_f32_16x16x32_bf16 v[94:97], v[182:185], v[216:219], v[94:97]
	v_mfma_f32_16x16x32_bf16 v[90:93], v[190:193], v[216:219], v[90:93]
	v_mfma_f32_16x16x32_bf16 v[78:81], v[182:185], v[224:227], v[78:81]
	v_mfma_f32_16x16x32_bf16 v[74:77], v[190:193], v[224:227], v[74:77]
	v_mfma_f32_16x16x32_bf16 v[70:73], v[182:185], v[232:235], v[70:73]
	v_mfma_f32_16x16x32_bf16 v[66:69], v[190:193], v[232:235], v[66:69]
	s_setprio 0
	s_barrier
	s_add_i32 s42, s42, s22
	s_mov_b32 m0, s42
	ds_read_b128 v[194:197], v143 offset:16384
	ds_read_b128 v[208:211], v143 offset:17408
	ds_read_b128 v[212:215], v143 offset:18432
	ds_read_b128 v[216:219], v143 offset:19456
	ds_read_b128 v[220:223], v143 offset:20480
	ds_read_b128 v[224:227], v143 offset:21504
	ds_read_b128 v[228:231], v143 offset:22528
	ds_read_b128 v[232:235], v143 offset:23552
	global_load_lds_dwordx4 v64, s[16:17]
	s_add_i32 m0, s42, 0x2000
	s_add_u32 s42, s16, 0x80000
	s_addc_u32 s43, s17, 0
	s_add_i32 s44, s44, s22
	global_load_lds_dwordx4 v130, s[16:17]
	s_mov_b32 m0, s44
	s_mov_b64 s[100:101], s[18:19]
	global_load_lds_dwordx4 v64, s[42:43]
	s_add_i32 m0, s44, 0x2000
	s_nop 0
	global_load_lds_dwordx4 v130, s[42:43]
	s_mov_b32 m0, s23
	s_nop 0
	global_load_lds_dwordx4 v134, s[18:19]
	s_mov_b32 m0, s24
	s_nop 0
	global_load_lds_dwordx4 v132, s[18:19]
	s_waitcnt vmcnt(8)
	s_waitcnt lgkmcnt(0)
	s_setprio 1
	s_barrier
	v_mfma_f32_16x16x32_bf16 v[60:63], v[144:147], v[194:197], v[60:63]
	v_mfma_f32_16x16x32_bf16 v[56:59], v[152:155], v[194:197], v[56:59]
	v_mfma_f32_16x16x32_bf16 v[52:55], v[144:147], v[212:215], v[52:55]
	v_mfma_f32_16x16x32_bf16 v[48:51], v[152:155], v[212:215], v[48:51]
	v_mfma_f32_16x16x32_bf16 v[36:39], v[144:147], v[220:223], v[36:39]
	v_mfma_f32_16x16x32_bf16 v[32:35], v[152:155], v[220:223], v[32:35]
	v_mfma_f32_16x16x32_bf16 v[20:23], v[144:147], v[228:231], v[20:23]
	v_mfma_f32_16x16x32_bf16 v[16:19], v[152:155], v[228:231], v[16:19]
	s_setprio 0
	s_setprio 1
	v_mfma_f32_16x16x32_bf16 v[60:63], v[148:151], v[208:211], v[60:63]
	v_mfma_f32_16x16x32_bf16 v[56:59], v[156:159], v[208:211], v[56:59]
	v_mfma_f32_16x16x32_bf16 v[52:55], v[148:151], v[216:219], v[52:55]
	v_mfma_f32_16x16x32_bf16 v[48:51], v[156:159], v[216:219], v[48:51]
	v_mfma_f32_16x16x32_bf16 v[36:39], v[148:151], v[224:227], v[36:39]
	v_mfma_f32_16x16x32_bf16 v[32:35], v[156:159], v[224:227], v[32:35]
	v_mfma_f32_16x16x32_bf16 v[20:23], v[148:151], v[232:235], v[20:23]
	v_mfma_f32_16x16x32_bf16 v[16:19], v[156:159], v[232:235], v[16:19]
	s_setprio 0
	s_setprio 1
	v_mfma_f32_16x16x32_bf16 v[44:47], v[178:181], v[194:197], v[44:47]
	v_mfma_f32_16x16x32_bf16 v[40:43], v[186:189], v[194:197], v[40:43]
	v_mfma_f32_16x16x32_bf16 v[28:31], v[178:181], v[212:215], v[28:31]
	v_mfma_f32_16x16x32_bf16 v[24:27], v[186:189], v[212:215], v[24:27]
	v_mfma_f32_16x16x32_bf16 v[12:15], v[178:181], v[220:223], v[12:15]
	v_mfma_f32_16x16x32_bf16 v[8:11], v[186:189], v[220:223], v[8:11]
	v_mfma_f32_16x16x32_bf16 v[4:7], v[178:181], v[228:231], v[4:7]
	v_mfma_f32_16x16x32_bf16 v[0:3], v[186:189], v[228:231], v[0:3]
	s_setprio 0
	s_setprio 1
	v_mfma_f32_16x16x32_bf16 v[44:47], v[182:185], v[208:211], v[44:47]
	v_mfma_f32_16x16x32_bf16 v[40:43], v[190:193], v[208:211], v[40:43]
	v_mfma_f32_16x16x32_bf16 v[28:31], v[182:185], v[216:219], v[28:31]
	v_mfma_f32_16x16x32_bf16 v[24:27], v[190:193], v[216:219], v[24:27]
	v_mfma_f32_16x16x32_bf16 v[12:15], v[182:185], v[224:227], v[12:15]
	v_mfma_f32_16x16x32_bf16 v[8:11], v[190:193], v[224:227], v[8:11]
	v_mfma_f32_16x16x32_bf16 v[4:7], v[182:185], v[232:235], v[4:7]
	v_mfma_f32_16x16x32_bf16 v[0:3], v[190:193], v[232:235], v[0:3]
	s_setprio 0
	s_barrier
; #define PG8_STAGE(bufoff, gbase, voff) do { _Pragma("unroll") for (int _i = 0; _i < 2; ++_i) \
;         __builtin_amdgcn_global_load_lds((const unsigned*)((const char*)(gbase) + (voff)[_i]), (PG8_LAS unsigned*)(lds + (bufoff) + ldsw + _i * 8192), 16, 0, 0); } while (0)
; #define PG8_LDA(dst, b, h) do { _Pragma("unroll") for (int m = 0; m < 4; ++m) _Pragma("unroll") for (int k = 0; k < 2; ++k) dst[m][k] = *(const PG8_LAS bf16x8*)(lds + PG8_SA(b, h) + aoff + m * 2048 + k * 1024); } while (0)
; #define PG8_LDB(dst, b, h) do { _Pragma("unroll") for (int n = 0; n < 2; ++n) _Pragma("unroll") for (int k = 0; k < 2; ++k) dst[n][k] = *(const PG8_LAS bf16x8*)(lds + PG8_SB(b, h) + boff + n * 2048 + k * 1024); } while (0)
; #define PG8_MMA(ai, bj, At, Bt) do { __builtin_amdgcn_s_setprio(1); _Pragma("unroll") for (int m = 0; m < 4; ++m) _Pragma("unroll") for (int n = 0; n < 2; ++n) _Pragma("unroll") for (int k = 0; k < 2; ++k) \
;         acc[ai][bj][m][n] = __builtin_amdgcn_mfma_f32_16x16x32_bf16(Bt[n][k], At[m][k], acc[ai][bj][m][n], 0, 0, 0); __builtin_amdgcn_s_setprio(0); } while (0)
; #define PG8_WAIT_V(n) asm volatile("s_waitcnt vmcnt(" #n ")" ::: "memory")
; #define PG8_WAIT_L(n) asm volatile("s_waitcnt lgkmcnt(" #n ")" ::: "memory")
; #define PG8_BAR __builtin_amdgcn_s_barrier()
; #define PG8_SCHED __builtin_amdgcn_sched_barrier(0)
; template <class Epi, class Sched, bool ALIGN_EPI = false, bool SP2 = false>
; __device__ __forceinline__ void gemm_phase(PG8_LAS unsigned char* lds, const Gemm g, const Sched& S, const Epi& E, const int wave0) {
;     ...
;         for (int t = 0; t < nt; t += 2) {
;             const bool last = (t == nt - 2);
;             const char* a1 = cA + (size_t)(t + 1) * kstep;
;             const char* a2 = last ? nA : cA + (size_t)(t + 2) * kstep; const char* b2 = last ? nB : cB + (size_t)(t + 2) * kstep;
;     ...
;             PG8_LDB(B0, 1, 0); PG8_LDB(B1, 1, 1); PG8_SCHED; PG8_LDA(At, 1, 0); PG8_STAGE(PG8_SA(0, 1), a2 + hstepA, voffA);
;             PG8_WAIT_V(8); PG8_WAIT_L(0); PG8_BAR; PG8_MMA(0, 0, At, B0); PG8_MMA(0, 1, At, B1); PG8_BAR; PG8_SCHED;
;             PG8_LDA(At, 1, 1); PG8_STAGE(PG8_SB(1, 0), b3, voffB); PG8_STAGE(PG8_SB(1, 1), b3 + hstepB, voffB); PG8_STAGE(PG8_SA(1, 0), a3, voffA);
;             PG8_WAIT_V(8); PG8_WAIT_L(0); PG8_BAR; PG8_MMA(1, 0, At, B0); PG8_MMA(1, 1, At, B1); PG8_BAR; PG8_SCHED;
	s_add_i32 s42, 0, 0x18000
	s_add_i32 s43, 0, 0x1c000
	ds_read_b128 v[144:147], v254
	ds_read_b128 v[148:151], v254 offset:1024
	ds_read_b128 v[152:155], v254 offset:2048
	ds_read_b128 v[156:159], v254 offset:3072
	ds_read_b128 v[178:181], v255
	ds_read_b128 v[182:185], v255 offset:1024
	ds_read_b128 v[186:189], v255 offset:2048
	ds_read_b128 v[190:193], v255 offset:3072
	s_add_u32 s18, s18, 0x80000
	s_addc_u32 s19, s19, 0
	s_mov_b32 m0, s25
	ds_read_b128 v[194:197], v143 offset:32768
	ds_read_b128 v[208:211], v143 offset:33792
	ds_read_b128 v[212:215], v143 offset:34816
	ds_read_b128 v[216:219], v143 offset:35840
	ds_read_b128 v[220:223], v143 offset:36864
	ds_read_b128 v[224:227], v143 offset:37888
	ds_read_b128 v[228:231], v143 offset:38912
	ds_read_b128 v[232:235], v143 offset:39936
	global_load_lds_dwordx4 v134, s[18:19]
	s_mov_b32 m0, s33
	s_nop 0
	global_load_lds_dwordx4 v132, s[18:19]
	s_waitcnt vmcnt(8)
	s_waitcnt lgkmcnt(0)
	s_setprio 1
	s_barrier
	v_mfma_f32_16x16x32_bf16 v[126:129], v[144:147], v[194:197], v[126:129]
	v_mfma_f32_16x16x32_bf16 v[122:125], v[152:155], v[194:197], v[122:125]
	v_mfma_f32_16x16x32_bf16 v[118:121], v[144:147], v[212:215], v[118:121]
	v_mfma_f32_16x16x32_bf16 v[114:117], v[152:155], v[212:215], v[114:117]
	v_mfma_f32_16x16x32_bf16 v[102:105], v[144:147], v[220:223], v[102:105]
	v_mfma_f32_16x16x32_bf16 v[98:101], v[152:155], v[220:223], v[98:101]
	v_mfma_f32_16x16x32_bf16 v[86:89], v[144:147], v[228:231], v[86:89]
	v_mfma_f32_16x16x32_bf16 v[82:85], v[152:155], v[228:231], v[82:85]
	s_setprio 0
	s_setprio 1
	v_mfma_f32_16x16x32_bf16 v[126:129], v[148:151], v[208:211], v[126:129]
	v_mfma_f32_16x16x32_bf16 v[122:125], v[156:159], v[208:211], v[122:125]
	v_mfma_f32_16x16x32_bf16 v[118:121], v[148:151], v[216:219], v[118:121]
	v_mfma_f32_16x16x32_bf16 v[114:117], v[156:159], v[216:219], v[114:117]
	v_mfma_f32_16x16x32_bf16 v[102:105], v[148:151], v[224:227], v[102:105]
	v_mfma_f32_16x16x32_bf16 v[98:101], v[156:159], v[224:227], v[98:101]
	v_mfma_f32_16x16x32_bf16 v[86:89], v[148:151], v[232:235], v[86:89]
	v_mfma_f32_16x16x32_bf16 v[82:85], v[156:159], v[232:235], v[82:85]
	s_setprio 0
	s_setprio 1
	v_mfma_f32_16x16x32_bf16 v[110:113], v[178:181], v[194:197], v[110:113]
	v_mfma_f32_16x16x32_bf16 v[106:109], v[186:189], v[194:197], v[106:109]
	v_mfma_f32_16x16x32_bf16 v[94:97], v[178:181], v[212:215], v[94:97]
	v_mfma_f32_16x16x32_bf16 v[90:93], v[186:189], v[212:215], v[90:93]
	v_mfma_f32_16x16x32_bf16 v[78:81], v[178:181], v[220:223], v[78:81]
	v_mfma_f32_16x16x32_bf16 v[74:77], v[186:189], v[220:223], v[74:77]
	v_mfma_f32_16x16x32_bf16 v[70:73], v[178:181], v[228:231], v[70:73]
	v_mfma_f32_16x16x32_bf16 v[66:69], v[186:189], v[228:231], v[66:69]
	s_setprio 0
	s_setprio 1
	v_mfma_f32_16x16x32_bf16 v[110:113], v[182:185], v[208:211], v[110:113]
	v_mfma_f32_16x16x32_bf16 v[106:109], v[190:193], v[208:211], v[106:109]
	v_mfma_f32_16x16x32_bf16 v[94:97], v[182:185], v[216:219], v[94:97]
	v_mfma_f32_16x16x32_bf16 v[90:93], v[190:193], v[216:219], v[90:93]
	v_mfma_f32_16x16x32_bf16 v[78:81], v[182:185], v[224:227], v[78:81]
	v_mfma_f32_16x16x32_bf16 v[74:77], v[190:193], v[224:227], v[74:77]
	v_mfma_f32_16x16x32_bf16 v[70:73], v[182:185], v[232:235], v[70:73]
	v_mfma_f32_16x16x32_bf16 v[66:69], v[190:193], v[232:235], v[66:69]
	s_setprio 0
	s_barrier
	s_add_i32 s18, s42, s22
	s_add_u32 s46, s16, 0x80
	s_addc_u32 s47, s17, 0
	s_mov_b32 m0, s18
	ds_read_b128 v[194:197], v143 offset:49152
	ds_read_b128 v[208:211], v143 offset:50176
	ds_read_b128 v[212:215], v143 offset:51200
	ds_read_b128 v[216:219], v143 offset:52224
	ds_read_b128 v[220:223], v143 offset:53248
	ds_read_b128 v[224:227], v143 offset:54272
	ds_read_b128 v[228:231], v143 offset:55296
	ds_read_b128 v[232:235], v143 offset:56320
	global_load_lds_dwordx4 v64, s[46:47]
	s_add_i32 m0, s18, 0x2000
	s_add_u32 s16, s16, 0x80080
	s_addc_u32 s17, s17, 0
	s_add_i32 s18, s43, s22
	global_load_lds_dwordx4 v130, s[46:47]
	s_mov_b32 m0, s18
	s_nop 0
	global_load_lds_dwordx4 v64, s[16:17]
	s_add_i32 m0, s18, 0x2000
	s_nop 0
	global_load_lds_dwordx4 v130, s[16:17]
	s_add_u32 s100, s100, 0x80
	s_addc_u32 s101, s101, 0
	s_mov_b32 m0, s34
	s_nop 0
	global_load_lds_dwordx4 v134, s[100:101]
	s_mov_b32 m0, s35
	s_nop 0
	global_load_lds_dwordx4 v132, s[100:101]
	s_waitcnt vmcnt(8)
	s_waitcnt lgkmcnt(0)
	s_setprio 1
	s_barrier
	v_mfma_f32_16x16x32_bf16 v[60:63], v[144:147], v[194:197], v[60:63]
	v_mfma_f32_16x16x32_bf16 v[56:59], v[152:155], v[194:197], v[56:59]
	v_mfma_f32_16x16x32_bf16 v[52:55], v[144:147], v[212:215], v[52:55]
	v_mfma_f32_16x16x32_bf16 v[48:51], v[152:155], v[212:215], v[48:51]
	v_mfma_f32_16x16x32_bf16 v[36:39], v[144:147], v[220:223], v[36:39]
	v_mfma_f32_16x16x32_bf16 v[32:35], v[152:155], v[220:223], v[32:35]
	v_mfma_f32_16x16x32_bf16 v[20:23], v[144:147], v[228:231], v[20:23]
	v_mfma_f32_16x16x32_bf16 v[16:19], v[152:155], v[228:231], v[16:19]
	s_setprio 0
	s_setprio 1
	v_mfma_f32_16x16x32_bf16 v[60:63], v[148:151], v[208:211], v[60:63]
	v_mfma_f32_16x16x32_bf16 v[56:59], v[156:159], v[208:211], v[56:59]
	v_mfma_f32_16x16x32_bf16 v[52:55], v[148:151], v[216:219], v[52:55]
	v_mfma_f32_16x16x32_bf16 v[48:51], v[156:159], v[216:219], v[48:51]
	v_mfma_f32_16x16x32_bf16 v[36:39], v[148:151], v[224:227], v[36:39]
	v_mfma_f32_16x16x32_bf16 v[32:35], v[156:159], v[224:227], v[32:35]
	v_mfma_f32_16x16x32_bf16 v[20:23], v[148:151], v[232:235], v[20:23]
	v_mfma_f32_16x16x32_bf16 v[16:19], v[156:159], v[232:235], v[16:19]
	s_setprio 0
	s_setprio 1
	v_mfma_f32_16x16x32_bf16 v[44:47], v[178:181], v[194:197], v[44:47]
	v_mfma_f32_16x16x32_bf16 v[40:43], v[186:189], v[194:197], v[40:43]
	v_mfma_f32_16x16x32_bf16 v[28:31], v[178:181], v[212:215], v[28:31]
	v_mfma_f32_16x16x32_bf16 v[24:27], v[186:189], v[212:215], v[24:27]
	v_mfma_f32_16x16x32_bf16 v[12:15], v[178:181], v[220:223], v[12:15]
	v_mfma_f32_16x16x32_bf16 v[8:11], v[186:189], v[220:223], v[8:11]
	v_mfma_f32_16x16x32_bf16 v[4:7], v[178:181], v[228:231], v[4:7]
	v_mfma_f32_16x16x32_bf16 v[0:3], v[186:189], v[228:231], v[0:3]
	s_setprio 0
	s_setprio 1
	v_mfma_f32_16x16x32_bf16 v[44:47], v[182:185], v[208:211], v[44:47]
	v_mfma_f32_16x16x32_bf16 v[40:43], v[190:193], v[208:211], v[40:43]
	v_mfma_f32_16x16x32_bf16 v[28:31], v[182:185], v[216:219], v[28:31]
	v_mfma_f32_16x16x32_bf16 v[24:27], v[190:193], v[216:219], v[24:27]
	v_mfma_f32_16x16x32_bf16 v[12:15], v[182:185], v[224:227], v[12:15]
	v_mfma_f32_16x16x32_bf16 v[8:11], v[190:193], v[224:227], v[8:11]
	v_mfma_f32_16x16x32_bf16 v[4:7], v[182:185], v[232:235], v[4:7]
	v_mfma_f32_16x16x32_bf16 v[0:3], v[190:193], v[232:235], v[0:3]
	s_setprio 0
	s_barrier
	s_add_i32 s41, s41, 2
	s_add_u32 s0, s0, 0x100
	s_addc_u32 s1, s1, 0
	s_add_u32 s15, s15, 0x100
	s_addc_u32 s27, s27, 0
	s_cmp_gt_u32 s41, 13
	s_cbranch_scc0 .LBB0_1360
	s_mov_b64 s[46:47], 0x80
	s_and_b64 vcc, exec, s[8:9]
	s_cbranch_vccz .LBB0_1363
	s_barrier

; #define PG8_STAGE(bufoff, gbase, voff) do { _Pragma("unroll") for (int _i = 0; _i < 2; ++_i) \
;         __builtin_amdgcn_global_load_lds((const unsigned*)((const char*)(gbase) + (voff)[_i]), (PG8_LAS unsigned*)(lds + (bufoff) + ldsw + _i * 8192), 16, 0, 0); } while (0)
; #define PG8_LDA(dst, b, h) do { _Pragma("unroll") for (int m = 0; m < 4; ++m) _Pragma("unroll") for (int k = 0; k < 2; ++k) dst[m][k] = *(const PG8_LAS bf16x8*)(lds + PG8_SA(b, h) + aoff + m * 2048 + k * 1024); } while (0)
; #define PG8_LDB(dst, b, h) do { _Pragma("unroll") for (int n = 0; n < 2; ++n) _Pragma("unroll") for (int k = 0; k < 2; ++k) dst[n][k] = *(const PG8_LAS bf16x8*)(lds + PG8_SB(b, h) + boff + n * 2048 + k * 1024); } while (0)
; #define PG8_MMA(ai, bj, At, Bt) do { __builtin_amdgcn_s_setprio(1); _Pragma("unroll") for (int m = 0; m < 4; ++m) _Pragma("unroll") for (int n = 0; n < 2; ++n) _Pragma("unroll") for (int k = 0; k < 2; ++k) \
;         acc[ai][bj][m][n] = __builtin_amdgcn_mfma_f32_16x16x32_bf16(Bt[n][k], At[m][k], acc[ai][bj][m][n], 0, 0, 0); __builtin_amdgcn_s_setprio(0); } while (0)
; #define PG8_WAIT_V(n) asm volatile("s_waitcnt vmcnt(" #n ")" ::: "memory")
; #define PG8_WAIT_L(n) asm volatile("s_waitcnt lgkmcnt(" #n ")" ::: "memory")
; template <class Epi, class Sched, bool ALIGN_EPI = false, bool SP2 = false>
; __device__ __forceinline__ void gemm_phase(PG8_LAS unsigned char* lds, const Gemm g, const Sched& S, const Epi& E, const int wave0) {
;     ...
;             const bool last = (t == nt - 2);
;             const char* a1 = cA + (size_t)(t + 1) * kstep;
;             const char* a2 = last ? nA : cA + (size_t)(t + 2) * kstep; const char* b2 = last ? nB : cB + (size_t)(t + 2) * kstep;
;             const char* a3 = a2 + kstep; const char* b3 = b2 + kstep;
;             if (last && has_next) S.a_ready(nxt);
;             if constexpr (SP2) {
;             PG8_LDB(B0, 0, 0); PG8_LDB(B1, 0, 1); PG8_SCHED; PG8_LDA(At, 0, 0); PG8_STAGE(PG8_SA(1, 1), a1 + hstepA, voffA);
;             PG8_WAIT_V(8); PG8_WAIT_L(0); PG8_BAR; PG8_MMA(0, 0, At, B0); PG8_MMA(0, 1, At, B1); PG8_BAR; PG8_SCHED;
;             PG8_LDA(At, 0, 1); PG8_STAGE(PG8_SB(0, 0), b2, voffB); PG8_STAGE(PG8_SB(0, 1), b2 + hstepB, voffB); PG8_STAGE(PG8_SA(0, 0), a2, voffA);
;             PG8_WAIT_V(8); PG8_WAIT_L(0); PG8_BAR; PG8_MMA(1, 0, At, B0); PG8_MMA(1, 1, At, B1); PG8_BAR; PG8_SCHED;
.LBB0_1571:
	s_add_u32 s16, s0, 0xfff80080
	s_addc_u32 s17, s1, -1
	s_add_i32 s46, 0, 0x10000
	s_cmp_eq_u32 s45, 28
	s_cselect_b32 s19, s9, s17
	s_cselect_b32 s18, s33, s16
	s_cselect_b32 s17, s7, s44
	s_cselect_b32 s16, s36, s37
	s_add_i32 s48, 0, 0x14000
	ds_read_b128 v[140:143], v252
	ds_read_b128 v[148:151], v252 offset:1024
	ds_read_b128 v[152:155], v252 offset:2048
	ds_read_b128 v[156:159], v252 offset:3072
	ds_read_b128 v[178:181], v253
	ds_read_b128 v[182:185], v253 offset:1024
	ds_read_b128 v[186:189], v253 offset:2048
	ds_read_b128 v[190:193], v253 offset:3072
	s_add_i32 m0, s15, 0xc000
	ds_read_b128 v[194:197], v147
	ds_read_b128 v[208:211], v147 offset:1024
	ds_read_b128 v[212:215], v147 offset:2048
	ds_read_b128 v[216:219], v147 offset:3072
	ds_read_b128 v[220:223], v147 offset:4096
	ds_read_b128 v[224:227], v147 offset:5120
	ds_read_b128 v[228:231], v147 offset:6144
	ds_read_b128 v[232:235], v147 offset:7168
	global_load_lds_dwordx4 v136, s[0:1]
	s_add_i32 m0, s15, 0xe000
	s_nop 0
	global_load_lds_dwordx4 v138, s[0:1]
	s_waitcnt vmcnt(8)
	s_waitcnt lgkmcnt(0)
	s_setprio 1
	s_barrier
	v_mfma_f32_16x16x32_bf16 v[126:129], v[140:143], v[194:197], v[126:129]
	v_mfma_f32_16x16x32_bf16 v[122:125], v[152:155], v[194:197], v[122:125]
	v_mfma_f32_16x16x32_bf16 v[110:113], v[140:143], v[212:215], v[110:113]
	v_mfma_f32_16x16x32_bf16 v[106:109], v[152:155], v[212:215], v[106:109]
	v_mfma_f32_16x16x32_bf16 v[94:97], v[140:143], v[220:223], v[94:97]
	v_mfma_f32_16x16x32_bf16 v[90:93], v[152:155], v[220:223], v[90:93]
	v_mfma_f32_16x16x32_bf16 v[78:81], v[140:143], v[228:231], v[78:81]
	v_mfma_f32_16x16x32_bf16 v[74:77], v[152:155], v[228:231], v[74:77]
	s_setprio 0
	s_setprio 1
	v_mfma_f32_16x16x32_bf16 v[126:129], v[148:151], v[208:211], v[126:129]
	v_mfma_f32_16x16x32_bf16 v[122:125], v[156:159], v[208:211], v[122:125]
	v_mfma_f32_16x16x32_bf16 v[110:113], v[148:151], v[216:219], v[110:113]
	v_mfma_f32_16x16x32_bf16 v[106:109], v[156:159], v[216:219], v[106:109]
	v_mfma_f32_16x16x32_bf16 v[94:97], v[148:151], v[224:227], v[94:97]
	v_mfma_f32_16x16x32_bf16 v[90:93], v[156:159], v[224:227], v[90:93]
	v_mfma_f32_16x16x32_bf16 v[78:81], v[148:151], v[232:235], v[78:81]
	v_mfma_f32_16x16x32_bf16 v[74:77], v[156:159], v[232:235], v[74:77]
	s_setprio 0
	s_setprio 1
	v_mfma_f32_16x16x32_bf16 v[118:121], v[178:181], v[194:197], v[118:121]
	v_mfma_f32_16x16x32_bf16 v[114:117], v[186:189], v[194:197], v[114:117]
	v_mfma_f32_16x16x32_bf16 v[102:105], v[178:181], v[212:215], v[102:105]
	v_mfma_f32_16x16x32_bf16 v[98:101], v[186:189], v[212:215], v[98:101]
	v_mfma_f32_16x16x32_bf16 v[86:89], v[178:181], v[220:223], v[86:89]
	v_mfma_f32_16x16x32_bf16 v[82:85], v[186:189], v[220:223], v[82:85]
	v_mfma_f32_16x16x32_bf16 v[70:73], v[178:181], v[228:231], v[70:73]
	v_mfma_f32_16x16x32_bf16 v[66:69], v[186:189], v[228:231], v[66:69]
	s_setprio 0
	s_setprio 1
	v_mfma_f32_16x16x32_bf16 v[118:121], v[182:185], v[208:211], v[118:121]
	v_mfma_f32_16x16x32_bf16 v[114:117], v[190:193], v[208:211], v[114:117]
	v_mfma_f32_16x16x32_bf16 v[102:105], v[182:185], v[216:219], v[102:105]
	v_mfma_f32_16x16x32_bf16 v[98:101], v[190:193], v[216:219], v[98:101]
	v_mfma_f32_16x16x32_bf16 v[86:89], v[182:185], v[224:227], v[86:89]
	v_mfma_f32_16x16x32_bf16 v[82:85], v[190:193], v[224:227], v[82:85]
	v_mfma_f32_16x16x32_bf16 v[70:73], v[182:185], v[232:235], v[70:73]
	v_mfma_f32_16x16x32_bf16 v[66:69], v[190:193], v[232:235], v[66:69]
	s_setprio 0
	s_barrier
	s_add_i32 s46, s46, s28
	s_mov_b32 m0, s46
	ds_read_b128 v[194:197], v147 offset:16384
	ds_read_b128 v[208:211], v147 offset:17408
	ds_read_b128 v[212:215], v147 offset:18432
	ds_read_b128 v[216:219], v147 offset:19456
	ds_read_b128 v[220:223], v147 offset:20480
	ds_read_b128 v[224:227], v147 offset:21504
	ds_read_b128 v[228:231], v147 offset:22528
	ds_read_b128 v[232:235], v147 offset:23552
	global_load_lds_dwordx4 v64, s[16:17]
	s_add_i32 m0, s46, 0x2000
	s_add_u32 s46, s16, 0x80000
	s_addc_u32 s47, s17, 0
	s_add_i32 s48, s48, s28
	global_load_lds_dwordx4 v130, s[16:17]
	s_mov_b32 m0, s48
	s_mov_b64 s[100:101], s[18:19]
	global_load_lds_dwordx4 v64, s[46:47]
	s_add_i32 m0, s48, 0x2000
	s_nop 0
	global_load_lds_dwordx4 v130, s[46:47]
	s_mov_b32 m0, s15
	s_nop 0
	global_load_lds_dwordx4 v134, s[18:19]
	s_mov_b32 m0, s27
	s_nop 0
	global_load_lds_dwordx4 v132, s[18:19]
	s_waitcnt vmcnt(8)
	s_waitcnt lgkmcnt(0)
	s_setprio 1
	s_barrier
	v_mfma_f32_16x16x32_bf16 v[60:63], v[140:143], v[194:197], v[60:63]
	v_mfma_f32_16x16x32_bf16 v[56:59], v[152:155], v[194:197], v[56:59]
	v_mfma_f32_16x16x32_bf16 v[44:47], v[140:143], v[212:215], v[44:47]
	v_mfma_f32_16x16x32_bf16 v[40:43], v[152:155], v[212:215], v[40:43]
	v_mfma_f32_16x16x32_bf16 v[28:31], v[140:143], v[220:223], v[28:31]
	v_mfma_f32_16x16x32_bf16 v[24:27], v[152:155], v[220:223], v[24:27]
	v_mfma_f32_16x16x32_bf16 v[12:15], v[140:143], v[228:231], v[12:15]
	v_mfma_f32_16x16x32_bf16 v[8:11], v[152:155], v[228:231], v[8:11]
	s_setprio 0
	s_setprio 1
	v_mfma_f32_16x16x32_bf16 v[60:63], v[148:151], v[208:211], v[60:63]
	v_mfma_f32_16x16x32_bf16 v[56:59], v[156:159], v[208:211], v[56:59]
	v_mfma_f32_16x16x32_bf16 v[44:47], v[148:151], v[216:219], v[44:47]
	v_mfma_f32_16x16x32_bf16 v[40:43], v[156:159], v[216:219], v[40:43]
	v_mfma_f32_16x16x32_bf16 v[28:31], v[148:151], v[224:227], v[28:31]
	v_mfma_f32_16x16x32_bf16 v[24:27], v[156:159], v[224:227], v[24:27]
	v_mfma_f32_16x16x32_bf16 v[12:15], v[148:151], v[232:235], v[12:15]
	v_mfma_f32_16x16x32_bf16 v[8:11], v[156:159], v[232:235], v[8:11]
	s_setprio 0
	s_setprio 1
	v_mfma_f32_16x16x32_bf16 v[52:55], v[178:181], v[194:197], v[52:55]
	v_mfma_f32_16x16x32_bf16 v[48:51], v[186:189], v[194:197], v[48:51]
	v_mfma_f32_16x16x32_bf16 v[36:39], v[178:181], v[212:215], v[36:39]
	v_mfma_f32_16x16x32_bf16 v[32:35], v[186:189], v[212:215], v[32:35]
	v_mfma_f32_16x16x32_bf16 v[20:23], v[178:181], v[220:223], v[20:23]
	v_mfma_f32_16x16x32_bf16 v[16:19], v[186:189], v[220:223], v[16:19]
	v_mfma_f32_16x16x32_bf16 v[4:7], v[178:181], v[228:231], v[4:7]
	v_mfma_f32_16x16x32_bf16 v[0:3], v[186:189], v[228:231], v[0:3]
	s_setprio 0
	s_setprio 1
	v_mfma_f32_16x16x32_bf16 v[52:55], v[182:185], v[208:211], v[52:55]
	v_mfma_f32_16x16x32_bf16 v[48:51], v[190:193], v[208:211], v[48:51]
	v_mfma_f32_16x16x32_bf16 v[36:39], v[182:185], v[216:219], v[36:39]
	v_mfma_f32_16x16x32_bf16 v[32:35], v[190:193], v[216:219], v[32:35]
	v_mfma_f32_16x16x32_bf16 v[20:23], v[182:185], v[224:227], v[20:23]
	v_mfma_f32_16x16x32_bf16 v[16:19], v[190:193], v[224:227], v[16:19]
	v_mfma_f32_16x16x32_bf16 v[4:7], v[182:185], v[232:235], v[4:7]
	v_mfma_f32_16x16x32_bf16 v[0:3], v[190:193], v[232:235], v[0:3]
	s_setprio 0
	s_barrier
; #define PG8_STAGE(bufoff, gbase, voff) do { _Pragma("unroll") for (int _i = 0; _i < 2; ++_i) \
;         __builtin_amdgcn_global_load_lds((const unsigned*)((const char*)(gbase) + (voff)[_i]), (PG8_LAS unsigned*)(lds + (bufoff) + ldsw + _i * 8192), 16, 0, 0); } while (0)
; #define PG8_LDA(dst, b, h) do { _Pragma("unroll") for (int m = 0; m < 4; ++m) _Pragma("unroll") for (int k = 0; k < 2; ++k) dst[m][k] = *(const PG8_LAS bf16x8*)(lds + PG8_SA(b, h) + aoff + m * 2048 + k * 1024); } while (0)
; #define PG8_LDB(dst, b, h) do { _Pragma("unroll") for (int n = 0; n < 2; ++n) _Pragma("unroll") for (int k = 0; k < 2; ++k) dst[n][k] = *(const PG8_LAS bf16x8*)(lds + PG8_SB(b, h) + boff + n * 2048 + k * 1024); } while (0)
; #define PG8_MMA(ai, bj, At, Bt) do { __builtin_amdgcn_s_setprio(1); _Pragma("unroll") for (int m = 0; m < 4; ++m) _Pragma("unroll") for (int n = 0; n < 2; ++n) _Pragma("unroll") for (int k = 0; k < 2; ++k) \
;         acc[ai][bj][m][n] = __builtin_amdgcn_mfma_f32_16x16x32_bf16(Bt[n][k], At[m][k], acc[ai][bj][m][n], 0, 0, 0); __builtin_amdgcn_s_setprio(0); } while (0)
; #define PG8_WAIT_V(n) asm volatile("s_waitcnt vmcnt(" #n ")" ::: "memory")
; #define PG8_WAIT_L(n) asm volatile("s_waitcnt lgkmcnt(" #n ")" ::: "memory")
; #define PG8_BAR __builtin_amdgcn_s_barrier()
; #define PG8_SCHED __builtin_amdgcn_sched_barrier(0)
; template <class Epi, class Sched, bool ALIGN_EPI = false, bool SP2 = false>
; __device__ __forceinline__ void gemm_phase(PG8_LAS unsigned char* lds, const Gemm g, const Sched& S, const Epi& E, const int wave0) {
;     ...
;         for (int t = 0; t < nt; t += 2) {
;     ...
;             PG8_LDB(B0, 1, 0); PG8_LDB(B1, 1, 1); PG8_SCHED; PG8_LDA(At, 1, 0); PG8_STAGE(PG8_SA(0, 1), a2 + hstepA, voffA);
;             PG8_WAIT_V(8); PG8_WAIT_L(0); PG8_BAR; PG8_MMA(0, 0, At, B0); PG8_MMA(0, 1, At, B1); PG8_BAR; PG8_SCHED;
;             PG8_LDA(At, 1, 1); PG8_STAGE(PG8_SB(1, 0), b3, voffB); PG8_STAGE(PG8_SB(1, 1), b3 + hstepB, voffB); PG8_STAGE(PG8_SA(1, 0), a3, voffA);
;             PG8_WAIT_V(8); PG8_WAIT_L(0); PG8_BAR; PG8_MMA(1, 0, At, B0); PG8_MMA(1, 1, At, B1); PG8_BAR; PG8_SCHED;
	s_add_i32 s46, 0, 0x18000
	s_add_i32 s47, 0, 0x1c000
	ds_read_b128 v[140:143], v254
	ds_read_b128 v[148:151], v254 offset:1024
	ds_read_b128 v[152:155], v254 offset:2048
	ds_read_b128 v[156:159], v254 offset:3072
	ds_read_b128 v[178:181], v255
	ds_read_b128 v[182:185], v255 offset:1024
	ds_read_b128 v[186:189], v255 offset:2048
	ds_read_b128 v[190:193], v255 offset:3072
	s_add_u32 s18, s18, 0x80000
	s_addc_u32 s19, s19, 0
	s_mov_b32 m0, s29
	ds_read_b128 v[194:197], v147 offset:32768
	ds_read_b128 v[208:211], v147 offset:33792
	ds_read_b128 v[212:215], v147 offset:34816
	ds_read_b128 v[216:219], v147 offset:35840
	ds_read_b128 v[220:223], v147 offset:36864
	ds_read_b128 v[224:227], v147 offset:37888
	ds_read_b128 v[228:231], v147 offset:38912
	ds_read_b128 v[232:235], v147 offset:39936
	global_load_lds_dwordx4 v134, s[18:19]
	s_mov_b32 m0, s30
	s_nop 0
	global_load_lds_dwordx4 v132, s[18:19]
	s_waitcnt vmcnt(8)
	s_waitcnt lgkmcnt(0)
	s_setprio 1
	s_barrier
	v_mfma_f32_16x16x32_bf16 v[126:129], v[140:143], v[194:197], v[126:129]
	v_mfma_f32_16x16x32_bf16 v[122:125], v[152:155], v[194:197], v[122:125]
	v_mfma_f32_16x16x32_bf16 v[110:113], v[140:143], v[212:215], v[110:113]
	v_mfma_f32_16x16x32_bf16 v[106:109], v[152:155], v[212:215], v[106:109]
	v_mfma_f32_16x16x32_bf16 v[94:97], v[140:143], v[220:223], v[94:97]
	v_mfma_f32_16x16x32_bf16 v[90:93], v[152:155], v[220:223], v[90:93]
	v_mfma_f32_16x16x32_bf16 v[78:81], v[140:143], v[228:231], v[78:81]
	v_mfma_f32_16x16x32_bf16 v[74:77], v[152:155], v[228:231], v[74:77]
	s_setprio 0
	s_setprio 1
	v_mfma_f32_16x16x32_bf16 v[126:129], v[148:151], v[208:211], v[126:129]
	v_mfma_f32_16x16x32_bf16 v[122:125], v[156:159], v[208:211], v[122:125]
	v_mfma_f32_16x16x32_bf16 v[110:113], v[148:151], v[216:219], v[110:113]
	v_mfma_f32_16x16x32_bf16 v[106:109], v[156:159], v[216:219], v[106:109]
	v_mfma_f32_16x16x32_bf16 v[94:97], v[148:151], v[224:227], v[94:97]
	v_mfma_f32_16x16x32_bf16 v[90:93], v[156:159], v[224:227], v[90:93]
	v_mfma_f32_16x16x32_bf16 v[78:81], v[148:151], v[232:235], v[78:81]
	v_mfma_f32_16x16x32_bf16 v[74:77], v[156:159], v[232:235], v[74:77]
	s_setprio 0
	s_setprio 1
	v_mfma_f32_16x16x32_bf16 v[118:121], v[178:181], v[194:197], v[118:121]
	v_mfma_f32_16x16x32_bf16 v[114:117], v[186:189], v[194:197], v[114:117]
	v_mfma_f32_16x16x32_bf16 v[102:105], v[178:181], v[212:215], v[102:105]
	v_mfma_f32_16x16x32_bf16 v[98:101], v[186:189], v[212:215], v[98:101]
	v_mfma_f32_16x16x32_bf16 v[86:89], v[178:181], v[220:223], v[86:89]
	v_mfma_f32_16x16x32_bf16 v[82:85], v[186:189], v[220:223], v[82:85]
	v_mfma_f32_16x16x32_bf16 v[70:73], v[178:181], v[228:231], v[70:73]
	v_mfma_f32_16x16x32_bf16 v[66:69], v[186:189], v[228:231], v[66:69]
	s_setprio 0
	s_setprio 1
	v_mfma_f32_16x16x32_bf16 v[118:121], v[182:185], v[208:211], v[118:121]
	v_mfma_f32_16x16x32_bf16 v[114:117], v[190:193], v[208:211], v[114:117]
	v_mfma_f32_16x16x32_bf16 v[102:105], v[182:185], v[216:219], v[102:105]
	v_mfma_f32_16x16x32_bf16 v[98:101], v[190:193], v[216:219], v[98:101]
	v_mfma_f32_16x16x32_bf16 v[86:89], v[182:185], v[224:227], v[86:89]
	v_mfma_f32_16x16x32_bf16 v[82:85], v[190:193], v[224:227], v[82:85]
	v_mfma_f32_16x16x32_bf16 v[70:73], v[182:185], v[232:235], v[70:73]
	v_mfma_f32_16x16x32_bf16 v[66:69], v[190:193], v[232:235], v[66:69]
	s_setprio 0
	s_barrier
	s_add_i32 s18, s46, s28
	s_add_u32 s50, s16, 0x80
	s_addc_u32 s51, s17, 0
	s_mov_b32 m0, s18
	ds_read_b128 v[194:197], v147 offset:49152
	ds_read_b128 v[208:211], v147 offset:50176
	ds_read_b128 v[212:215], v147 offset:51200
	ds_read_b128 v[216:219], v147 offset:52224
	ds_read_b128 v[220:223], v147 offset:53248
	ds_read_b128 v[224:227], v147 offset:54272
	ds_read_b128 v[228:231], v147 offset:55296
	ds_read_b128 v[232:235], v147 offset:56320
	global_load_lds_dwordx4 v64, s[50:51]
	s_add_i32 m0, s18, 0x2000
	s_add_u32 s16, s16, 0x80080
	s_addc_u32 s17, s17, 0
	s_add_i32 s18, s47, s28
	global_load_lds_dwordx4 v130, s[50:51]
	s_mov_b32 m0, s18
	s_nop 0
	global_load_lds_dwordx4 v64, s[16:17]
	s_add_i32 m0, s18, 0x2000
	s_nop 0
	global_load_lds_dwordx4 v130, s[16:17]
	s_add_u32 s100, s100, 0x80
	s_addc_u32 s101, s101, 0
	s_mov_b32 m0, s31
	s_nop 0
	global_load_lds_dwordx4 v134, s[100:101]
	s_mov_b32 m0, s34
	s_nop 0
	global_load_lds_dwordx4 v132, s[100:101]
	s_waitcnt vmcnt(8)
	s_waitcnt lgkmcnt(0)
	s_setprio 1
	s_barrier
	v_mfma_f32_16x16x32_bf16 v[60:63], v[140:143], v[194:197], v[60:63]
	v_mfma_f32_16x16x32_bf16 v[56:59], v[152:155], v[194:197], v[56:59]
	v_mfma_f32_16x16x32_bf16 v[44:47], v[140:143], v[212:215], v[44:47]
	v_mfma_f32_16x16x32_bf16 v[40:43], v[152:155], v[212:215], v[40:43]
	v_mfma_f32_16x16x32_bf16 v[28:31], v[140:143], v[220:223], v[28:31]
	v_mfma_f32_16x16x32_bf16 v[24:27], v[152:155], v[220:223], v[24:27]
	v_mfma_f32_16x16x32_bf16 v[12:15], v[140:143], v[228:231], v[12:15]
	v_mfma_f32_16x16x32_bf16 v[8:11], v[152:155], v[228:231], v[8:11]
	s_setprio 0
	s_setprio 1
	v_mfma_f32_16x16x32_bf16 v[60:63], v[148:151], v[208:211], v[60:63]
	v_mfma_f32_16x16x32_bf16 v[56:59], v[156:159], v[208:211], v[56:59]
	v_mfma_f32_16x16x32_bf16 v[44:47], v[148:151], v[216:219], v[44:47]
	v_mfma_f32_16x16x32_bf16 v[40:43], v[156:159], v[216:219], v[40:43]
	v_mfma_f32_16x16x32_bf16 v[28:31], v[148:151], v[224:227], v[28:31]
	v_mfma_f32_16x16x32_bf16 v[24:27], v[156:159], v[224:227], v[24:27]
	v_mfma_f32_16x16x32_bf16 v[12:15], v[148:151], v[232:235], v[12:15]
	v_mfma_f32_16x16x32_bf16 v[8:11], v[156:159], v[232:235], v[8:11]
	s_setprio 0
	s_setprio 1
	v_mfma_f32_16x16x32_bf16 v[52:55], v[178:181], v[194:197], v[52:55]
	v_mfma_f32_16x16x32_bf16 v[48:51], v[186:189], v[194:197], v[48:51]
	v_mfma_f32_16x16x32_bf16 v[36:39], v[178:181], v[212:215], v[36:39]
	v_mfma_f32_16x16x32_bf16 v[32:35], v[186:189], v[212:215], v[32:35]
	v_mfma_f32_16x16x32_bf16 v[20:23], v[178:181], v[220:223], v[20:23]
	v_mfma_f32_16x16x32_bf16 v[16:19], v[186:189], v[220:223], v[16:19]
	v_mfma_f32_16x16x32_bf16 v[4:7], v[178:181], v[228:231], v[4:7]
	v_mfma_f32_16x16x32_bf16 v[0:3], v[186:189], v[228:231], v[0:3]
	s_setprio 0
	s_setprio 1
	v_mfma_f32_16x16x32_bf16 v[52:55], v[182:185], v[208:211], v[52:55]
	v_mfma_f32_16x16x32_bf16 v[48:51], v[190:193], v[208:211], v[48:51]
	v_mfma_f32_16x16x32_bf16 v[36:39], v[182:185], v[216:219], v[36:39]
	v_mfma_f32_16x16x32_bf16 v[32:35], v[190:193], v[216:219], v[32:35]
	v_mfma_f32_16x16x32_bf16 v[20:23], v[182:185], v[224:227], v[20:23]
	v_mfma_f32_16x16x32_bf16 v[16:19], v[190:193], v[224:227], v[16:19]
	v_mfma_f32_16x16x32_bf16 v[4:7], v[182:185], v[232:235], v[4:7]
	v_mfma_f32_16x16x32_bf16 v[0:3], v[190:193], v[232:235], v[0:3]
	s_setprio 0
	s_barrier
	s_add_i32 s45, s45, 2
	s_add_u32 s0, s0, 0x100
	s_addc_u32 s1, s1, 0
	s_add_u32 s37, s37, 0x100
	s_addc_u32 s44, s44, 0
	s_cmp_gt_u32 s45, 29
	s_cbranch_scc0 .LBB0_1571
	s_mov_b64 s[50:51], 0x80
	s_and_b64 vcc, exec, s[4:5]
	s_cbranch_vccz .LBB0_1574
	s_barrier

; #define PG8_STAGE(bufoff, gbase, voff) do { _Pragma("unroll") for (int _i = 0; _i < 2; ++_i) \
;         __builtin_amdgcn_global_load_lds((const unsigned*)((const char*)(gbase) + (voff)[_i]), (PG8_LAS unsigned*)(lds + (bufoff) + ldsw + _i * 8192), 16, 0, 0); } while (0)
; #define PG8_LDA(dst, b, h) do { _Pragma("unroll") for (int m = 0; m < 4; ++m) _Pragma("unroll") for (int k = 0; k < 2; ++k) dst[m][k] = *(const PG8_LAS bf16x8*)(lds + PG8_SA(b, h) + aoff + m * 2048 + k * 1024); } while (0)
; #define PG8_LDB(dst, b, h) do { _Pragma("unroll") for (int n = 0; n < 2; ++n) _Pragma("unroll") for (int k = 0; k < 2; ++k) dst[n][k] = *(const PG8_LAS bf16x8*)(lds + PG8_SB(b, h) + boff + n * 2048 + k * 1024); } while (0)
; #define PG8_WAIT_V(n) asm volatile("s_waitcnt vmcnt(" #n ")" ::: "memory")
; template <class Epi, class Sched, bool ALIGN_EPI = false, bool SP2 = false>
; __device__ __forceinline__ void gemm_phase(PG8_LAS unsigned char* lds, const Gemm g, const Sched& S, const Epi& E, const int wave0) {
;     ...
;             const bool last = (t == nt - 2);
;             const char* a1 = cA + (size_t)(t + 1) * kstep;
;             const char* a2 = last ? nA : cA + (size_t)(t + 2) * kstep; const char* b2 = last ? nB : cB + (size_t)(t + 2) * kstep;
;             const char* a3 = a2 + kstep; const char* b3 = b2 + kstep;
;             if (last && has_next) S.a_ready(nxt);
;             if constexpr (SP2) {
;             PG8_LDB(B0, 0, 0); PG8_LDB(B1, 0, 1); PG8_SCHED; PG8_LDA(At, 0, 0); PG8_STAGE(PG8_SA(1, 1), a1 + hstepA, voffA);
;             PG8_WAIT_V(8); PG8_WAIT_L(0); PG8_BAR; PG8_MMA(0, 0, At, B0); PG8_MMA(0, 1, At, B1); PG8_BAR; PG8_SCHED;
;             PG8_LDA(At, 0, 1); PG8_STAGE(PG8_SB(0, 0), b2, voffB); PG8_STAGE(PG8_SB(0, 1), b2 + hstepB, voffB); PG8_STAGE(PG8_SA(0, 0), a2, voffA);
;             PG8_WAIT_V(8); PG8_WAIT_L(0); PG8_BAR; PG8_MMA(1, 0, At, B0); PG8_MMA(1, 1, At, B1); PG8_BAR; PG8_SCHED;
; __global__ void __launch_bounds__(NWAVES * 64, 2) fwd_kernel(Args args) {
;     ...
;             RUN(8, { pg8::Gemm g{(const bf16*)(ws + WS_HM), (const bf16*)(ws + WS_WM2) + (size_t)l * 2048 * 8192, ML, 2048, DFF, 0, 0, DFF, DFF}; pg8::StaticOrder S; S.init(ML, 2048, F.G, (int)blockIdx.x, WGM_M2);
;             pg8::EpiBf16<0> E{(bf16*)(ws + WS_MIX), 2048, 0};
;             pg8::gemm_phase<pg8::EpiBf16<0>, pg8::StaticOrder, true, true>(F.lds + RING_OFF, g, S, E, F.wave);
.LBB0_1685:
	s_add_u32 s16, s0, 0xffe00080
	s_addc_u32 s17, s1, -1
	s_add_i32 s43, 0, 0x10000
	s_cmpk_eq_i32 s42, 0x7c
	s_cselect_b32 s19, s11, s17
	s_cselect_b32 s18, s34, s16
	s_cselect_b32 s17, s9, s37
	s_cselect_b32 s16, s35, s36
	s_add_i32 s46, 0, 0x14000
	ds_read_b128 v[144:147], v252
	ds_read_b128 v[148:151], v252 offset:1024
	ds_read_b128 v[152:155], v252 offset:2048
	ds_read_b128 v[156:159], v252 offset:3072
	ds_read_b128 v[178:181], v253
	ds_read_b128 v[182:185], v253 offset:1024
	ds_read_b128 v[186:189], v253 offset:2048
	ds_read_b128 v[190:193], v253 offset:3072
	s_add_i32 m0, s21, 0xc000
	ds_read_b128 v[194:197], v143
	ds_read_b128 v[208:211], v143 offset:1024
	ds_read_b128 v[212:215], v143 offset:2048
	ds_read_b128 v[216:219], v143 offset:3072
	ds_read_b128 v[220:223], v143 offset:4096
	ds_read_b128 v[224:227], v143 offset:5120
	ds_read_b128 v[228:231], v143 offset:6144
	ds_read_b128 v[232:235], v143 offset:7168
	global_load_lds_dwordx4 v136, s[0:1]
	s_add_i32 m0, s21, 0xe000
	s_nop 0
	global_load_lds_dwordx4 v138, s[0:1]
	s_waitcnt vmcnt(8)
	s_waitcnt lgkmcnt(0)
	s_setprio 1
	s_barrier
	v_mfma_f32_16x16x32_bf16 v[126:129], v[144:147], v[194:197], v[126:129]
	v_mfma_f32_16x16x32_bf16 v[122:125], v[152:155], v[194:197], v[122:125]
	v_mfma_f32_16x16x32_bf16 v[118:121], v[144:147], v[212:215], v[118:121]
	v_mfma_f32_16x16x32_bf16 v[114:117], v[152:155], v[212:215], v[114:117]
	v_mfma_f32_16x16x32_bf16 v[102:105], v[144:147], v[220:223], v[102:105]
	v_mfma_f32_16x16x32_bf16 v[98:101], v[152:155], v[220:223], v[98:101]
	v_mfma_f32_16x16x32_bf16 v[86:89], v[144:147], v[228:231], v[86:89]
	v_mfma_f32_16x16x32_bf16 v[82:85], v[152:155], v[228:231], v[82:85]
	s_setprio 0
	s_setprio 1
	v_mfma_f32_16x16x32_bf16 v[126:129], v[148:151], v[208:211], v[126:129]
	v_mfma_f32_16x16x32_bf16 v[122:125], v[156:159], v[208:211], v[122:125]
	v_mfma_f32_16x16x32_bf16 v[118:121], v[148:151], v[216:219], v[118:121]
	v_mfma_f32_16x16x32_bf16 v[114:117], v[156:159], v[216:219], v[114:117]
	v_mfma_f32_16x16x32_bf16 v[102:105], v[148:151], v[224:227], v[102:105]
	v_mfma_f32_16x16x32_bf16 v[98:101], v[156:159], v[224:227], v[98:101]
	v_mfma_f32_16x16x32_bf16 v[86:89], v[148:151], v[232:235], v[86:89]
	v_mfma_f32_16x16x32_bf16 v[82:85], v[156:159], v[232:235], v[82:85]
	s_setprio 0
	s_setprio 1
	v_mfma_f32_16x16x32_bf16 v[110:113], v[178:181], v[194:197], v[110:113]
	v_mfma_f32_16x16x32_bf16 v[106:109], v[186:189], v[194:197], v[106:109]
	v_mfma_f32_16x16x32_bf16 v[94:97], v[178:181], v[212:215], v[94:97]
	v_mfma_f32_16x16x32_bf16 v[90:93], v[186:189], v[212:215], v[90:93]
	v_mfma_f32_16x16x32_bf16 v[78:81], v[178:181], v[220:223], v[78:81]
	v_mfma_f32_16x16x32_bf16 v[74:77], v[186:189], v[220:223], v[74:77]
	v_mfma_f32_16x16x32_bf16 v[70:73], v[178:181], v[228:231], v[70:73]
	v_mfma_f32_16x16x32_bf16 v[66:69], v[186:189], v[228:231], v[66:69]
	s_setprio 0
	s_setprio 1
	v_mfma_f32_16x16x32_bf16 v[110:113], v[182:185], v[208:211], v[110:113]
	v_mfma_f32_16x16x32_bf16 v[106:109], v[190:193], v[208:211], v[106:109]
	v_mfma_f32_16x16x32_bf16 v[94:97], v[182:185], v[216:219], v[94:97]
	v_mfma_f32_16x16x32_bf16 v[90:93], v[190:193], v[216:219], v[90:93]
	v_mfma_f32_16x16x32_bf16 v[78:81], v[182:185], v[224:227], v[78:81]
	v_mfma_f32_16x16x32_bf16 v[74:77], v[190:193], v[224:227], v[74:77]
	v_mfma_f32_16x16x32_bf16 v[70:73], v[182:185], v[232:235], v[70:73]
	v_mfma_f32_16x16x32_bf16 v[66:69], v[190:193], v[232:235], v[66:69]
	s_setprio 0
	s_barrier
	s_add_i32 s43, s43, s20
	s_mov_b32 m0, s43
	ds_read_b128 v[194:197], v143 offset:16384
	ds_read_b128 v[208:211], v143 offset:17408
	ds_read_b128 v[212:215], v143 offset:18432
	ds_read_b128 v[216:219], v143 offset:19456
	ds_read_b128 v[220:223], v143 offset:20480
	ds_read_b128 v[224:227], v143 offset:21504
	ds_read_b128 v[228:231], v143 offset:22528
	ds_read_b128 v[232:235], v143 offset:23552
	global_load_lds_dwordx4 v64, s[16:17]
	s_add_i32 m0, s43, 0x2000
	s_add_u32 s44, s16, 0x200000
	s_addc_u32 s45, s17, 0
	s_add_i32 s43, s46, s20
	global_load_lds_dwordx4 v130, s[16:17]
	s_mov_b32 m0, s43
	s_mov_b64 s[100:101], s[18:19]
	global_load_lds_dwordx4 v64, s[44:45]
	s_add_i32 m0, s43, 0x2000
	s_nop 0
	global_load_lds_dwordx4 v130, s[44:45]
	s_mov_b32 m0, s21
	s_nop 0
	global_load_lds_dwordx4 v134, s[18:19]
	s_mov_b32 m0, s25
	s_nop 0
	global_load_lds_dwordx4 v132, s[18:19]
	s_waitcnt vmcnt(8)
	s_waitcnt lgkmcnt(0)
	s_setprio 1
	s_barrier
	v_mfma_f32_16x16x32_bf16 v[60:63], v[144:147], v[194:197], v[60:63]
	v_mfma_f32_16x16x32_bf16 v[56:59], v[152:155], v[194:197], v[56:59]
	v_mfma_f32_16x16x32_bf16 v[52:55], v[144:147], v[212:215], v[52:55]
	v_mfma_f32_16x16x32_bf16 v[48:51], v[152:155], v[212:215], v[48:51]
	v_mfma_f32_16x16x32_bf16 v[36:39], v[144:147], v[220:223], v[36:39]
	v_mfma_f32_16x16x32_bf16 v[32:35], v[152:155], v[220:223], v[32:35]
	v_mfma_f32_16x16x32_bf16 v[20:23], v[144:147], v[228:231], v[20:23]
	v_mfma_f32_16x16x32_bf16 v[16:19], v[152:155], v[228:231], v[16:19]
	s_setprio 0
	s_setprio 1
	v_mfma_f32_16x16x32_bf16 v[60:63], v[148:151], v[208:211], v[60:63]
	v_mfma_f32_16x16x32_bf16 v[56:59], v[156:159], v[208:211], v[56:59]
	v_mfma_f32_16x16x32_bf16 v[52:55], v[148:151], v[216:219], v[52:55]
	v_mfma_f32_16x16x32_bf16 v[48:51], v[156:159], v[216:219], v[48:51]
	v_mfma_f32_16x16x32_bf16 v[36:39], v[148:151], v[224:227], v[36:39]
	v_mfma_f32_16x16x32_bf16 v[32:35], v[156:159], v[224:227], v[32:35]
	v_mfma_f32_16x16x32_bf16 v[20:23], v[148:151], v[232:235], v[20:23]
	v_mfma_f32_16x16x32_bf16 v[16:19], v[156:159], v[232:235], v[16:19]
	s_setprio 0
	s_setprio 1
	v_mfma_f32_16x16x32_bf16 v[44:47], v[178:181], v[194:197], v[44:47]
	v_mfma_f32_16x16x32_bf16 v[40:43], v[186:189], v[194:197], v[40:43]
	v_mfma_f32_16x16x32_bf16 v[28:31], v[178:181], v[212:215], v[28:31]
	v_mfma_f32_16x16x32_bf16 v[24:27], v[186:189], v[212:215], v[24:27]
	v_mfma_f32_16x16x32_bf16 v[12:15], v[178:181], v[220:223], v[12:15]
	v_mfma_f32_16x16x32_bf16 v[8:11], v[186:189], v[220:223], v[8:11]
	v_mfma_f32_16x16x32_bf16 v[4:7], v[178:181], v[228:231], v[4:7]
	v_mfma_f32_16x16x32_bf16 v[0:3], v[186:189], v[228:231], v[0:3]
	s_setprio 0
	s_setprio 1
	v_mfma_f32_16x16x32_bf16 v[44:47], v[182:185], v[208:211], v[44:47]
	v_mfma_f32_16x16x32_bf16 v[40:43], v[190:193], v[208:211], v[40:43]
	v_mfma_f32_16x16x32_bf16 v[28:31], v[182:185], v[216:219], v[28:31]
	v_mfma_f32_16x16x32_bf16 v[24:27], v[190:193], v[216:219], v[24:27]
	v_mfma_f32_16x16x32_bf16 v[12:15], v[182:185], v[224:227], v[12:15]
	v_mfma_f32_16x16x32_bf16 v[8:11], v[190:193], v[224:227], v[8:11]
	v_mfma_f32_16x16x32_bf16 v[4:7], v[182:185], v[232:235], v[4:7]
	v_mfma_f32_16x16x32_bf16 v[0:3], v[190:193], v[232:235], v[0:3]
	s_setprio 0
	s_barrier
; #define PG8_STAGE(bufoff, gbase, voff) do { _Pragma("unroll") for (int _i = 0; _i < 2; ++_i) \
;         __builtin_amdgcn_global_load_lds((const unsigned*)((const char*)(gbase) + (voff)[_i]), (PG8_LAS unsigned*)(lds + (bufoff) + ldsw + _i * 8192), 16, 0, 0); } while (0)
; #define PG8_LDA(dst, b, h) do { _Pragma("unroll") for (int m = 0; m < 4; ++m) _Pragma("unroll") for (int k = 0; k < 2; ++k) dst[m][k] = *(const PG8_LAS bf16x8*)(lds + PG8_SA(b, h) + aoff + m * 2048 + k * 1024); } while (0)
; #define PG8_LDB(dst, b, h) do { _Pragma("unroll") for (int n = 0; n < 2; ++n) _Pragma("unroll") for (int k = 0; k < 2; ++k) dst[n][k] = *(const PG8_LAS bf16x8*)(lds + PG8_SB(b, h) + boff + n * 2048 + k * 1024); } while (0)
; #define PG8_MMA(ai, bj, At, Bt) do { __builtin_amdgcn_s_setprio(1); _Pragma("unroll") for (int m = 0; m < 4; ++m) _Pragma("unroll") for (int n = 0; n < 2; ++n) _Pragma("unroll") for (int k = 0; k < 2; ++k) \
;         acc[ai][bj][m][n] = __builtin_amdgcn_mfma_f32_16x16x32_bf16(Bt[n][k], At[m][k], acc[ai][bj][m][n], 0, 0, 0); __builtin_amdgcn_s_setprio(0); } while (0)
; #define PG8_WAIT_V(n) asm volatile("s_waitcnt vmcnt(" #n ")" ::: "memory")
; #define PG8_WAIT_L(n) asm volatile("s_waitcnt lgkmcnt(" #n ")" ::: "memory")
; #define PG8_BAR __builtin_amdgcn_s_barrier()
; #define PG8_SCHED __builtin_amdgcn_sched_barrier(0)
; template <class Epi, class Sched, bool ALIGN_EPI = false, bool SP2 = false>
; __device__ __forceinline__ void gemm_phase(PG8_LAS unsigned char* lds, const Gemm g, const Sched& S, const Epi& E, const int wave0) {
;     ...
;         for (int t = 0; t < nt; t += 2) {
;     ...
;             PG8_LDB(B0, 1, 0); PG8_LDB(B1, 1, 1); PG8_SCHED; PG8_LDA(At, 1, 0); PG8_STAGE(PG8_SA(0, 1), a2 + hstepA, voffA);
;             PG8_WAIT_V(8); PG8_WAIT_L(0); PG8_BAR; PG8_MMA(0, 0, At, B0); PG8_MMA(0, 1, At, B1); PG8_BAR; PG8_SCHED;
;             PG8_LDA(At, 1, 1); PG8_STAGE(PG8_SB(1, 0), b3, voffB); PG8_STAGE(PG8_SB(1, 1), b3 + hstepB, voffB); PG8_STAGE(PG8_SA(1, 0), a3, voffA);
;             PG8_WAIT_V(8); PG8_WAIT_L(0); PG8_BAR; PG8_MMA(1, 0, At, B0); PG8_MMA(1, 1, At, B1); PG8_BAR; PG8_SCHED;
	s_add_i32 s43, 0, 0x18000
	s_add_i32 s44, 0, 0x1c000
	ds_read_b128 v[144:147], v254
	ds_read_b128 v[148:151], v254 offset:1024
	ds_read_b128 v[152:155], v254 offset:2048
	ds_read_b128 v[156:159], v254 offset:3072
	ds_read_b128 v[178:181], v255
	ds_read_b128 v[182:185], v255 offset:1024
	ds_read_b128 v[186:189], v255 offset:2048
	ds_read_b128 v[190:193], v255 offset:3072
	s_add_u32 s18, s18, 0x200000
	s_addc_u32 s19, s19, 0
	s_mov_b32 m0, s26
	ds_read_b128 v[194:197], v143 offset:32768
	ds_read_b128 v[208:211], v143 offset:33792
	ds_read_b128 v[212:215], v143 offset:34816
	ds_read_b128 v[216:219], v143 offset:35840
	ds_read_b128 v[220:223], v143 offset:36864
	ds_read_b128 v[224:227], v143 offset:37888
	ds_read_b128 v[228:231], v143 offset:38912
	ds_read_b128 v[232:235], v143 offset:39936
	global_load_lds_dwordx4 v134, s[18:19]
	s_mov_b32 m0, s27
	s_nop 0
	global_load_lds_dwordx4 v132, s[18:19]
	s_waitcnt vmcnt(8)
	s_waitcnt lgkmcnt(0)
	s_setprio 1
	s_barrier
	v_mfma_f32_16x16x32_bf16 v[126:129], v[144:147], v[194:197], v[126:129]
	v_mfma_f32_16x16x32_bf16 v[122:125], v[152:155], v[194:197], v[122:125]
	v_mfma_f32_16x16x32_bf16 v[118:121], v[144:147], v[212:215], v[118:121]
	v_mfma_f32_16x16x32_bf16 v[114:117], v[152:155], v[212:215], v[114:117]
	v_mfma_f32_16x16x32_bf16 v[102:105], v[144:147], v[220:223], v[102:105]
	v_mfma_f32_16x16x32_bf16 v[98:101], v[152:155], v[220:223], v[98:101]
	v_mfma_f32_16x16x32_bf16 v[86:89], v[144:147], v[228:231], v[86:89]
	v_mfma_f32_16x16x32_bf16 v[82:85], v[152:155], v[228:231], v[82:85]
	s_setprio 0
	s_setprio 1
	v_mfma_f32_16x16x32_bf16 v[126:129], v[148:151], v[208:211], v[126:129]
	v_mfma_f32_16x16x32_bf16 v[122:125], v[156:159], v[208:211], v[122:125]
	v_mfma_f32_16x16x32_bf16 v[118:121], v[148:151], v[216:219], v[118:121]
	v_mfma_f32_16x16x32_bf16 v[114:117], v[156:159], v[216:219], v[114:117]
	v_mfma_f32_16x16x32_bf16 v[102:105], v[148:151], v[224:227], v[102:105]
	v_mfma_f32_16x16x32_bf16 v[98:101], v[156:159], v[224:227], v[98:101]
	v_mfma_f32_16x16x32_bf16 v[86:89], v[148:151], v[232:235], v[86:89]
	v_mfma_f32_16x16x32_bf16 v[82:85], v[156:159], v[232:235], v[82:85]
	s_setprio 0
	s_setprio 1
	v_mfma_f32_16x16x32_bf16 v[110:113], v[178:181], v[194:197], v[110:113]
	v_mfma_f32_16x16x32_bf16 v[106:109], v[186:189], v[194:197], v[106:109]
	v_mfma_f32_16x16x32_bf16 v[94:97], v[178:181], v[212:215], v[94:97]
	v_mfma_f32_16x16x32_bf16 v[90:93], v[186:189], v[212:215], v[90:93]
	v_mfma_f32_16x16x32_bf16 v[78:81], v[178:181], v[220:223], v[78:81]
	v_mfma_f32_16x16x32_bf16 v[74:77], v[186:189], v[220:223], v[74:77]
	v_mfma_f32_16x16x32_bf16 v[70:73], v[178:181], v[228:231], v[70:73]
	v_mfma_f32_16x16x32_bf16 v[66:69], v[186:189], v[228:231], v[66:69]
	s_setprio 0
	s_setprio 1
	v_mfma_f32_16x16x32_bf16 v[110:113], v[182:185], v[208:211], v[110:113]
	v_mfma_f32_16x16x32_bf16 v[106:109], v[190:193], v[208:211], v[106:109]
	v_mfma_f32_16x16x32_bf16 v[94:97], v[182:185], v[216:219], v[94:97]
	v_mfma_f32_16x16x32_bf16 v[90:93], v[190:193], v[216:219], v[90:93]
	v_mfma_f32_16x16x32_bf16 v[78:81], v[182:185], v[224:227], v[78:81]
	v_mfma_f32_16x16x32_bf16 v[74:77], v[190:193], v[224:227], v[74:77]
	v_mfma_f32_16x16x32_bf16 v[70:73], v[182:185], v[232:235], v[70:73]
	v_mfma_f32_16x16x32_bf16 v[66:69], v[190:193], v[232:235], v[66:69]
	s_setprio 0
	s_barrier
	s_add_i32 s18, s43, s20
	s_add_u32 s48, s16, 0x80
	s_addc_u32 s49, s17, 0
	s_mov_b32 m0, s18
	ds_read_b128 v[194:197], v143 offset:49152
	ds_read_b128 v[208:211], v143 offset:50176
	ds_read_b128 v[212:215], v143 offset:51200
	ds_read_b128 v[216:219], v143 offset:52224
	ds_read_b128 v[220:223], v143 offset:53248
	ds_read_b128 v[224:227], v143 offset:54272
	ds_read_b128 v[228:231], v143 offset:55296
	ds_read_b128 v[232:235], v143 offset:56320
	global_load_lds_dwordx4 v64, s[48:49]
	s_add_i32 m0, s18, 0x2000
	s_add_u32 s16, s16, 0x200080
	s_addc_u32 s17, s17, 0
	s_add_i32 s18, s44, s20
	global_load_lds_dwordx4 v130, s[48:49]
	s_mov_b32 m0, s18
	s_nop 0
	global_load_lds_dwordx4 v64, s[16:17]
	s_add_i32 m0, s18, 0x2000
	s_nop 0
	global_load_lds_dwordx4 v130, s[16:17]
	s_add_u32 s100, s100, 0x80
	s_addc_u32 s101, s101, 0
	s_mov_b32 m0, s28
	s_nop 0
	global_load_lds_dwordx4 v134, s[100:101]
	s_mov_b32 m0, s29
	s_nop 0
	global_load_lds_dwordx4 v132, s[100:101]
	s_waitcnt vmcnt(8)
	s_waitcnt lgkmcnt(0)
	s_setprio 1
	s_barrier
	v_mfma_f32_16x16x32_bf16 v[60:63], v[144:147], v[194:197], v[60:63]
	v_mfma_f32_16x16x32_bf16 v[56:59], v[152:155], v[194:197], v[56:59]
	v_mfma_f32_16x16x32_bf16 v[52:55], v[144:147], v[212:215], v[52:55]
	v_mfma_f32_16x16x32_bf16 v[48:51], v[152:155], v[212:215], v[48:51]
	v_mfma_f32_16x16x32_bf16 v[36:39], v[144:147], v[220:223], v[36:39]
	v_mfma_f32_16x16x32_bf16 v[32:35], v[152:155], v[220:223], v[32:35]
	v_mfma_f32_16x16x32_bf16 v[20:23], v[144:147], v[228:231], v[20:23]
	v_mfma_f32_16x16x32_bf16 v[16:19], v[152:155], v[228:231], v[16:19]
	s_setprio 0
	s_setprio 1
	v_mfma_f32_16x16x32_bf16 v[60:63], v[148:151], v[208:211], v[60:63]
	v_mfma_f32_16x16x32_bf16 v[56:59], v[156:159], v[208:211], v[56:59]
	v_mfma_f32_16x16x32_bf16 v[52:55], v[148:151], v[216:219], v[52:55]
	v_mfma_f32_16x16x32_bf16 v[48:51], v[156:159], v[216:219], v[48:51]
	v_mfma_f32_16x16x32_bf16 v[36:39], v[148:151], v[224:227], v[36:39]
	v_mfma_f32_16x16x32_bf16 v[32:35], v[156:159], v[224:227], v[32:35]
	v_mfma_f32_16x16x32_bf16 v[20:23], v[148:151], v[232:235], v[20:23]
	v_mfma_f32_16x16x32_bf16 v[16:19], v[156:159], v[232:235], v[16:19]
	s_setprio 0
	s_setprio 1
	v_mfma_f32_16x16x32_bf16 v[44:47], v[178:181], v[194:197], v[44:47]
	v_mfma_f32_16x16x32_bf16 v[40:43], v[186:189], v[194:197], v[40:43]
	v_mfma_f32_16x16x32_bf16 v[28:31], v[178:181], v[212:215], v[28:31]
	v_mfma_f32_16x16x32_bf16 v[24:27], v[186:189], v[212:215], v[24:27]
	v_mfma_f32_16x16x32_bf16 v[12:15], v[178:181], v[220:223], v[12:15]
	v_mfma_f32_16x16x32_bf16 v[8:11], v[186:189], v[220:223], v[8:11]
	v_mfma_f32_16x16x32_bf16 v[4:7], v[178:181], v[228:231], v[4:7]
	v_mfma_f32_16x16x32_bf16 v[0:3], v[186:189], v[228:231], v[0:3]
	s_setprio 0
	s_setprio 1
	v_mfma_f32_16x16x32_bf16 v[44:47], v[182:185], v[208:211], v[44:47]
	v_mfma_f32_16x16x32_bf16 v[40:43], v[190:193], v[208:211], v[40:43]
	v_mfma_f32_16x16x32_bf16 v[28:31], v[182:185], v[216:219], v[28:31]
	v_mfma_f32_16x16x32_bf16 v[24:27], v[190:193], v[216:219], v[24:27]
	v_mfma_f32_16x16x32_bf16 v[12:15], v[182:185], v[224:227], v[12:15]
	v_mfma_f32_16x16x32_bf16 v[8:11], v[190:193], v[224:227], v[8:11]
	v_mfma_f32_16x16x32_bf16 v[4:7], v[182:185], v[232:235], v[4:7]
	v_mfma_f32_16x16x32_bf16 v[0:3], v[190:193], v[232:235], v[0:3]
	s_setprio 0
	s_barrier
	s_add_i32 s42, s42, 2
	s_add_u32 s0, s0, 0x100
	s_addc_u32 s1, s1, 0
	s_add_u32 s36, s36, 0x100
	s_addc_u32 s37, s37, 0
	s_cmpk_gt_u32 s42, 0x7d
	s_cbranch_scc0 .LBB0_1685
	s_mov_b64 s[48:49], 0x80
	s_and_b64 vcc, exec, s[6:7]
	s_mov_b64 s[34:35], 0x45000
	s_cbranch_vccz .LBB0_1688
	s_barrier

; #define PG8_STAGE(bufoff, gbase, voff) do { _Pragma("unroll") for (int _i = 0; _i < 2; ++_i) \
;         __builtin_amdgcn_global_load_lds((const unsigned*)((const char*)(gbase) + (voff)[_i]), (PG8_LAS unsigned*)(lds + (bufoff) + ldsw + _i * 8192), 16, 0, 0); } while (0)
; #define PG8_LDA(dst, b, h) do { _Pragma("unroll") for (int m = 0; m < 4; ++m) _Pragma("unroll") for (int k = 0; k < 2; ++k) dst[m][k] = *(const PG8_LAS bf16x8*)(lds + PG8_SA(b, h) + aoff + m * 2048 + k * 1024); } while (0)
; #define PG8_LDB(dst, b, h) do { _Pragma("unroll") for (int n = 0; n < 2; ++n) _Pragma("unroll") for (int k = 0; k < 2; ++k) dst[n][k] = *(const PG8_LAS bf16x8*)(lds + PG8_SB(b, h) + boff + n * 2048 + k * 1024); } while (0)
; template <class Epi, class Sched, bool ALIGN_EPI = false, bool SP2 = false>
; __device__ __forceinline__ void gemm_phase(PG8_LAS unsigned char* lds, const Gemm g, const Sched& S, const Epi& E, const int wave0) {
;     ...
;             const bool last = (t == nt - 2);
;             const char* a1 = cA + (size_t)(t + 1) * kstep;
;             const char* a2 = last ? nA : cA + (size_t)(t + 2) * kstep; const char* b2 = last ? nB : cB + (size_t)(t + 2) * kstep;
;             const char* a3 = a2 + kstep; const char* b3 = b2 + kstep;
;             if (last && has_next) S.a_ready(nxt);
;             if constexpr (SP2) {
;             PG8_LDB(B0, 0, 0); PG8_LDB(B1, 0, 1); PG8_SCHED; PG8_LDA(At, 0, 0); PG8_STAGE(PG8_SA(1, 1), a1 + hstepA, voffA);
;             PG8_WAIT_V(8); PG8_WAIT_L(0); PG8_BAR; PG8_MMA(0, 0, At, B0); PG8_MMA(0, 1, At, B1); PG8_BAR; PG8_SCHED;
;             PG8_LDA(At, 0, 1); PG8_STAGE(PG8_SB(0, 0), b2, voffB); PG8_STAGE(PG8_SB(0, 1), b2 + hstepB, voffB); PG8_STAGE(PG8_SA(0, 0), a2, voffA);
;             PG8_WAIT_V(8); PG8_WAIT_L(0); PG8_BAR; PG8_MMA(1, 0, At, B0); PG8_MMA(1, 1, At, B1); PG8_BAR; PG8_SCHED;
; __global__ void __launch_bounds__(NWAVES * 64, 2) fwd_kernel(Args args) {
;     ...
;             if (!lastl) { pg8::Gemm g2{(const bf16*)(ws + WS_HM), (const bf16*)(ws + WS_WM2) + (size_t)l * 2048 * 8192, MC, 2048, 1024, 0, 0, DFF, DFF}; pg8::SplitKOrder<8> S2; S2.init(MC, 2048, F.G, (int)blockIdx.x, ML / 256, 1024);
;                 pg8::EpiBf16<0> E2{(bf16*)(ws + WS_PART) - (size_t)ML * 2048, 2048, (size_t)MC * 2048};
;                 pg8::gemm_phase<pg8::EpiBf16<0>, pg8::SplitKOrder<8>, true, true>(F.lds + RING_OFF, g2, S2, E2, F.wave); } });
.LBB0_1702:
	s_add_u32 s18, s16, 0xffe00080
	s_addc_u32 s19, s17, -1
	s_add_i32 s44, 0, 0x10000
	s_cmp_eq_u32 s43, 12
	s_cselect_b32 s21, s9, s19
	s_cselect_b32 s20, s11, s18
	s_cselect_b32 s19, s13, s42
	s_cselect_b32 s18, s38, s39
	s_add_i32 s46, 0, 0x14000
	ds_read_b128 v[144:147], v252
	ds_read_b128 v[148:151], v252 offset:1024
	ds_read_b128 v[152:155], v252 offset:2048
	ds_read_b128 v[156:159], v252 offset:3072
	ds_read_b128 v[178:181], v253
	ds_read_b128 v[182:185], v253 offset:1024
	ds_read_b128 v[186:189], v253 offset:2048
	ds_read_b128 v[190:193], v253 offset:3072
	s_add_i32 m0, s28, 0xc000
	ds_read_b128 v[194:197], v143
	ds_read_b128 v[208:211], v143 offset:1024
	ds_read_b128 v[212:215], v143 offset:2048
	ds_read_b128 v[216:219], v143 offset:3072
	ds_read_b128 v[220:223], v143 offset:4096
	ds_read_b128 v[224:227], v143 offset:5120
	ds_read_b128 v[228:231], v143 offset:6144
	ds_read_b128 v[232:235], v143 offset:7168
	global_load_lds_dwordx4 v136, s[16:17]
	s_add_i32 m0, s28, 0xe000
	s_nop 0
	global_load_lds_dwordx4 v138, s[16:17]
	s_waitcnt vmcnt(8)
	s_waitcnt lgkmcnt(0)
	s_setprio 1
	s_barrier
	v_mfma_f32_16x16x32_bf16 v[126:129], v[144:147], v[194:197], v[126:129]
	v_mfma_f32_16x16x32_bf16 v[122:125], v[152:155], v[194:197], v[122:125]
	v_mfma_f32_16x16x32_bf16 v[118:121], v[144:147], v[212:215], v[118:121]
	v_mfma_f32_16x16x32_bf16 v[114:117], v[152:155], v[212:215], v[114:117]
	v_mfma_f32_16x16x32_bf16 v[102:105], v[144:147], v[220:223], v[102:105]
	v_mfma_f32_16x16x32_bf16 v[98:101], v[152:155], v[220:223], v[98:101]
	v_mfma_f32_16x16x32_bf16 v[86:89], v[144:147], v[228:231], v[86:89]
	v_mfma_f32_16x16x32_bf16 v[82:85], v[152:155], v[228:231], v[82:85]
	s_setprio 0
	s_setprio 1
	v_mfma_f32_16x16x32_bf16 v[126:129], v[148:151], v[208:211], v[126:129]
	v_mfma_f32_16x16x32_bf16 v[122:125], v[156:159], v[208:211], v[122:125]
	v_mfma_f32_16x16x32_bf16 v[118:121], v[148:151], v[216:219], v[118:121]
	v_mfma_f32_16x16x32_bf16 v[114:117], v[156:159], v[216:219], v[114:117]
	v_mfma_f32_16x16x32_bf16 v[102:105], v[148:151], v[224:227], v[102:105]
	v_mfma_f32_16x16x32_bf16 v[98:101], v[156:159], v[224:227], v[98:101]
	v_mfma_f32_16x16x32_bf16 v[86:89], v[148:151], v[232:235], v[86:89]
	v_mfma_f32_16x16x32_bf16 v[82:85], v[156:159], v[232:235], v[82:85]
	s_setprio 0
	s_setprio 1
	v_mfma_f32_16x16x32_bf16 v[110:113], v[178:181], v[194:197], v[110:113]
	v_mfma_f32_16x16x32_bf16 v[106:109], v[186:189], v[194:197], v[106:109]
	v_mfma_f32_16x16x32_bf16 v[94:97], v[178:181], v[212:215], v[94:97]
	v_mfma_f32_16x16x32_bf16 v[90:93], v[186:189], v[212:215], v[90:93]
	v_mfma_f32_16x16x32_bf16 v[78:81], v[178:181], v[220:223], v[78:81]
	v_mfma_f32_16x16x32_bf16 v[74:77], v[186:189], v[220:223], v[74:77]
	v_mfma_f32_16x16x32_bf16 v[70:73], v[178:181], v[228:231], v[70:73]
	v_mfma_f32_16x16x32_bf16 v[66:69], v[186:189], v[228:231], v[66:69]
	s_setprio 0
	s_setprio 1
	v_mfma_f32_16x16x32_bf16 v[110:113], v[182:185], v[208:211], v[110:113]
	v_mfma_f32_16x16x32_bf16 v[106:109], v[190:193], v[208:211], v[106:109]
	v_mfma_f32_16x16x32_bf16 v[94:97], v[182:185], v[216:219], v[94:97]
	v_mfma_f32_16x16x32_bf16 v[90:93], v[190:193], v[216:219], v[90:93]
	v_mfma_f32_16x16x32_bf16 v[78:81], v[182:185], v[224:227], v[78:81]
	v_mfma_f32_16x16x32_bf16 v[74:77], v[190:193], v[224:227], v[74:77]
	v_mfma_f32_16x16x32_bf16 v[70:73], v[182:185], v[232:235], v[70:73]
	v_mfma_f32_16x16x32_bf16 v[66:69], v[190:193], v[232:235], v[66:69]
	s_setprio 0
	s_barrier
	s_add_i32 s44, s44, s25
	s_mov_b32 m0, s44
	ds_read_b128 v[194:197], v143 offset:16384
	ds_read_b128 v[208:211], v143 offset:17408
	ds_read_b128 v[212:215], v143 offset:18432
	ds_read_b128 v[216:219], v143 offset:19456
	ds_read_b128 v[220:223], v143 offset:20480
	ds_read_b128 v[224:227], v143 offset:21504
	ds_read_b128 v[228:231], v143 offset:22528
	ds_read_b128 v[232:235], v143 offset:23552
	global_load_lds_dwordx4 v64, s[18:19]
	s_add_i32 m0, s44, 0x2000
	s_add_u32 s44, s18, 0x200000
	s_addc_u32 s45, s19, 0
	s_add_i32 s46, s46, s25
	global_load_lds_dwordx4 v130, s[18:19]
	s_mov_b32 m0, s46
	s_mov_b64 s[100:101], s[20:21]
	global_load_lds_dwordx4 v64, s[44:45]
	s_add_i32 m0, s46, 0x2000
	s_nop 0
	global_load_lds_dwordx4 v130, s[44:45]
	s_mov_b32 m0, s28
	s_nop 0
	global_load_lds_dwordx4 v134, s[20:21]
	s_mov_b32 m0, s29
	s_nop 0
	global_load_lds_dwordx4 v132, s[20:21]
	s_waitcnt vmcnt(8)
	s_waitcnt lgkmcnt(0)
	s_setprio 1
	s_barrier
	v_mfma_f32_16x16x32_bf16 v[60:63], v[144:147], v[194:197], v[60:63]
	v_mfma_f32_16x16x32_bf16 v[56:59], v[152:155], v[194:197], v[56:59]
	v_mfma_f32_16x16x32_bf16 v[52:55], v[144:147], v[212:215], v[52:55]
	v_mfma_f32_16x16x32_bf16 v[48:51], v[152:155], v[212:215], v[48:51]
	v_mfma_f32_16x16x32_bf16 v[36:39], v[144:147], v[220:223], v[36:39]
	v_mfma_f32_16x16x32_bf16 v[32:35], v[152:155], v[220:223], v[32:35]
	v_mfma_f32_16x16x32_bf16 v[20:23], v[144:147], v[228:231], v[20:23]
	v_mfma_f32_16x16x32_bf16 v[16:19], v[152:155], v[228:231], v[16:19]
	s_setprio 0
	s_setprio 1
	v_mfma_f32_16x16x32_bf16 v[60:63], v[148:151], v[208:211], v[60:63]
	v_mfma_f32_16x16x32_bf16 v[56:59], v[156:159], v[208:211], v[56:59]
	v_mfma_f32_16x16x32_bf16 v[52:55], v[148:151], v[216:219], v[52:55]
	v_mfma_f32_16x16x32_bf16 v[48:51], v[156:159], v[216:219], v[48:51]
	v_mfma_f32_16x16x32_bf16 v[36:39], v[148:151], v[224:227], v[36:39]
	v_mfma_f32_16x16x32_bf16 v[32:35], v[156:159], v[224:227], v[32:35]
	v_mfma_f32_16x16x32_bf16 v[20:23], v[148:151], v[232:235], v[20:23]
	v_mfma_f32_16x16x32_bf16 v[16:19], v[156:159], v[232:235], v[16:19]
	s_setprio 0
	s_setprio 1
	v_mfma_f32_16x16x32_bf16 v[44:47], v[178:181], v[194:197], v[44:47]
	v_mfma_f32_16x16x32_bf16 v[40:43], v[186:189], v[194:197], v[40:43]
	v_mfma_f32_16x16x32_bf16 v[28:31], v[178:181], v[212:215], v[28:31]
	v_mfma_f32_16x16x32_bf16 v[24:27], v[186:189], v[212:215], v[24:27]
	v_mfma_f32_16x16x32_bf16 v[12:15], v[178:181], v[220:223], v[12:15]
	v_mfma_f32_16x16x32_bf16 v[8:11], v[186:189], v[220:223], v[8:11]
	v_mfma_f32_16x16x32_bf16 v[4:7], v[178:181], v[228:231], v[4:7]
	v_mfma_f32_16x16x32_bf16 v[0:3], v[186:189], v[228:231], v[0:3]
	s_setprio 0
	s_setprio 1
	v_mfma_f32_16x16x32_bf16 v[44:47], v[182:185], v[208:211], v[44:47]
	v_mfma_f32_16x16x32_bf16 v[40:43], v[190:193], v[208:211], v[40:43]
	v_mfma_f32_16x16x32_bf16 v[28:31], v[182:185], v[216:219], v[28:31]
	v_mfma_f32_16x16x32_bf16 v[24:27], v[190:193], v[216:219], v[24:27]
	v_mfma_f32_16x16x32_bf16 v[12:15], v[182:185], v[224:227], v[12:15]
	v_mfma_f32_16x16x32_bf16 v[8:11], v[190:193], v[224:227], v[8:11]
	v_mfma_f32_16x16x32_bf16 v[4:7], v[182:185], v[232:235], v[4:7]
	v_mfma_f32_16x16x32_bf16 v[0:3], v[190:193], v[232:235], v[0:3]
	s_setprio 0
	s_barrier
; #define PG8_STAGE(bufoff, gbase, voff) do { _Pragma("unroll") for (int _i = 0; _i < 2; ++_i) \
;         __builtin_amdgcn_global_load_lds((const unsigned*)((const char*)(gbase) + (voff)[_i]), (PG8_LAS unsigned*)(lds + (bufoff) + ldsw + _i * 8192), 16, 0, 0); } while (0)
; #define PG8_LDA(dst, b, h) do { _Pragma("unroll") for (int m = 0; m < 4; ++m) _Pragma("unroll") for (int k = 0; k < 2; ++k) dst[m][k] = *(const PG8_LAS bf16x8*)(lds + PG8_SA(b, h) + aoff + m * 2048 + k * 1024); } while (0)
; #define PG8_LDB(dst, b, h) do { _Pragma("unroll") for (int n = 0; n < 2; ++n) _Pragma("unroll") for (int k = 0; k < 2; ++k) dst[n][k] = *(const PG8_LAS bf16x8*)(lds + PG8_SB(b, h) + boff + n * 2048 + k * 1024); } while (0)
; #define PG8_MMA(ai, bj, At, Bt) do { __builtin_amdgcn_s_setprio(1); _Pragma("unroll") for (int m = 0; m < 4; ++m) _Pragma("unroll") for (int n = 0; n < 2; ++n) _Pragma("unroll") for (int k = 0; k < 2; ++k) \
;         acc[ai][bj][m][n] = __builtin_amdgcn_mfma_f32_16x16x32_bf16(Bt[n][k], At[m][k], acc[ai][bj][m][n], 0, 0, 0); __builtin_amdgcn_s_setprio(0); } while (0)
; #define PG8_WAIT_V(n) asm volatile("s_waitcnt vmcnt(" #n ")" ::: "memory")
; #define PG8_WAIT_L(n) asm volatile("s_waitcnt lgkmcnt(" #n ")" ::: "memory")
; #define PG8_BAR __builtin_amdgcn_s_barrier()
; #define PG8_SCHED __builtin_amdgcn_sched_barrier(0)
; template <class Epi, class Sched, bool ALIGN_EPI = false, bool SP2 = false>
; __device__ __forceinline__ void gemm_phase(PG8_LAS unsigned char* lds, const Gemm g, const Sched& S, const Epi& E, const int wave0) {
;     ...
;         for (int t = 0; t < nt; t += 2) {
;     ...
;             PG8_LDB(B0, 1, 0); PG8_LDB(B1, 1, 1); PG8_SCHED; PG8_LDA(At, 1, 0); PG8_STAGE(PG8_SA(0, 1), a2 + hstepA, voffA);
;             PG8_WAIT_V(8); PG8_WAIT_L(0); PG8_BAR; PG8_MMA(0, 0, At, B0); PG8_MMA(0, 1, At, B1); PG8_BAR; PG8_SCHED;
;             PG8_LDA(At, 1, 1); PG8_STAGE(PG8_SB(1, 0), b3, voffB); PG8_STAGE(PG8_SB(1, 1), b3 + hstepB, voffB); PG8_STAGE(PG8_SA(1, 0), a3, voffA);
;             PG8_WAIT_V(8); PG8_WAIT_L(0); PG8_BAR; PG8_MMA(1, 0, At, B0); PG8_MMA(1, 1, At, B1); PG8_BAR; PG8_SCHED;
	s_add_i32 s44, 0, 0x18000
	s_add_i32 s45, 0, 0x1c000
	ds_read_b128 v[144:147], v254
	ds_read_b128 v[148:151], v254 offset:1024
	ds_read_b128 v[152:155], v254 offset:2048
	ds_read_b128 v[156:159], v254 offset:3072
	ds_read_b128 v[178:181], v255
	ds_read_b128 v[182:185], v255 offset:1024
	ds_read_b128 v[186:189], v255 offset:2048
	ds_read_b128 v[190:193], v255 offset:3072
	s_add_u32 s20, s20, 0x200000
	s_addc_u32 s21, s21, 0
	s_mov_b32 m0, s30
	ds_read_b128 v[194:197], v143 offset:32768
	ds_read_b128 v[208:211], v143 offset:33792
	ds_read_b128 v[212:215], v143 offset:34816
	ds_read_b128 v[216:219], v143 offset:35840
	ds_read_b128 v[220:223], v143 offset:36864
	ds_read_b128 v[224:227], v143 offset:37888
	ds_read_b128 v[228:231], v143 offset:38912
	ds_read_b128 v[232:235], v143 offset:39936
	global_load_lds_dwordx4 v134, s[20:21]
	s_mov_b32 m0, s31
	s_nop 0
	global_load_lds_dwordx4 v132, s[20:21]
	s_waitcnt vmcnt(8)
	s_waitcnt lgkmcnt(0)
	s_setprio 1
	s_barrier
	v_mfma_f32_16x16x32_bf16 v[126:129], v[144:147], v[194:197], v[126:129]
	v_mfma_f32_16x16x32_bf16 v[122:125], v[152:155], v[194:197], v[122:125]
	v_mfma_f32_16x16x32_bf16 v[118:121], v[144:147], v[212:215], v[118:121]
	v_mfma_f32_16x16x32_bf16 v[114:117], v[152:155], v[212:215], v[114:117]
	v_mfma_f32_16x16x32_bf16 v[102:105], v[144:147], v[220:223], v[102:105]
	v_mfma_f32_16x16x32_bf16 v[98:101], v[152:155], v[220:223], v[98:101]
	v_mfma_f32_16x16x32_bf16 v[86:89], v[144:147], v[228:231], v[86:89]
	v_mfma_f32_16x16x32_bf16 v[82:85], v[152:155], v[228:231], v[82:85]
	s_setprio 0
	s_setprio 1
	v_mfma_f32_16x16x32_bf16 v[126:129], v[148:151], v[208:211], v[126:129]
	v_mfma_f32_16x16x32_bf16 v[122:125], v[156:159], v[208:211], v[122:125]
	v_mfma_f32_16x16x32_bf16 v[118:121], v[148:151], v[216:219], v[118:121]
	v_mfma_f32_16x16x32_bf16 v[114:117], v[156:159], v[216:219], v[114:117]
	v_mfma_f32_16x16x32_bf16 v[102:105], v[148:151], v[224:227], v[102:105]
	v_mfma_f32_16x16x32_bf16 v[98:101], v[156:159], v[224:227], v[98:101]
	v_mfma_f32_16x16x32_bf16 v[86:89], v[148:151], v[232:235], v[86:89]
	v_mfma_f32_16x16x32_bf16 v[82:85], v[156:159], v[232:235], v[82:85]
	s_setprio 0
	s_setprio 1
	v_mfma_f32_16x16x32_bf16 v[110:113], v[178:181], v[194:197], v[110:113]
	v_mfma_f32_16x16x32_bf16 v[106:109], v[186:189], v[194:197], v[106:109]
	v_mfma_f32_16x16x32_bf16 v[94:97], v[178:181], v[212:215], v[94:97]
	v_mfma_f32_16x16x32_bf16 v[90:93], v[186:189], v[212:215], v[90:93]
	v_mfma_f32_16x16x32_bf16 v[78:81], v[178:181], v[220:223], v[78:81]
	v_mfma_f32_16x16x32_bf16 v[74:77], v[186:189], v[220:223], v[74:77]
	v_mfma_f32_16x16x32_bf16 v[70:73], v[178:181], v[228:231], v[70:73]
	v_mfma_f32_16x16x32_bf16 v[66:69], v[186:189], v[228:231], v[66:69]
	s_setprio 0
	s_setprio 1
	v_mfma_f32_16x16x32_bf16 v[110:113], v[182:185], v[208:211], v[110:113]
	v_mfma_f32_16x16x32_bf16 v[106:109], v[190:193], v[208:211], v[106:109]
	v_mfma_f32_16x16x32_bf16 v[94:97], v[182:185], v[216:219], v[94:97]
	v_mfma_f32_16x16x32_bf16 v[90:93], v[190:193], v[216:219], v[90:93]
	v_mfma_f32_16x16x32_bf16 v[78:81], v[182:185], v[224:227], v[78:81]
	v_mfma_f32_16x16x32_bf16 v[74:77], v[190:193], v[224:227], v[74:77]
	v_mfma_f32_16x16x32_bf16 v[70:73], v[182:185], v[232:235], v[70:73]
	v_mfma_f32_16x16x32_bf16 v[66:69], v[190:193], v[232:235], v[66:69]
	s_setprio 0
	s_barrier
	s_add_i32 s20, s44, s25
	s_add_u32 s48, s18, 0x80
	s_addc_u32 s49, s19, 0
	s_mov_b32 m0, s20
	ds_read_b128 v[194:197], v143 offset:49152
	ds_read_b128 v[208:211], v143 offset:50176
	ds_read_b128 v[212:215], v143 offset:51200
	ds_read_b128 v[216:219], v143 offset:52224
	ds_read_b128 v[220:223], v143 offset:53248
	ds_read_b128 v[224:227], v143 offset:54272
	ds_read_b128 v[228:231], v143 offset:55296
	ds_read_b128 v[232:235], v143 offset:56320
	global_load_lds_dwordx4 v64, s[48:49]
	s_add_i32 m0, s20, 0x2000
	s_add_u32 s18, s18, 0x200080
	s_addc_u32 s19, s19, 0
	s_add_i32 s20, s45, s25
	global_load_lds_dwordx4 v130, s[48:49]
	s_mov_b32 m0, s20
	s_nop 0
	global_load_lds_dwordx4 v64, s[18:19]
	s_add_i32 m0, s20, 0x2000
	s_nop 0
	global_load_lds_dwordx4 v130, s[18:19]
	s_add_u32 s100, s100, 0x80
	s_addc_u32 s101, s101, 0
	s_mov_b32 m0, s33
	s_nop 0
	global_load_lds_dwordx4 v134, s[100:101]
	s_mov_b32 m0, s34
	s_nop 0
	global_load_lds_dwordx4 v132, s[100:101]
	s_waitcnt vmcnt(8)
	s_waitcnt lgkmcnt(0)
	s_setprio 1
	s_barrier
	v_mfma_f32_16x16x32_bf16 v[60:63], v[144:147], v[194:197], v[60:63]
	v_mfma_f32_16x16x32_bf16 v[56:59], v[152:155], v[194:197], v[56:59]
	v_mfma_f32_16x16x32_bf16 v[52:55], v[144:147], v[212:215], v[52:55]
	v_mfma_f32_16x16x32_bf16 v[48:51], v[152:155], v[212:215], v[48:51]
	v_mfma_f32_16x16x32_bf16 v[36:39], v[144:147], v[220:223], v[36:39]
	v_mfma_f32_16x16x32_bf16 v[32:35], v[152:155], v[220:223], v[32:35]
	v_mfma_f32_16x16x32_bf16 v[20:23], v[144:147], v[228:231], v[20:23]
	v_mfma_f32_16x16x32_bf16 v[16:19], v[152:155], v[228:231], v[16:19]
	s_setprio 0
	s_setprio 1
	v_mfma_f32_16x16x32_bf16 v[60:63], v[148:151], v[208:211], v[60:63]
	v_mfma_f32_16x16x32_bf16 v[56:59], v[156:159], v[208:211], v[56:59]
	v_mfma_f32_16x16x32_bf16 v[52:55], v[148:151], v[216:219], v[52:55]
	v_mfma_f32_16x16x32_bf16 v[48:51], v[156:159], v[216:219], v[48:51]
	v_mfma_f32_16x16x32_bf16 v[36:39], v[148:151], v[224:227], v[36:39]
	v_mfma_f32_16x16x32_bf16 v[32:35], v[156:159], v[224:227], v[32:35]
	v_mfma_f32_16x16x32_bf16 v[20:23], v[148:151], v[232:235], v[20:23]
	v_mfma_f32_16x16x32_bf16 v[16:19], v[156:159], v[232:235], v[16:19]
	s_setprio 0
	s_setprio 1
	v_mfma_f32_16x16x32_bf16 v[44:47], v[178:181], v[194:197], v[44:47]
	v_mfma_f32_16x16x32_bf16 v[40:43], v[186:189], v[194:197], v[40:43]
	v_mfma_f32_16x16x32_bf16 v[28:31], v[178:181], v[212:215], v[28:31]
	v_mfma_f32_16x16x32_bf16 v[24:27], v[186:189], v[212:215], v[24:27]
	v_mfma_f32_16x16x32_bf16 v[12:15], v[178:181], v[220:223], v[12:15]
	v_mfma_f32_16x16x32_bf16 v[8:11], v[186:189], v[220:223], v[8:11]
	v_mfma_f32_16x16x32_bf16 v[4:7], v[178:181], v[228:231], v[4:7]
	v_mfma_f32_16x16x32_bf16 v[0:3], v[186:189], v[228:231], v[0:3]
	s_setprio 0
	s_setprio 1
	v_mfma_f32_16x16x32_bf16 v[44:47], v[182:185], v[208:211], v[44:47]
	v_mfma_f32_16x16x32_bf16 v[40:43], v[190:193], v[208:211], v[40:43]
	v_mfma_f32_16x16x32_bf16 v[28:31], v[182:185], v[216:219], v[28:31]
	v_mfma_f32_16x16x32_bf16 v[24:27], v[190:193], v[216:219], v[24:27]
	v_mfma_f32_16x16x32_bf16 v[12:15], v[182:185], v[224:227], v[12:15]
	v_mfma_f32_16x16x32_bf16 v[8:11], v[190:193], v[224:227], v[8:11]
	v_mfma_f32_16x16x32_bf16 v[4:7], v[182:185], v[232:235], v[4:7]
	v_mfma_f32_16x16x32_bf16 v[0:3], v[190:193], v[232:235], v[0:3]
	s_setprio 0
	s_barrier
	s_add_i32 s43, s43, 2
	s_add_u32 s16, s16, 0x100
	s_addc_u32 s17, s17, 0
	s_add_u32 s39, s39, 0x100
	s_addc_u32 s42, s42, 0
	s_cmp_gt_u32 s43, 13
	s_cbranch_scc0 .LBB0_1702
	s_mov_b64 s[48:49], 0x80
	s_and_b64 vcc, exec, s[6:7]
	s_cbranch_vccz .LBB0_1705
	s_barrier
